# baseline (speedup 1.0000x reference)
; #define WAIT_V(n) asm volatile("s_waitcnt vmcnt(" #n ")" ::: "memory")
; #define WAIT_L(n) asm volatile("s_waitcnt lgkmcnt(" #n ")" ::: "memory")
; #define BAR __builtin_amdgcn_s_barrier()
; #define SCHED __builtin_amdgcn_sched_barrier(0)
; #define STG_A(b, h, kt) stage_half_s(lds0 + ((b) * 2 + (h)) * HT_B, ((h) ? A1 : Ap) + (kt) * BK, off0, off1)
; #define STG_B(b, h, kt) stage_half_s(lds0 + (4 + (b) * 2 + (h)) * HT_B, ((h) ? B1p : Bp) + (kt) * BK, off0, off1)
; #define STG_A(b, h, kt) stage_half_s(lds0 + ((b) * 2 + (h)) * HT_B, ((h) ? A1 : Ap) + (kt) * BK, off0, off1)
; #define STG_B(b, h, kt) stage_half_s(lds0 + (4 + (b) * 2 + (h)) * HT_B, ((h) ? B1p : Bp) + (kt) * BK, off0, off1)
; #define LDA8(b, h) _Pragma("unroll") for (int m = 0; m < 4; ++m) _Pragma("unroll") for (int k = 0; k < 2; ++k) \
;     At[m][k] = *(const bf16x8*)(SA_(shm, b, h) + abase + (m * 2 + k) * 1024)
; template <bool HS>
; __device__ __forceinline__ void gemm_tile8(const u16* __restrict__ Ap, const u16* __restrict__ Bp, int K,
;                                            f32x4 (&acc)[2][2][4][2], char* shm, const int tid, const float* hsr = nullptr) {
;   const int wid = tid >> 6, lane = tid & 63, wr = wid >> 2, wc = wid & 3, fr = lane & 15, fq = lane >> 4;
;   int r0, c0, r1, c1;
;   stage_rc(tid * 16, r0, c0);
;   stage_rc(tid * 16 + 8192, r1, c1);
;   const unsigned off0 = (unsigned)(r0 * K + c0) * 2u, off1 = (unsigned)(r1 * K + c1) * 2u;
;   const int wvoff = __builtin_amdgcn_readfirstlane(tid >> 6) * 1024;
;   const u16* A1 = Ap + (size_t)128 * K;
;   const u16* B1p = Bp + (size_t)128 * K;
; #pragma unroll
;   for (int a = 0; a < 2; ++a)
; #pragma unroll
;     for (int b = 0; b < 2; ++b)
; #pragma unroll
;       for (int m = 0; m < 4; ++m)
; #pragma unroll
;         for (int n = 0; n < 2; ++n) acc[a][b][m][n] = f32x4{0.f, 0.f, 0.f, 0.f};
;   const int abase = lds_byte(wr * 64 + fr, fq * 8), bbase = lds_byte(wc * 32 + fr, fq * 8);
;   bf16x8 At[4][2], B0[2][2], B1[2][2];
;   const unsigned lds0 = (unsigned)(size_t)(__attribute__((address_space(3))) char*)shm + (unsigned)wvoff;
;     ...
;   const int nt = K / BK;
;   WAIT_V(0);
;   if (wr == 1) BAR;
;   BAR;
;   BAR;
;     ...
;     LDB8(B0, 0, 0); SCHED; LDA8(0, 0); STG_A(1, 1, t + 1);
;     WAIT_L(8); BAR; WAIT_L(0); MMA8(0, 0, B0); BAR; SCHED;
;     LDB8(B1, 0, 1); STG_B(0, 0, t + 2);
;     BAR; WAIT_L(0); MMA8(0, 1, B1); BAR;
.LBB0_98:
	s_or_b64 exec, exec, s[2:3]
	v_mov_b32_e32 v4, s14
	v_bfe_i32 v4, v4, 0, 8
	v_ashrrev_i32_e32 v5, 31, v4
	v_lshlrev_b64 v[4:5], 19, v[4:5]
	v_bfe_i32 v6, v0, 27, 1
	v_lshl_add_u64 v[130:131], s[0:1], 0, v[4:5]
	v_lshlrev_b32_e32 v4, 4, v0
	v_lshrrev_b32_e32 v6, 22, v6
	v_add_u32_e32 v6, v4, v6
	v_and_b32_e32 v6, 0xfffffc00, v6
	v_ashrrev_i32_e32 v5, 31, v0
	v_sub_u32_e32 v6, v4, v6
	v_lshrrev_b32_e32 v5, 26, v5
	v_lshrrev_b32_e32 v7, 4, v6
	v_add_u32_e32 v5, v0, v5
	v_bitop3_b32 v7, v7, v6, 32 bitop3:0x6c
	v_ashrrev_i32_e32 v6, 31, v6
	v_ashrrev_i32_e32 v5, 6, v5
	v_lshrrev_b32_e32 v6, 26, v6
	v_lshlrev_b32_e32 v8, 3, v5
	v_add_u32_e32 v6, v7, v6
	v_and_b32_e32 v8, 0x1ffff0, v8
	v_ashrrev_i32_e32 v6, 6, v6
	v_add_u32_e32 v8, v6, v8
	v_mul_i32_i24_e32 v6, 64, v6
	v_add_u32_e32 v4, 0x2000, v4
	v_sub_u32_e32 v6, v7, v6
	v_ashrrev_i32_e32 v7, 31, v4
	v_lshrrev_b32_e32 v7, 22, v7
	v_add_u32_e32 v7, v4, v7
	v_ashrrev_i32_e32 v7, 10, v7
	v_mul_i32_i24_e32 v9, 0x400, v7
	v_sub_u32_e32 v4, v4, v9
	v_lshrrev_b32_e32 v9, 4, v4
	v_bitop3_b32 v4, v9, v4, 32 bitop3:0x6c
	v_ashrrev_i32_e32 v10, 31, v4
	v_lshrrev_b32_e32 v10, 26, v10
	v_add_u32_e32 v10, v4, v10
	v_lshlrev_b32_e32 v9, 3, v7
	v_lshrrev_b32_e32 v11, 6, v10
	v_and_b32_e32 v10, 0xc0, v10
	s_ashr_i32 s5, s4, 31
	v_and_b32_e32 v9, 0x1ffff0, v9
	v_lshlrev_b32_e32 v7, 5, v7
	v_sub_u32_e32 v4, v4, v10
	s_lshl_b64 s[10:11], s[4:5], 11
	v_readlane_b32 s2, v253, 63
	v_lshlrev_b32_e32 v5, 5, v5
	v_add_u32_e32 v9, v11, v9
	v_and_b32_e32 v7, 32, v7
	v_ashrrev_i16_sdwa v4, v178, sext(v4) dst_sel:DWORD dst_unused:UNUSED_PAD src0_sel:DWORD src1_sel:BYTE_0
	v_readlane_b32 s3, v254, 0
	s_add_u32 s9, s2, s10
	v_and_b32_e32 v5, 32, v5
	v_ashrrev_i16_sdwa v6, v178, sext(v6) dst_sel:DWORD dst_unused:UNUSED_PAD src0_sel:DWORD src1_sel:BYTE_0
	v_bfe_i32 v4, v4, 0, 16
	v_lshl_or_b32 v7, v9, 10, v7
	s_addc_u32 s12, s3, s11
	v_bfe_i32 v6, v6, 0, 16
	v_lshl_or_b32 v5, v8, 10, v5
	v_and_b32_e32 v8, 15, v0
	v_add_lshl_u32 v135, v7, v4, 1
	s_lshl_b32 s13, s13, 10
	v_lshlrev_b32_e32 v7, 2, v0
	v_add_lshl_u32 v136, v5, v6, 1
	s_mov_b64 s[2:3], 0x40000
	v_and_b32_e32 v4, 48, v0
	v_lshlrev_b32_e32 v5, 6, v8
	v_and_b32_e32 v7, 32, v7
	s_add_i32 s14, s13, 0
	v_lshl_add_u64 v[132:133], v[130:131], 0, s[2:3]
	v_or_b32_e32 v6, v5, v4
	v_bitop3_b32 v4, v5, v7, v4 bitop3:0x36
	v_lshlrev_b32_e32 v2, 12, v2
	s_movk_i32 s2, 0x3000
	s_add_u32 s15, s9, 0x40100
	v_lshlrev_b32_e32 v3, 13, v3
	v_and_or_b32 v137, v2, s2, v4
	s_addc_u32 s16, s12, 0
	v_readlane_b32 s2, v254, 32
	v_bitop3_b32 v3, v6, v3, v7 bitop3:0xde
	s_add_u32 s17, s2, s10
	v_readlane_b32 s2, v254, 33
	v_mov_b32_e32 v2, 0
	s_addc_u32 s18, s2, s11
	s_mov_b32 s19, -2
	s_mov_b64 s[2:3], 0
	v_add_u32_e32 v134, 0, v3
	s_waitcnt lgkmcnt(0)
	v_readfirstlane_b32 s24, v130
	v_readfirstlane_b32 s25, v131
	v_readfirstlane_b32 s26, v132
	v_readfirstlane_b32 s27, v133
	s_barrier
	s_barrier
	v_add_u32_e32 v158, 0x10000, v137
	ds_read_b128 v[138:141], v158
	ds_read_b128 v[142:145], v158 offset:1024
	ds_read_b128 v[154:157], v158 offset:2048
	ds_read_b128 v[158:161], v158 offset:3072
	ds_read_b128 v[162:165], v134
	ds_read_b128 v[166:169], v134 offset:1024
	ds_read_b128 v[170:173], v134 offset:2048
	ds_read_b128 v[174:177], v134 offset:3072
	ds_read_b128 v[180:183], v134 offset:4096
	ds_read_b128 v[184:187], v134 offset:5120
	ds_read_b128 v[188:191], v134 offset:6144
	ds_read_b128 v[192:195], v134 offset:7168
	v_add_u32_e32 v208, 0x14000, v137
	ds_read_b128 v[196:199], v208
	ds_read_b128 v[200:203], v208 offset:1024
	ds_read_b128 v[204:207], v208 offset:2048
	ds_read_b128 v[208:211], v208 offset:3072
	s_add_u32 s22, s17, s2
	s_addc_u32 s23, s18, s3
	s_add_u32 s22, s22, 0x80
	s_addc_u32 s23, s23, 0
	s_add_i32 s36, s14, 0xc000
	s_mov_b32 m0, s36
	s_nop 0
	global_load_lds_dwordx4 v136, s[22:23]
	s_add_i32 s36, s14, 0xe000
	s_mov_b32 m0, s36
	s_nop 0
	global_load_lds_dwordx4 v135, s[22:23]
	s_waitcnt vmcnt(8) lgkmcnt(0)
	s_barrier
	s_setprio 1
	v_mfma_f32_16x16x32_bf16 v[126:129], v[162:165], v[138:141], 0
	v_mfma_f32_16x16x32_bf16 v[122:125], v[162:165], v[154:157], 0
	v_mfma_f32_16x16x32_bf16 v[118:121], v[170:173], v[138:141], 0
	v_mfma_f32_16x16x32_bf16 v[114:117], v[170:173], v[154:157], 0
	v_mfma_f32_16x16x32_bf16 v[110:113], v[180:183], v[138:141], 0
	v_mfma_f32_16x16x32_bf16 v[106:109], v[180:183], v[154:157], 0
	v_mfma_f32_16x16x32_bf16 v[102:105], v[188:191], v[138:141], 0
	v_mfma_f32_16x16x32_bf16 v[98:101], v[188:191], v[154:157], 0
	v_mfma_f32_16x16x32_bf16 v[126:129], v[166:169], v[142:145], v[126:129]
	v_mfma_f32_16x16x32_bf16 v[122:125], v[166:169], v[158:161], v[122:125]
	v_mfma_f32_16x16x32_bf16 v[118:121], v[174:177], v[142:145], v[118:121]
	v_mfma_f32_16x16x32_bf16 v[114:117], v[174:177], v[158:161], v[114:117]
	v_mfma_f32_16x16x32_bf16 v[110:113], v[184:187], v[142:145], v[110:113]
	v_mfma_f32_16x16x32_bf16 v[106:109], v[184:187], v[158:161], v[106:109]
	v_mfma_f32_16x16x32_bf16 v[102:105], v[192:195], v[142:145], v[102:105]
	v_mfma_f32_16x16x32_bf16 v[98:101], v[192:195], v[158:161], v[98:101]
	v_mfma_f32_16x16x32_bf16 v[94:97], v[162:165], v[196:199], 0
	v_mfma_f32_16x16x32_bf16 v[90:93], v[162:165], v[204:207], 0
	v_mfma_f32_16x16x32_bf16 v[86:89], v[170:173], v[196:199], 0
	v_mfma_f32_16x16x32_bf16 v[82:85], v[170:173], v[204:207], 0
	v_mfma_f32_16x16x32_bf16 v[78:81], v[180:183], v[196:199], 0
	v_mfma_f32_16x16x32_bf16 v[74:77], v[180:183], v[204:207], 0
	v_mfma_f32_16x16x32_bf16 v[70:73], v[188:191], v[196:199], 0
	v_mfma_f32_16x16x32_bf16 v[66:69], v[188:191], v[204:207], 0
	v_mfma_f32_16x16x32_bf16 v[94:97], v[166:169], v[200:203], v[94:97]
	v_mfma_f32_16x16x32_bf16 v[90:93], v[166:169], v[208:211], v[90:93]
	v_mfma_f32_16x16x32_bf16 v[86:89], v[174:177], v[200:203], v[86:89]
	v_mfma_f32_16x16x32_bf16 v[82:85], v[174:177], v[208:211], v[82:85]
	v_mfma_f32_16x16x32_bf16 v[78:81], v[184:187], v[200:203], v[78:81]
	v_mfma_f32_16x16x32_bf16 v[74:77], v[184:187], v[208:211], v[74:77]
	v_mfma_f32_16x16x32_bf16 v[70:73], v[192:195], v[200:203], v[70:73]
	v_mfma_f32_16x16x32_bf16 v[66:69], v[192:195], v[208:211], v[66:69]
	s_setprio 0
	s_barrier
; #define WAIT_V(n) asm volatile("s_waitcnt vmcnt(" #n ")" ::: "memory")
; #define WAIT_L(n) asm volatile("s_waitcnt lgkmcnt(" #n ")" ::: "memory")
; #define BAR __builtin_amdgcn_s_barrier()
; #define SCHED __builtin_amdgcn_sched_barrier(0)
; #define STG_A(b, h, kt) stage_half_s(lds0 + ((b) * 2 + (h)) * HT_B, ((h) ? A1 : Ap) + (kt) * BK, off0, off1)
; #define STG_B(b, h, kt) stage_half_s(lds0 + (4 + (b) * 2 + (h)) * HT_B, ((h) ? B1p : Bp) + (kt) * BK, off0, off1)
; #define STG_A(b, h, kt) stage_half_s(lds0 + ((b) * 2 + (h)) * HT_B, ((h) ? A1 : Ap) + (kt) * BK, off0, off1)
; #define STG_B(b, h, kt) stage_half_s(lds0 + (4 + (b) * 2 + (h)) * HT_B, ((h) ? B1p : Bp) + (kt) * BK, off0, off1)
; #define LDA8(b, h) _Pragma("unroll") for (int m = 0; m < 4; ++m) _Pragma("unroll") for (int k = 0; k < 2; ++k) \
;     At[m][k] = *(const bf16x8*)(SA_(shm, b, h) + abase + (m * 2 + k) * 1024)
; #define LDB8(dst, b, h) _Pragma("unroll") for (int n = 0; n < 2; ++n) _Pragma("unroll") for (int k = 0; k < 2; ++k) \
;     dst[n][k] = *(const bf16x8*)(SB_(shm, b, h) + bbase + (n * 2 + k) * 1024)
; #define MMA8(ai, bj, Bx) do { __builtin_amdgcn_s_setprio(1); \
;     _Pragma("unroll") for (int m = 0; m < 4; ++m) _Pragma("unroll") for (int n = 0; n < 2; ++n) _Pragma("unroll") for (int k = 0; k < 2; ++k) \
;       acc[ai][bj][m][n] = __builtin_amdgcn_mfma_f32_16x16x32_bf16(At[m][k], Bx[n][k], acc[ai][bj][m][n], 0, 0, 0); \
;     __builtin_amdgcn_s_setprio(0); } while (0)
; template <bool HS>
; __device__ __forceinline__ void gemm_tile8(const u16* __restrict__ Ap, const u16* __restrict__ Bp, int K,
;                                            f32x4 (&acc)[2][2][4][2], char* shm, const int tid, const float* hsr = nullptr) {
;     ...
;     LDA8(0, 1); STG_A(0, 0, t + 2);
;     BAR; WAIT_L(0); MMA8(1, 0, B0); BAR; SCHED;
;     STG_B(0, 1, t + 2);
;     WAIT_V(6); BAR; MMA8(1, 1, B1); BAR;
;     LDB8(B0, 1, 0); SCHED; LDA8(1, 0); STG_A(0, 1, t + 2);
;     WAIT_L(8); BAR; WAIT_L(0); MMA8(0, 0, B0); BAR; SCHED;
	ds_read_b128 v[162:165], v134 offset:16384
	ds_read_b128 v[166:169], v134 offset:17408
	ds_read_b128 v[170:173], v134 offset:18432
	ds_read_b128 v[174:177], v134 offset:19456
	ds_read_b128 v[180:183], v134 offset:20480
	ds_read_b128 v[184:187], v134 offset:21504
	ds_read_b128 v[188:191], v134 offset:22528
	ds_read_b128 v[192:195], v134 offset:23552
	s_add_u32 s22, s24, s2
	s_addc_u32 s23, s25, s3
	s_add_u32 s22, s22, 0x100
	s_addc_u32 s23, s23, 0
	s_add_i32 s36, s14, 0x10000
	s_mov_b32 m0, s36
	s_nop 0
	global_load_lds_dwordx4 v136, s[22:23]
	s_add_i32 s36, s14, 0x12000
	s_mov_b32 m0, s36
	s_nop 0
	global_load_lds_dwordx4 v135, s[22:23]
	s_add_u32 s22, s9, s2
	s_addc_u32 s23, s12, s3
	s_add_u32 s22, s22, 0x100
	s_addc_u32 s23, s23, 0
	s_mov_b32 m0, s14
	s_nop 0
	global_load_lds_dwordx4 v136, s[22:23]
	s_add_i32 s36, s14, 0x2000
	s_mov_b32 m0, s36
	s_nop 0
	global_load_lds_dwordx4 v135, s[22:23]
	s_add_u32 s22, s26, s2
	s_addc_u32 s23, s27, s3
	s_add_u32 s22, s22, 0x100
	s_addc_u32 s23, s23, 0
	s_add_i32 s36, s14, 0x14000
	s_mov_b32 m0, s36
	s_nop 0
	global_load_lds_dwordx4 v136, s[22:23]
	s_add_i32 s36, s14, 0x16000
	s_mov_b32 m0, s36
	s_nop 0
	global_load_lds_dwordx4 v135, s[22:23]
	s_waitcnt vmcnt(8) lgkmcnt(0)
	s_barrier
	s_setprio 1
	v_mfma_f32_16x16x32_bf16 v[62:65], v[162:165], v[138:141], 0
	v_mfma_f32_16x16x32_bf16 v[58:61], v[162:165], v[154:157], 0
	v_mfma_f32_16x16x32_bf16 v[54:57], v[170:173], v[138:141], 0
	v_mfma_f32_16x16x32_bf16 v[50:53], v[170:173], v[154:157], 0
	v_mfma_f32_16x16x32_bf16 v[46:49], v[180:183], v[138:141], 0
	v_mfma_f32_16x16x32_bf16 v[42:45], v[180:183], v[154:157], 0
	v_mfma_f32_16x16x32_bf16 v[38:41], v[188:191], v[138:141], 0
	v_mfma_f32_16x16x32_bf16 v[34:37], v[188:191], v[154:157], 0
	v_mfma_f32_16x16x32_bf16 v[62:65], v[166:169], v[142:145], v[62:65]
	v_mfma_f32_16x16x32_bf16 v[58:61], v[166:169], v[158:161], v[58:61]
	v_mfma_f32_16x16x32_bf16 v[54:57], v[174:177], v[142:145], v[54:57]
	v_mfma_f32_16x16x32_bf16 v[50:53], v[174:177], v[158:161], v[50:53]
	v_mfma_f32_16x16x32_bf16 v[46:49], v[184:187], v[142:145], v[46:49]
	v_mfma_f32_16x16x32_bf16 v[42:45], v[184:187], v[158:161], v[42:45]
	v_mfma_f32_16x16x32_bf16 v[38:41], v[192:195], v[142:145], v[38:41]
	v_mfma_f32_16x16x32_bf16 v[34:37], v[192:195], v[158:161], v[34:37]
	v_mfma_f32_16x16x32_bf16 v[30:33], v[162:165], v[196:199], 0
	v_mfma_f32_16x16x32_bf16 v[26:29], v[162:165], v[204:207], 0
	v_mfma_f32_16x16x32_bf16 v[22:25], v[170:173], v[196:199], 0
	v_mfma_f32_16x16x32_bf16 v[18:21], v[170:173], v[204:207], 0
	v_mfma_f32_16x16x32_bf16 v[14:17], v[180:183], v[196:199], 0
	v_mfma_f32_16x16x32_bf16 v[10:13], v[180:183], v[204:207], 0
	v_mfma_f32_16x16x32_bf16 v[6:9], v[188:191], v[196:199], 0
	v_mfma_f32_16x16x32_bf16 v[2:5], v[188:191], v[204:207], 0
	v_mfma_f32_16x16x32_bf16 v[30:33], v[166:169], v[200:203], v[30:33]
	v_mfma_f32_16x16x32_bf16 v[26:29], v[166:169], v[208:211], v[26:29]
	v_mfma_f32_16x16x32_bf16 v[22:25], v[174:177], v[200:203], v[22:25]
	v_mfma_f32_16x16x32_bf16 v[18:21], v[174:177], v[208:211], v[18:21]
	v_mfma_f32_16x16x32_bf16 v[14:17], v[184:187], v[200:203], v[14:17]
	v_mfma_f32_16x16x32_bf16 v[10:13], v[184:187], v[208:211], v[10:13]
	v_mfma_f32_16x16x32_bf16 v[6:9], v[192:195], v[200:203], v[6:9]
	v_mfma_f32_16x16x32_bf16 v[2:5], v[192:195], v[208:211], v[2:5]
	s_setprio 0
	s_barrier
	v_add_u32_e32 v158, 0x18000, v137
	ds_read_b128 v[138:141], v158
	ds_read_b128 v[142:145], v158 offset:1024
	ds_read_b128 v[154:157], v158 offset:2048
	ds_read_b128 v[158:161], v158 offset:3072
	ds_read_b128 v[162:165], v134 offset:32768
	ds_read_b128 v[166:169], v134 offset:33792
	ds_read_b128 v[170:173], v134 offset:34816
	ds_read_b128 v[174:177], v134 offset:35840
	ds_read_b128 v[180:183], v134 offset:36864
	ds_read_b128 v[184:187], v134 offset:37888
	ds_read_b128 v[188:191], v134 offset:38912
	ds_read_b128 v[192:195], v134 offset:39936
	v_add_u32_e32 v208, 0x1c000, v137
	ds_read_b128 v[196:199], v208
	ds_read_b128 v[200:203], v208 offset:1024
	ds_read_b128 v[204:207], v208 offset:2048
	ds_read_b128 v[208:211], v208 offset:3072
	s_add_u32 s22, s17, s2
	s_addc_u32 s23, s18, s3
	s_add_u32 s22, s22, 0x100
	s_addc_u32 s23, s23, 0
	s_add_i32 s36, s14, 0x4000
	s_mov_b32 m0, s36
	s_nop 0
	global_load_lds_dwordx4 v136, s[22:23]
	s_add_i32 s36, s14, 0x6000
	s_mov_b32 m0, s36
	s_nop 0
	global_load_lds_dwordx4 v135, s[22:23]
	s_waitcnt vmcnt(8) lgkmcnt(0)
	s_barrier
; #define WAIT_V(n) asm volatile("s_waitcnt vmcnt(" #n ")" ::: "memory")
; #define WAIT_L(n) asm volatile("s_waitcnt lgkmcnt(" #n ")" ::: "memory")
; #define BAR __builtin_amdgcn_s_barrier()
; #define SCHED __builtin_amdgcn_sched_barrier(0)
; #define STG_A(b, h, kt) stage_half_s(lds0 + ((b) * 2 + (h)) * HT_B, ((h) ? A1 : Ap) + (kt) * BK, off0, off1)
; #define STG_B(b, h, kt) stage_half_s(lds0 + (4 + (b) * 2 + (h)) * HT_B, ((h) ? B1p : Bp) + (kt) * BK, off0, off1)
; #define STG_A(b, h, kt) stage_half_s(lds0 + ((b) * 2 + (h)) * HT_B, ((h) ? A1 : Ap) + (kt) * BK, off0, off1)
; #define STG_B(b, h, kt) stage_half_s(lds0 + (4 + (b) * 2 + (h)) * HT_B, ((h) ? B1p : Bp) + (kt) * BK, off0, off1)
; #define LDA8(b, h) _Pragma("unroll") for (int m = 0; m < 4; ++m) _Pragma("unroll") for (int k = 0; k < 2; ++k) \
;     At[m][k] = *(const bf16x8*)(SA_(shm, b, h) + abase + (m * 2 + k) * 1024)
; #define LDB8(dst, b, h) _Pragma("unroll") for (int n = 0; n < 2; ++n) _Pragma("unroll") for (int k = 0; k < 2; ++k) \
;     dst[n][k] = *(const bf16x8*)(SB_(shm, b, h) + bbase + (n * 2 + k) * 1024)
; #define MMA8(ai, bj, Bx) do { __builtin_amdgcn_s_setprio(1); \
;     _Pragma("unroll") for (int m = 0; m < 4; ++m) _Pragma("unroll") for (int n = 0; n < 2; ++n) _Pragma("unroll") for (int k = 0; k < 2; ++k) \
;       acc[ai][bj][m][n] = __builtin_amdgcn_mfma_f32_16x16x32_bf16(At[m][k], Bx[n][k], acc[ai][bj][m][n], 0, 0, 0); \
;     __builtin_amdgcn_s_setprio(0); } while (0)
; template <bool HS>
; __device__ __forceinline__ void gemm_tile8(const u16* __restrict__ Ap, const u16* __restrict__ Bp, int K,
;                                            f32x4 (&acc)[2][2][4][2], char* shm, const int tid, const float* hsr = nullptr) {
;     ...
;     WAIT_L(8); BAR; WAIT_L(0); MMA8(0, 0, B0); BAR; SCHED;
;     LDB8(B1, 1, 1); STG_B(1, 0, t + 3);
;     BAR; WAIT_L(0); MMA8(0, 1, B1); BAR;
;     LDA8(1, 1); STG_A(1, 0, t + 3);
;     BAR; WAIT_L(0); MMA8(1, 0, B0); BAR; SCHED;
;     STG_B(1, 1, t + 3);
;     WAIT_V(6); BAR; MMA8(1, 1, B1); BAR;
;   }
	s_setprio 1
	v_mfma_f32_16x16x32_bf16 v[126:129], v[162:165], v[138:141], v[126:129]
	v_mfma_f32_16x16x32_bf16 v[122:125], v[162:165], v[154:157], v[122:125]
	v_mfma_f32_16x16x32_bf16 v[118:121], v[170:173], v[138:141], v[118:121]
	v_mfma_f32_16x16x32_bf16 v[114:117], v[170:173], v[154:157], v[114:117]
	v_mfma_f32_16x16x32_bf16 v[110:113], v[180:183], v[138:141], v[110:113]
	v_mfma_f32_16x16x32_bf16 v[106:109], v[180:183], v[154:157], v[106:109]
	v_mfma_f32_16x16x32_bf16 v[102:105], v[188:191], v[138:141], v[102:105]
	v_mfma_f32_16x16x32_bf16 v[98:101], v[188:191], v[154:157], v[98:101]
	v_mfma_f32_16x16x32_bf16 v[126:129], v[166:169], v[142:145], v[126:129]
	v_mfma_f32_16x16x32_bf16 v[122:125], v[166:169], v[158:161], v[122:125]
	v_mfma_f32_16x16x32_bf16 v[118:121], v[174:177], v[142:145], v[118:121]
	v_mfma_f32_16x16x32_bf16 v[114:117], v[174:177], v[158:161], v[114:117]
	v_mfma_f32_16x16x32_bf16 v[110:113], v[184:187], v[142:145], v[110:113]
	v_mfma_f32_16x16x32_bf16 v[106:109], v[184:187], v[158:161], v[106:109]
	v_mfma_f32_16x16x32_bf16 v[102:105], v[192:195], v[142:145], v[102:105]
	v_mfma_f32_16x16x32_bf16 v[98:101], v[192:195], v[158:161], v[98:101]
	v_mfma_f32_16x16x32_bf16 v[94:97], v[162:165], v[196:199], v[94:97]
	v_mfma_f32_16x16x32_bf16 v[90:93], v[162:165], v[204:207], v[90:93]
	v_mfma_f32_16x16x32_bf16 v[86:89], v[170:173], v[196:199], v[86:89]
	v_mfma_f32_16x16x32_bf16 v[82:85], v[170:173], v[204:207], v[82:85]
	v_mfma_f32_16x16x32_bf16 v[78:81], v[180:183], v[196:199], v[78:81]
	v_mfma_f32_16x16x32_bf16 v[74:77], v[180:183], v[204:207], v[74:77]
	v_mfma_f32_16x16x32_bf16 v[70:73], v[188:191], v[196:199], v[70:73]
	v_mfma_f32_16x16x32_bf16 v[66:69], v[188:191], v[204:207], v[66:69]
	v_mfma_f32_16x16x32_bf16 v[94:97], v[166:169], v[200:203], v[94:97]
	v_mfma_f32_16x16x32_bf16 v[90:93], v[166:169], v[208:211], v[90:93]
	v_mfma_f32_16x16x32_bf16 v[86:89], v[174:177], v[200:203], v[86:89]
	v_mfma_f32_16x16x32_bf16 v[82:85], v[174:177], v[208:211], v[82:85]
	v_mfma_f32_16x16x32_bf16 v[78:81], v[184:187], v[200:203], v[78:81]
	v_mfma_f32_16x16x32_bf16 v[74:77], v[184:187], v[208:211], v[74:77]
	v_mfma_f32_16x16x32_bf16 v[70:73], v[192:195], v[200:203], v[70:73]
	v_mfma_f32_16x16x32_bf16 v[66:69], v[192:195], v[208:211], v[66:69]
	s_setprio 0
	s_barrier
	ds_read_b128 v[162:165], v134 offset:49152
	ds_read_b128 v[166:169], v134 offset:50176
	ds_read_b128 v[170:173], v134 offset:51200
	ds_read_b128 v[174:177], v134 offset:52224
	ds_read_b128 v[180:183], v134 offset:53248
	ds_read_b128 v[184:187], v134 offset:54272
	ds_read_b128 v[188:191], v134 offset:55296
	ds_read_b128 v[192:195], v134 offset:56320
	s_add_u32 s22, s24, s2
	s_addc_u32 s23, s25, s3
	s_add_u32 s22, s22, 0x180
	s_addc_u32 s23, s23, 0
	s_add_i32 s36, s14, 0x18000
	s_mov_b32 m0, s36
	s_nop 0
	global_load_lds_dwordx4 v136, s[22:23]
	s_add_i32 s36, s14, 0x1a000
	s_mov_b32 m0, s36
	s_nop 0
	global_load_lds_dwordx4 v135, s[22:23]
	s_add_u32 s22, s9, s2
	s_addc_u32 s23, s12, s3
	s_add_u32 s22, s22, 0x180
	s_addc_u32 s23, s23, 0
	s_add_i32 s36, s14, 0x8000
	s_mov_b32 m0, s36
	s_nop 0
	global_load_lds_dwordx4 v136, s[22:23]
	s_add_i32 s36, s14, 0xa000
	s_mov_b32 m0, s36
	s_nop 0
	global_load_lds_dwordx4 v135, s[22:23]
	s_add_u32 s22, s26, s2
	s_addc_u32 s23, s27, s3
	s_add_u32 s22, s22, 0x180
	s_addc_u32 s23, s23, 0
	s_add_i32 s36, s14, 0x1c000
	s_mov_b32 m0, s36
	s_nop 0
	global_load_lds_dwordx4 v136, s[22:23]
	s_add_i32 s36, s14, 0x1e000
	s_mov_b32 m0, s36
	s_nop 0
	global_load_lds_dwordx4 v135, s[22:23]
	s_waitcnt vmcnt(8) lgkmcnt(0)
	s_barrier
	s_setprio 1
	v_mfma_f32_16x16x32_bf16 v[62:65], v[162:165], v[138:141], v[62:65]
	v_mfma_f32_16x16x32_bf16 v[58:61], v[162:165], v[154:157], v[58:61]
	v_mfma_f32_16x16x32_bf16 v[54:57], v[170:173], v[138:141], v[54:57]
	v_mfma_f32_16x16x32_bf16 v[50:53], v[170:173], v[154:157], v[50:53]
	v_mfma_f32_16x16x32_bf16 v[46:49], v[180:183], v[138:141], v[46:49]
	v_mfma_f32_16x16x32_bf16 v[42:45], v[180:183], v[154:157], v[42:45]
	v_mfma_f32_16x16x32_bf16 v[38:41], v[188:191], v[138:141], v[38:41]
	v_mfma_f32_16x16x32_bf16 v[34:37], v[188:191], v[154:157], v[34:37]
	v_mfma_f32_16x16x32_bf16 v[62:65], v[166:169], v[142:145], v[62:65]
	v_mfma_f32_16x16x32_bf16 v[58:61], v[166:169], v[158:161], v[58:61]
	v_mfma_f32_16x16x32_bf16 v[54:57], v[174:177], v[142:145], v[54:57]
	v_mfma_f32_16x16x32_bf16 v[50:53], v[174:177], v[158:161], v[50:53]
	v_mfma_f32_16x16x32_bf16 v[46:49], v[184:187], v[142:145], v[46:49]
	v_mfma_f32_16x16x32_bf16 v[42:45], v[184:187], v[158:161], v[42:45]
	v_mfma_f32_16x16x32_bf16 v[38:41], v[192:195], v[142:145], v[38:41]
	v_mfma_f32_16x16x32_bf16 v[34:37], v[192:195], v[158:161], v[34:37]
	v_mfma_f32_16x16x32_bf16 v[30:33], v[162:165], v[196:199], v[30:33]
	v_mfma_f32_16x16x32_bf16 v[26:29], v[162:165], v[204:207], v[26:29]
	v_mfma_f32_16x16x32_bf16 v[22:25], v[170:173], v[196:199], v[22:25]
	v_mfma_f32_16x16x32_bf16 v[18:21], v[170:173], v[204:207], v[18:21]
	v_mfma_f32_16x16x32_bf16 v[14:17], v[180:183], v[196:199], v[14:17]
	v_mfma_f32_16x16x32_bf16 v[10:13], v[180:183], v[204:207], v[10:13]
	v_mfma_f32_16x16x32_bf16 v[6:9], v[188:191], v[196:199], v[6:9]
	v_mfma_f32_16x16x32_bf16 v[2:5], v[188:191], v[204:207], v[2:5]
	v_mfma_f32_16x16x32_bf16 v[30:33], v[166:169], v[200:203], v[30:33]
	v_mfma_f32_16x16x32_bf16 v[26:29], v[166:169], v[208:211], v[26:29]
	v_mfma_f32_16x16x32_bf16 v[22:25], v[174:177], v[200:203], v[22:25]
	v_mfma_f32_16x16x32_bf16 v[18:21], v[174:177], v[208:211], v[18:21]
	v_mfma_f32_16x16x32_bf16 v[14:17], v[184:187], v[200:203], v[14:17]
	v_mfma_f32_16x16x32_bf16 v[10:13], v[184:187], v[208:211], v[10:13]
	v_mfma_f32_16x16x32_bf16 v[6:9], v[192:195], v[200:203], v[6:9]
	v_mfma_f32_16x16x32_bf16 v[2:5], v[192:195], v[208:211], v[2:5]
	s_setprio 0
	s_add_i32 s19, s19, 2
	s_add_u32 s2, s2, 0x100
	s_addc_u32 s3, s3, 0
	s_cmp_lt_u32 s19, 12
	s_barrier
	s_cbranch_scc0 .Lk_conv_out_exit

; #define WAIT_V(n) asm volatile("s_waitcnt vmcnt(" #n ")" ::: "memory")
; #define WAIT_L(n) asm volatile("s_waitcnt lgkmcnt(" #n ")" ::: "memory")
; #define BAR __builtin_amdgcn_s_barrier()
; #define STG_A(b, h, kt) stage_half_s(lds0 + ((b) * 2 + (h)) * HT_B, ((h) ? A1 : Ap) + (kt) * BK, off0, off1)
; #define STG_A(b, h, kt) stage_half_s(lds0 + ((b) * 2 + (h)) * HT_B, ((h) ? A1 : Ap) + (kt) * BK, off0, off1)
; #define LDA8(b, h) _Pragma("unroll") for (int m = 0; m < 4; ++m) _Pragma("unroll") for (int k = 0; k < 2; ++k) \
;     At[m][k] = *(const bf16x8*)(SA_(shm, b, h) + abase + (m * 2 + k) * 1024)
; #define LDB8(dst, b, h) _Pragma("unroll") for (int n = 0; n < 2; ++n) _Pragma("unroll") for (int k = 0; k < 2; ++k) \
;     dst[n][k] = *(const bf16x8*)(SB_(shm, b, h) + bbase + (n * 2 + k) * 1024)
; #define MMA8(ai, bj, Bx) do { __builtin_amdgcn_s_setprio(1); \
;     _Pragma("unroll") for (int m = 0; m < 4; ++m) _Pragma("unroll") for (int n = 0; n < 2; ++n) _Pragma("unroll") for (int k = 0; k < 2; ++k) \
;       acc[ai][bj][m][n] = __builtin_amdgcn_mfma_f32_16x16x32_bf16(At[m][k], Bx[n][k], acc[ai][bj][m][n], 0, 0, 0); \
;     __builtin_amdgcn_s_setprio(0); } while (0)
; template <bool HS>
; __device__ __forceinline__ void gemm_tile8(const u16* __restrict__ Ap, const u16* __restrict__ Bp, int K,
;                                            f32x4 (&acc)[2][2][4][2], char* shm, const int tid, const float* hsr = nullptr) {
;     ...
;   { LDB8(B0, 0, 0); LDA8(0, 0); STG_A(1, 1, nt - 1);
;     BAR; WAIT_L(0); MMA8(0, 0, B0); BAR;
;     LDB8(B1, 0, 1); BAR; WAIT_L(0); MMA8(0, 1, B1); BAR;
;     LDA8(0, 1); WAIT_V(4); BAR; WAIT_L(0); MMA8(1, 0, B0); MMA8(1, 1, B1); BAR; }
;   { LDB8(B0, 1, 0); LDA8(1, 0); WAIT_V(2); BAR; WAIT_L(0); MMA8(0, 0, B0); BAR;
;     LDB8(B1, 1, 1); WAIT_V(0); BAR; WAIT_L(0); MMA8(0, 1, B1); BAR;
.Lk_conv_out_exit:
	s_waitcnt vmcnt(6)
	s_add_i32 s20, s14, 0xc000
	s_add_i32 s21, s14, 0xe000
	v_add_u32_e32 v220, 0, v137
	v_add_u32_e32 v137, 0x10000, v220
	ds_read_b128 v[130:133], v137
	ds_read_b128 v[138:141], v137 offset:1024
	ds_read_b128 v[142:145], v137 offset:2048
	ds_read_b128 v[154:157], v137 offset:3072
	ds_read_b128 v[158:161], v134
	ds_read_b128 v[162:165], v134 offset:1024
	ds_read_b128 v[166:169], v134 offset:2048
	ds_read_b128 v[170:173], v134 offset:3072
	ds_read_b128 v[174:177], v134 offset:4096
	ds_read_b128 v[180:183], v134 offset:5120
	ds_read_b128 v[184:187], v134 offset:6144
	ds_read_b128 v[188:191], v134 offset:7168
	s_add_u32 s2, s9, 0x40780
	s_addc_u32 s3, s12, 0
	s_mov_b32 m0, s20
	s_nop 0
	global_load_lds_dwordx4 v136, s[2:3]
	s_nop 0
	s_mov_b32 m0, s21
	s_nop 0
	global_load_lds_dwordx4 v135, s[2:3]
	s_barrier
	s_waitcnt lgkmcnt(0)
	s_setprio 1
	s_waitcnt lgkmcnt(7)
	v_mfma_f32_16x16x32_bf16 v[126:129], v[158:161], v[130:133], v[126:129]
	s_waitcnt lgkmcnt(5)
	v_mfma_f32_16x16x32_bf16 v[118:121], v[166:169], v[130:133], v[118:121]
	v_mfma_f32_16x16x32_bf16 v[114:117], v[166:169], v[142:145], v[114:117]
	s_waitcnt lgkmcnt(1)
	v_mfma_f32_16x16x32_bf16 v[102:105], v[184:187], v[130:133], v[102:105]
	v_mfma_f32_16x16x32_bf16 v[98:101], v[184:187], v[142:145], v[98:101]
	v_mfma_f32_16x16x32_bf16 v[126:129], v[162:165], v[138:141], v[126:129]
	v_mfma_f32_16x16x32_bf16 v[122:125], v[158:161], v[142:145], v[122:125]
	v_mfma_f32_16x16x32_bf16 v[118:121], v[170:173], v[138:141], v[118:121]
	v_mfma_f32_16x16x32_bf16 v[114:117], v[170:173], v[154:157], v[114:117]
	v_mfma_f32_16x16x32_bf16 v[110:113], v[174:177], v[130:133], v[110:113]
	v_mfma_f32_16x16x32_bf16 v[106:109], v[174:177], v[142:145], v[106:109]
	s_waitcnt lgkmcnt(0)
	v_mfma_f32_16x16x32_bf16 v[102:105], v[188:191], v[138:141], v[102:105]
	v_mfma_f32_16x16x32_bf16 v[98:101], v[188:191], v[154:157], v[98:101]
	v_mfma_f32_16x16x32_bf16 v[192:195], v[162:165], v[154:157], v[122:125]
	v_mfma_f32_16x16x32_bf16 v[196:199], v[180:183], v[138:141], v[110:113]
	v_mfma_f32_16x16x32_bf16 v[200:203], v[180:183], v[154:157], v[106:109]
	s_setprio 0
	v_add_u32_e32 v135, 0x14000, v220
	s_barrier
	ds_read_b128 v[106:109], v135
	ds_read_b128 v[110:113], v135 offset:1024
	ds_read_b128 v[122:125], v135 offset:2048
	ds_read_b128 v[204:207], v135 offset:3072
	s_barrier
	s_waitcnt lgkmcnt(0)
	s_setprio 1
	s_waitcnt lgkmcnt(3)
	v_mfma_f32_16x16x32_bf16 v[86:89], v[166:169], v[106:109], v[86:89]
	s_waitcnt lgkmcnt(1)
	v_mfma_f32_16x16x32_bf16 v[82:85], v[166:169], v[122:125], v[82:85]
	v_mfma_f32_16x16x32_bf16 v[70:73], v[184:187], v[106:109], v[70:73]
	v_mfma_f32_16x16x32_bf16 v[94:97], v[158:161], v[106:109], v[94:97]
	v_mfma_f32_16x16x32_bf16 v[90:93], v[158:161], v[122:125], v[90:93]
	v_mfma_f32_16x16x32_bf16 v[86:89], v[170:173], v[110:113], v[86:89]
	s_waitcnt lgkmcnt(0)
	v_mfma_f32_16x16x32_bf16 v[82:85], v[170:173], v[204:207], v[82:85]
	v_mfma_f32_16x16x32_bf16 v[78:81], v[174:177], v[106:109], v[78:81]
	v_mfma_f32_16x16x32_bf16 v[74:77], v[174:177], v[122:125], v[74:77]
	v_mfma_f32_16x16x32_bf16 v[70:73], v[188:191], v[110:113], v[70:73]
	v_mfma_f32_16x16x32_bf16 v[66:69], v[184:187], v[122:125], v[66:69]
	v_mfma_f32_16x16x32_bf16 v[208:211], v[162:165], v[110:113], v[94:97]
	v_mfma_f32_16x16x32_bf16 v[158:161], v[162:165], v[204:207], v[90:93]
	v_mfma_f32_16x16x32_bf16 v[162:165], v[180:183], v[110:113], v[78:81]
	v_mfma_f32_16x16x32_bf16 v[166:169], v[180:183], v[204:207], v[74:77]
	v_mfma_f32_16x16x32_bf16 v[170:173], v[188:191], v[204:207], v[66:69]
	s_setprio 0
	s_barrier
	s_nop 0
	ds_read_b128 v[66:69], v134 offset:16384
	ds_read_b128 v[74:77], v134 offset:17408
	ds_read_b128 v[78:81], v134 offset:18432
	ds_read_b128 v[90:93], v134 offset:19456
	ds_read_b128 v[94:97], v134 offset:20480
	ds_read_b128 v[174:177], v134 offset:21504
	ds_read_b128 v[180:183], v134 offset:22528
	ds_read_b128 v[184:187], v134 offset:23552
	s_waitcnt vmcnt(4)
	s_barrier
	s_waitcnt lgkmcnt(0)
	s_setprio 1
	s_waitcnt lgkmcnt(7)
	v_mfma_f32_16x16x32_bf16 v[62:65], v[66:69], v[130:133], v[62:65]
	s_waitcnt lgkmcnt(5)
	v_mfma_f32_16x16x32_bf16 v[54:57], v[78:81], v[130:133], v[54:57]
	v_mfma_f32_16x16x32_bf16 v[50:53], v[78:81], v[142:145], v[50:53]
	s_waitcnt lgkmcnt(1)
	v_mfma_f32_16x16x32_bf16 v[38:41], v[180:183], v[130:133], v[38:41]
	v_mfma_f32_16x16x32_bf16 v[34:37], v[180:183], v[142:145], v[34:37]
	v_mfma_f32_16x16x32_bf16 v[62:65], v[74:77], v[138:141], v[62:65]
	v_mfma_f32_16x16x32_bf16 v[58:61], v[66:69], v[142:145], v[58:61]
	v_mfma_f32_16x16x32_bf16 v[54:57], v[90:93], v[138:141], v[54:57]
	v_mfma_f32_16x16x32_bf16 v[50:53], v[90:93], v[154:157], v[50:53]
	v_mfma_f32_16x16x32_bf16 v[46:49], v[94:97], v[130:133], v[46:49]
	v_mfma_f32_16x16x32_bf16 v[42:45], v[94:97], v[142:145], v[42:45]
	s_waitcnt lgkmcnt(0)
	v_mfma_f32_16x16x32_bf16 v[38:41], v[184:187], v[138:141], v[38:41]
	v_mfma_f32_16x16x32_bf16 v[34:37], v[184:187], v[154:157], v[34:37]
	v_mfma_f32_16x16x32_bf16 v[188:191], v[74:77], v[154:157], v[58:61]
	v_mfma_f32_16x16x32_bf16 v[212:215], v[174:177], v[138:141], v[46:49]
	v_mfma_f32_16x16x32_bf16 v[216:219], v[174:177], v[154:157], v[42:45]
	s_setprio 0
	s_setprio 1
	v_mfma_f32_16x16x32_bf16 v[22:25], v[78:81], v[106:109], v[22:25]
	v_mfma_f32_16x16x32_bf16 v[18:21], v[78:81], v[122:125], v[18:21]
	v_mfma_f32_16x16x32_bf16 v[6:9], v[180:183], v[106:109], v[6:9]
	v_mfma_f32_16x16x32_bf16 v[30:33], v[66:69], v[106:109], v[30:33]
	v_mfma_f32_16x16x32_bf16 v[26:29], v[66:69], v[122:125], v[26:29]
	v_mfma_f32_16x16x32_bf16 v[22:25], v[90:93], v[110:113], v[22:25]
	v_mfma_f32_16x16x32_bf16 v[18:21], v[90:93], v[204:207], v[18:21]
	v_mfma_f32_16x16x32_bf16 v[14:17], v[94:97], v[106:109], v[14:17]
	v_mfma_f32_16x16x32_bf16 v[10:13], v[94:97], v[122:125], v[10:13]
	v_mfma_f32_16x16x32_bf16 v[6:9], v[184:187], v[110:113], v[6:9]
	v_mfma_f32_16x16x32_bf16 v[2:5], v[180:183], v[122:125], v[2:5]
	v_mfma_f32_16x16x32_bf16 v[130:133], v[74:77], v[110:113], v[30:33]
	v_mfma_f32_16x16x32_bf16 v[136:139], v[74:77], v[204:207], v[26:29]
	v_mfma_f32_16x16x32_bf16 v[140:143], v[174:177], v[110:113], v[14:17]
	v_mfma_f32_16x16x32_bf16 v[154:157], v[174:177], v[204:207], v[10:13]
	v_mfma_f32_16x16x32_bf16 v[174:177], v[184:187], v[204:207], v[2:5]
	s_setprio 0
	v_add_u32_e32 v26, 0x18000, v220
	s_barrier
; #define WAIT_V(n) asm volatile("s_waitcnt vmcnt(" #n ")" ::: "memory")
; #define WAIT_L(n) asm volatile("s_waitcnt lgkmcnt(" #n ")" ::: "memory")
; #define BAR __builtin_amdgcn_s_barrier()
; #define LDA8(b, h) _Pragma("unroll") for (int m = 0; m < 4; ++m) _Pragma("unroll") for (int k = 0; k < 2; ++k) \
;     At[m][k] = *(const bf16x8*)(SA_(shm, b, h) + abase + (m * 2 + k) * 1024)
; #define LDB8(dst, b, h) _Pragma("unroll") for (int n = 0; n < 2; ++n) _Pragma("unroll") for (int k = 0; k < 2; ++k) \
;     dst[n][k] = *(const bf16x8*)(SB_(shm, b, h) + bbase + (n * 2 + k) * 1024)
; #define MMA8(ai, bj, Bx) do { __builtin_amdgcn_s_setprio(1); \
;     _Pragma("unroll") for (int m = 0; m < 4; ++m) _Pragma("unroll") for (int n = 0; n < 2; ++n) _Pragma("unroll") for (int k = 0; k < 2; ++k) \
;       acc[ai][bj][m][n] = __builtin_amdgcn_mfma_f32_16x16x32_bf16(At[m][k], Bx[n][k], acc[ai][bj][m][n], 0, 0, 0); \
;     __builtin_amdgcn_s_setprio(0); } while (0)
; template <bool HS>
; __device__ __forceinline__ void gemm_tile8(const u16* __restrict__ Ap, const u16* __restrict__ Bp, int K,
;                                            f32x4 (&acc)[2][2][4][2], char* shm, const int tid, const float* hsr = nullptr) {
;     ...
;     LDA8(0, 1); WAIT_V(4); BAR; WAIT_L(0); MMA8(1, 0, B0); MMA8(1, 1, B1); BAR; }
;   { LDB8(B0, 1, 0); LDA8(1, 0); WAIT_V(2); BAR; WAIT_L(0); MMA8(0, 0, B0); BAR;
;     LDB8(B1, 1, 1); WAIT_V(0); BAR; WAIT_L(0); MMA8(0, 1, B1); BAR;
;     LDA8(1, 1); BAR; WAIT_L(0); MMA8(1, 0, B0); MMA8(1, 1, B1); BAR; }
;   if (wr == 0) BAR;
	ds_read_b128 v[2:5], v26
	ds_read_b128 v[10:13], v26 offset:1024
	ds_read_b128 v[14:17], v26 offset:2048
	ds_read_b128 v[180:183], v26 offset:3072
	ds_read_b128 v[26:29], v134 offset:32768
	ds_read_b128 v[30:33], v134 offset:33792
	ds_read_b128 v[42:45], v134 offset:34816
	ds_read_b128 v[46:49], v134 offset:35840
	ds_read_b128 v[58:61], v134 offset:36864
	ds_read_b128 v[66:69], v134 offset:37888
	ds_read_b128 v[184:187], v134 offset:38912
	ds_read_b128 v[204:207], v134 offset:39936
	s_waitcnt vmcnt(2)
	s_barrier
	s_waitcnt lgkmcnt(0)
	s_setprio 1
	s_waitcnt lgkmcnt(7)
	v_mfma_f32_16x16x32_bf16 v[74:77], v[26:29], v[2:5], v[126:129]
	s_waitcnt lgkmcnt(6)
	v_mfma_f32_16x16x32_bf16 v[122:125], v[30:33], v[10:13], v[74:77]
	v_mfma_f32_16x16x32_bf16 v[74:77], v[26:29], v[14:17], v[192:195]
	v_mfma_f32_16x16x32_bf16 v[126:129], v[30:33], v[180:183], v[74:77]
	s_waitcnt lgkmcnt(5)
	v_mfma_f32_16x16x32_bf16 v[74:77], v[42:45], v[2:5], v[118:121]
	s_waitcnt lgkmcnt(4)
	v_mfma_f32_16x16x32_bf16 v[106:109], v[46:49], v[10:13], v[74:77]
	v_mfma_f32_16x16x32_bf16 v[74:77], v[42:45], v[14:17], v[114:117]
	v_mfma_f32_16x16x32_bf16 v[110:113], v[46:49], v[180:183], v[74:77]
	s_waitcnt lgkmcnt(3)
	v_mfma_f32_16x16x32_bf16 v[74:77], v[58:61], v[2:5], v[196:199]
	s_waitcnt lgkmcnt(2)
	v_mfma_f32_16x16x32_bf16 v[90:93], v[66:69], v[10:13], v[74:77]
	v_mfma_f32_16x16x32_bf16 v[74:77], v[58:61], v[14:17], v[200:203]
	v_mfma_f32_16x16x32_bf16 v[94:97], v[66:69], v[180:183], v[74:77]
	s_waitcnt lgkmcnt(1)
	v_mfma_f32_16x16x32_bf16 v[74:77], v[184:187], v[2:5], v[102:105]
	v_mfma_f32_16x16x32_bf16 v[78:81], v[184:187], v[14:17], v[98:101]
	s_waitcnt lgkmcnt(0)
	v_mfma_f32_16x16x32_bf16 v[74:77], v[204:207], v[10:13], v[74:77]
	v_mfma_f32_16x16x32_bf16 v[78:81], v[204:207], v[180:183], v[78:81]
	s_setprio 0
	v_add_u32_e32 v98, 0x1c000, v220
	s_barrier
	ds_read_b128 v[192:195], v98
	ds_read_b128 v[196:199], v98 offset:1024
	ds_read_b128 v[200:203], v98 offset:2048
	ds_read_b128 v[220:223], v98 offset:3072
	s_waitcnt vmcnt(0)
	s_barrier
	s_waitcnt lgkmcnt(0)
	s_setprio 1
	s_waitcnt lgkmcnt(3)
	v_mfma_f32_16x16x32_bf16 v[98:101], v[26:29], v[192:195], v[208:211]
	s_waitcnt lgkmcnt(1)
	v_mfma_f32_16x16x32_bf16 v[26:29], v[26:29], v[200:203], v[158:161]
	s_waitcnt lgkmcnt(0)
	v_mfma_f32_16x16x32_bf16 v[118:121], v[30:33], v[220:223], v[26:29]
	v_mfma_f32_16x16x32_bf16 v[26:29], v[42:45], v[192:195], v[86:89]
	v_mfma_f32_16x16x32_bf16 v[114:117], v[30:33], v[196:199], v[98:101]
	v_mfma_f32_16x16x32_bf16 v[98:101], v[46:49], v[196:199], v[26:29]
	v_mfma_f32_16x16x32_bf16 v[26:29], v[42:45], v[200:203], v[82:85]
	v_mfma_f32_16x16x32_bf16 v[102:105], v[46:49], v[220:223], v[26:29]
	v_mfma_f32_16x16x32_bf16 v[26:29], v[58:61], v[192:195], v[162:165]
	v_mfma_f32_16x16x32_bf16 v[82:85], v[66:69], v[196:199], v[26:29]
	v_mfma_f32_16x16x32_bf16 v[26:29], v[58:61], v[200:203], v[166:169]
	v_mfma_f32_16x16x32_bf16 v[86:89], v[66:69], v[220:223], v[26:29]
	v_mfma_f32_16x16x32_bf16 v[26:29], v[184:187], v[192:195], v[70:73]
	v_mfma_f32_16x16x32_bf16 v[66:69], v[204:207], v[196:199], v[26:29]
	v_mfma_f32_16x16x32_bf16 v[26:29], v[184:187], v[200:203], v[170:173]
	v_mfma_f32_16x16x32_bf16 v[70:73], v[204:207], v[220:223], v[26:29]
	s_setprio 0
	s_barrier
	ds_read_b128 v[158:161], v134 offset:49152
	ds_read_b128 v[162:165], v134 offset:50176
	ds_read_b128 v[166:169], v134 offset:51200
	ds_read_b128 v[170:173], v134 offset:52224
	ds_read_b128 v[184:187], v134 offset:53248
	ds_read_b128 v[204:207], v134 offset:54272
	ds_read_b128 v[208:211], v134 offset:55296
	ds_read_b128 v[224:227], v134 offset:56320
	s_barrier
	s_waitcnt lgkmcnt(0)
	s_setprio 1
	s_waitcnt lgkmcnt(7)
	v_mfma_f32_16x16x32_bf16 v[26:29], v[158:161], v[2:5], v[62:65]
	s_waitcnt lgkmcnt(6)
	v_mfma_f32_16x16x32_bf16 v[58:61], v[162:165], v[10:13], v[26:29]
	v_mfma_f32_16x16x32_bf16 v[26:29], v[158:161], v[14:17], v[188:191]
	v_mfma_f32_16x16x32_bf16 v[62:65], v[162:165], v[180:183], v[26:29]
	s_waitcnt lgkmcnt(5)
	v_mfma_f32_16x16x32_bf16 v[26:29], v[166:169], v[2:5], v[54:57]
	s_waitcnt lgkmcnt(4)
	v_mfma_f32_16x16x32_bf16 v[42:45], v[170:173], v[10:13], v[26:29]
	v_mfma_f32_16x16x32_bf16 v[26:29], v[166:169], v[14:17], v[50:53]
	v_mfma_f32_16x16x32_bf16 v[46:49], v[170:173], v[180:183], v[26:29]
	s_waitcnt lgkmcnt(3)
	v_mfma_f32_16x16x32_bf16 v[26:29], v[184:187], v[2:5], v[212:215]
	s_waitcnt lgkmcnt(1)
	v_mfma_f32_16x16x32_bf16 v[2:5], v[208:211], v[2:5], v[38:41]
	v_mfma_f32_16x16x32_bf16 v[26:29], v[204:207], v[10:13], v[26:29]
	v_mfma_f32_16x16x32_bf16 v[30:33], v[184:187], v[14:17], v[216:219]
	s_waitcnt lgkmcnt(0)
	v_mfma_f32_16x16x32_bf16 v[10:13], v[224:227], v[10:13], v[2:5]
	v_mfma_f32_16x16x32_bf16 v[2:5], v[208:211], v[14:17], v[34:37]
	v_mfma_f32_16x16x32_bf16 v[30:33], v[204:207], v[180:183], v[30:33]
	v_mfma_f32_16x16x32_bf16 v[14:17], v[224:227], v[180:183], v[2:5]
	s_setprio 0
	s_setprio 1
	v_mfma_f32_16x16x32_bf16 v[2:5], v[158:161], v[192:195], v[130:133]
	v_mfma_f32_16x16x32_bf16 v[50:53], v[162:165], v[196:199], v[2:5]
	v_mfma_f32_16x16x32_bf16 v[2:5], v[158:161], v[200:203], v[136:139]
	v_mfma_f32_16x16x32_bf16 v[54:57], v[162:165], v[220:223], v[2:5]
	v_mfma_f32_16x16x32_bf16 v[2:5], v[166:169], v[192:195], v[22:25]
	v_mfma_f32_16x16x32_bf16 v[34:37], v[170:173], v[196:199], v[2:5]
	v_mfma_f32_16x16x32_bf16 v[2:5], v[166:169], v[200:203], v[18:21]
	v_mfma_f32_16x16x32_bf16 v[38:41], v[170:173], v[220:223], v[2:5]
	v_mfma_f32_16x16x32_bf16 v[2:5], v[184:187], v[192:195], v[140:143]
	v_mfma_f32_16x16x32_bf16 v[18:21], v[204:207], v[196:199], v[2:5]
	v_mfma_f32_16x16x32_bf16 v[2:5], v[184:187], v[200:203], v[154:157]
	v_mfma_f32_16x16x32_bf16 v[22:25], v[204:207], v[220:223], v[2:5]
	v_mfma_f32_16x16x32_bf16 v[2:5], v[208:211], v[192:195], v[6:9]
	v_mfma_f32_16x16x32_bf16 v[6:9], v[208:211], v[200:203], v[174:177]
	v_mfma_f32_16x16x32_bf16 v[2:5], v[224:227], v[196:199], v[2:5]
	v_mfma_f32_16x16x32_bf16 v[6:9], v[224:227], v[220:223], v[6:9]
	s_setprio 0
	s_movk_i32 s2, 0x100
	v_cmp_gt_u32_e32 vcc, s2, v0
	s_barrier
	s_and_saveexec_b64 s[2:3], vcc
	s_cbranch_execz .LBB0_102
	s_barrier

; #define WAIT_V(n) asm volatile("s_waitcnt vmcnt(" #n ")" ::: "memory")
; #define WAIT_L(n) asm volatile("s_waitcnt lgkmcnt(" #n ")" ::: "memory")
; #define BAR __builtin_amdgcn_s_barrier()
; #define SCHED __builtin_amdgcn_sched_barrier(0)
; #define STG_A(b, h, kt) stage_half_s(lds0 + ((b) * 2 + (h)) * HT_B, ((h) ? A1 : Ap) + (kt) * BK, off0, off1)
; #define STG_B(b, h, kt) stage_half_s(lds0 + (4 + (b) * 2 + (h)) * HT_B, ((h) ? B1p : Bp) + (kt) * BK, off0, off1)
; #define STG_A(b, h, kt) stage_half_s(lds0 + ((b) * 2 + (h)) * HT_B, ((h) ? A1 : Ap) + (kt) * BK, off0, off1)
; #define STG_B(b, h, kt) stage_half_s(lds0 + (4 + (b) * 2 + (h)) * HT_B, ((h) ? B1p : Bp) + (kt) * BK, off0, off1)
; #define LDA8(b, h) _Pragma("unroll") for (int m = 0; m < 4; ++m) _Pragma("unroll") for (int k = 0; k < 2; ++k) \
;     At[m][k] = *(const bf16x8*)(SA_(shm, b, h) + abase + (m * 2 + k) * 1024)
; template <bool HS>
; __device__ __forceinline__ void gemm_tile8(const u16* __restrict__ Ap, const u16* __restrict__ Bp, int K,
;                                            f32x4 (&acc)[2][2][4][2], char* shm, const int tid, const float* hsr = nullptr) {
;   const int wid = tid >> 6, lane = tid & 63, wr = wid >> 2, wc = wid & 3, fr = lane & 15, fq = lane >> 4;
;   int r0, c0, r1, c1;
;   stage_rc(tid * 16, r0, c0);
;   stage_rc(tid * 16 + 8192, r1, c1);
;   const unsigned off0 = (unsigned)(r0 * K + c0) * 2u, off1 = (unsigned)(r1 * K + c1) * 2u;
;   const int wvoff = __builtin_amdgcn_readfirstlane(tid >> 6) * 1024;
;   const u16* A1 = Ap + (size_t)128 * K;
;   const u16* B1p = Bp + (size_t)128 * K;
; #pragma unroll
;   for (int a = 0; a < 2; ++a)
; #pragma unroll
;     for (int b = 0; b < 2; ++b)
; #pragma unroll
;       for (int m = 0; m < 4; ++m)
; #pragma unroll
;         for (int n = 0; n < 2; ++n) acc[a][b][m][n] = f32x4{0.f, 0.f, 0.f, 0.f};
;   const int abase = lds_byte(wr * 64 + fr, fq * 8), bbase = lds_byte(wc * 32 + fr, fq * 8);
;   bf16x8 At[4][2], B0[2][2], B1[2][2];
;   const unsigned lds0 = (unsigned)(size_t)(__attribute__((address_space(3))) char*)shm + (unsigned)wvoff;
;     ...
;   const int nt = K / BK;
;   WAIT_V(0);
;   if (wr == 1) BAR;
;   BAR;
;   BAR;
;     ...
;     LDB8(B0, 0, 0); SCHED; LDA8(0, 0); STG_A(1, 1, t + 1);
;     WAIT_L(8); BAR; WAIT_L(0); MMA8(0, 0, B0); BAR; SCHED;
;     LDB8(B1, 0, 1); STG_B(0, 0, t + 2);
;     BAR; WAIT_L(0); MMA8(0, 1, B1); BAR;
.LBB0_317:
	s_or_b64 exec, exec, s[6:7]
	v_mov_b32_e32 v4, s11
	v_bfe_i32 v4, v4, 0, 8
	v_ashrrev_i32_e32 v5, 31, v4
	v_lshlrev_b64 v[4:5], 19, v[4:5]
	v_bfe_i32 v6, v0, 27, 1
	v_lshl_add_u64 v[130:131], s[0:1], 0, v[4:5]
	v_lshlrev_b32_e32 v4, 4, v0
	v_lshrrev_b32_e32 v6, 22, v6
	v_add_u32_e32 v6, v4, v6
	v_and_b32_e32 v6, 0xfffffc00, v6
	v_ashrrev_i32_e32 v5, 31, v0
	v_sub_u32_e32 v6, v4, v6
	v_lshrrev_b32_e32 v5, 26, v5
	v_lshrrev_b32_e32 v7, 4, v6
	v_add_u32_e32 v5, v0, v5
	v_bitop3_b32 v7, v7, v6, 32 bitop3:0x6c
	v_ashrrev_i32_e32 v6, 31, v6
	v_ashrrev_i32_e32 v5, 6, v5
	v_lshrrev_b32_e32 v6, 26, v6
	v_lshlrev_b32_e32 v8, 3, v5
	v_add_u32_e32 v6, v7, v6
	v_and_b32_e32 v8, 0x1ffff0, v8
	v_ashrrev_i32_e32 v6, 6, v6
	v_add_u32_e32 v8, v6, v8
	v_mul_i32_i24_e32 v6, 64, v6
	v_add_u32_e32 v4, 0x2000, v4
	v_sub_u32_e32 v6, v7, v6
	v_ashrrev_i32_e32 v7, 31, v4
	v_lshrrev_b32_e32 v7, 22, v7
	v_add_u32_e32 v7, v4, v7
	v_ashrrev_i32_e32 v7, 10, v7
	v_mul_i32_i24_e32 v9, 0x400, v7
	v_sub_u32_e32 v4, v4, v9
	v_lshrrev_b32_e32 v9, 4, v4
	v_bitop3_b32 v4, v9, v4, 32 bitop3:0x6c
	v_ashrrev_i32_e32 v10, 31, v4
	v_lshrrev_b32_e32 v10, 26, v10
	v_add_u32_e32 v10, v4, v10
	v_lshlrev_b32_e32 v9, 3, v7
	v_lshrrev_b32_e32 v11, 6, v10
	v_and_b32_e32 v10, 0xc0, v10
	s_ashr_i32 s5, s4, 31
	v_and_b32_e32 v9, 0x1ffff0, v9
	v_lshlrev_b32_e32 v7, 5, v7
	v_sub_u32_e32 v4, v4, v10
	s_lshl_b64 s[6:7], s[4:5], 11
	v_lshlrev_b32_e32 v5, 5, v5
	v_add_u32_e32 v9, v11, v9
	v_and_b32_e32 v7, 32, v7
	v_ashrrev_i16_sdwa v4, v178, sext(v4) dst_sel:DWORD dst_unused:UNUSED_PAD src0_sel:DWORD src1_sel:BYTE_0
	s_add_u32 s8, s88, s6
	v_and_b32_e32 v5, 32, v5
	v_ashrrev_i16_sdwa v6, v178, sext(v6) dst_sel:DWORD dst_unused:UNUSED_PAD src0_sel:DWORD src1_sel:BYTE_0
	v_bfe_i32 v4, v4, 0, 16
	v_lshl_or_b32 v7, v9, 10, v7
	s_addc_u32 s9, s89, s7
	v_bfe_i32 v6, v6, 0, 16
	v_lshl_or_b32 v5, v8, 10, v5
	v_and_b32_e32 v8, 15, v0
	v_add_lshl_u32 v139, v7, v4, 1
	s_lshl_b32 s10, s10, 10
	v_lshlrev_b32_e32 v7, 2, v0
	v_add_lshl_u32 v140, v5, v6, 1
	s_mov_b64 s[4:5], 0x40000
	v_and_b32_e32 v4, 48, v0
	v_lshlrev_b32_e32 v5, 6, v8
	v_and_b32_e32 v7, 32, v7
	s_add_i32 s11, s10, 0
	v_lshl_add_u64 v[132:133], v[130:131], 0, s[4:5]
	v_or_b32_e32 v6, v5, v4
	v_bitop3_b32 v4, v5, v7, v4 bitop3:0x36
	v_lshlrev_b32_e32 v2, 12, v2
	s_movk_i32 s4, 0x3000
	s_add_u32 s13, s8, 0x40100
	v_lshlrev_b32_e32 v3, 13, v3
	v_and_or_b32 v141, v2, s4, v4
	s_addc_u32 s14, s9, 0
	v_readlane_b32 s4, v254, 34
	v_bitop3_b32 v3, v6, v3, v7 bitop3:0xde
	s_add_u32 s15, s4, s6
	v_readlane_b32 s4, v254, 35
	v_mov_b32_e32 v2, 0
	s_addc_u32 s16, s4, s7
	s_mov_b32 s17, -2
	s_mov_b64 s[4:5], 0
	v_add_u32_e32 v138, 0, v3
	s_waitcnt lgkmcnt(0)
	v_readfirstlane_b32 s24, v130
	v_readfirstlane_b32 s25, v131
	v_readfirstlane_b32 s22, v132
	v_readfirstlane_b32 s23, v133
	s_barrier
	s_barrier
	v_add_u32_e32 v154, 0x10000, v141
	ds_read_b128 v[142:145], v154
	ds_read_b128 v[146:149], v154 offset:1024
	ds_read_b128 v[150:153], v154 offset:2048
	ds_read_b128 v[154:157], v154 offset:3072
	ds_read_b128 v[158:161], v138
	ds_read_b128 v[162:165], v138 offset:1024
	ds_read_b128 v[166:169], v138 offset:2048
	ds_read_b128 v[170:173], v138 offset:3072
	ds_read_b128 v[174:177], v138 offset:4096
	ds_read_b128 v[180:183], v138 offset:5120
	ds_read_b128 v[184:187], v138 offset:6144
	ds_read_b128 v[188:191], v138 offset:7168
	v_add_u32_e32 v204, 0x14000, v141
	ds_read_b128 v[192:195], v204
	ds_read_b128 v[196:199], v204 offset:1024
	ds_read_b128 v[200:203], v204 offset:2048
	ds_read_b128 v[204:207], v204 offset:3072
	s_add_u32 s20, s15, s4
	s_addc_u32 s21, s16, s5
	s_add_u32 s20, s20, 0x80
	s_addc_u32 s21, s21, 0
	s_add_i32 s18, s11, 0xc000
	s_mov_b32 m0, s18
	s_nop 0
	global_load_lds_dwordx4 v140, s[20:21]
	s_add_i32 s18, s11, 0xe000
	s_mov_b32 m0, s18
	s_nop 0
	global_load_lds_dwordx4 v139, s[20:21]
	s_waitcnt vmcnt(8) lgkmcnt(0)
	s_barrier
	s_setprio 1
	v_mfma_f32_16x16x32_bf16 v[126:129], v[158:161], v[142:145], 0
	v_mfma_f32_16x16x32_bf16 v[122:125], v[158:161], v[150:153], 0
	v_mfma_f32_16x16x32_bf16 v[118:121], v[166:169], v[142:145], 0
	v_mfma_f32_16x16x32_bf16 v[114:117], v[166:169], v[150:153], 0
	v_mfma_f32_16x16x32_bf16 v[110:113], v[174:177], v[142:145], 0
	v_mfma_f32_16x16x32_bf16 v[106:109], v[174:177], v[150:153], 0
	v_mfma_f32_16x16x32_bf16 v[102:105], v[184:187], v[142:145], 0
	v_mfma_f32_16x16x32_bf16 v[98:101], v[184:187], v[150:153], 0
	v_mfma_f32_16x16x32_bf16 v[126:129], v[162:165], v[146:149], v[126:129]
	v_mfma_f32_16x16x32_bf16 v[122:125], v[162:165], v[154:157], v[122:125]
	v_mfma_f32_16x16x32_bf16 v[118:121], v[170:173], v[146:149], v[118:121]
	v_mfma_f32_16x16x32_bf16 v[114:117], v[170:173], v[154:157], v[114:117]
	v_mfma_f32_16x16x32_bf16 v[110:113], v[180:183], v[146:149], v[110:113]
	v_mfma_f32_16x16x32_bf16 v[106:109], v[180:183], v[154:157], v[106:109]
	v_mfma_f32_16x16x32_bf16 v[102:105], v[188:191], v[146:149], v[102:105]
	v_mfma_f32_16x16x32_bf16 v[98:101], v[188:191], v[154:157], v[98:101]
	v_mfma_f32_16x16x32_bf16 v[94:97], v[158:161], v[192:195], 0
	v_mfma_f32_16x16x32_bf16 v[90:93], v[158:161], v[200:203], 0
	v_mfma_f32_16x16x32_bf16 v[86:89], v[166:169], v[192:195], 0
	v_mfma_f32_16x16x32_bf16 v[82:85], v[166:169], v[200:203], 0
	v_mfma_f32_16x16x32_bf16 v[78:81], v[174:177], v[192:195], 0
	v_mfma_f32_16x16x32_bf16 v[74:77], v[174:177], v[200:203], 0
	v_mfma_f32_16x16x32_bf16 v[70:73], v[184:187], v[192:195], 0
	v_mfma_f32_16x16x32_bf16 v[66:69], v[184:187], v[200:203], 0
	v_mfma_f32_16x16x32_bf16 v[94:97], v[162:165], v[196:199], v[94:97]
	v_mfma_f32_16x16x32_bf16 v[90:93], v[162:165], v[204:207], v[90:93]
	v_mfma_f32_16x16x32_bf16 v[86:89], v[170:173], v[196:199], v[86:89]
	v_mfma_f32_16x16x32_bf16 v[82:85], v[170:173], v[204:207], v[82:85]
	v_mfma_f32_16x16x32_bf16 v[78:81], v[180:183], v[196:199], v[78:81]
	v_mfma_f32_16x16x32_bf16 v[74:77], v[180:183], v[204:207], v[74:77]
	v_mfma_f32_16x16x32_bf16 v[70:73], v[188:191], v[196:199], v[70:73]
	v_mfma_f32_16x16x32_bf16 v[66:69], v[188:191], v[204:207], v[66:69]
	s_setprio 0
	s_barrier
; #define WAIT_V(n) asm volatile("s_waitcnt vmcnt(" #n ")" ::: "memory")
; #define WAIT_L(n) asm volatile("s_waitcnt lgkmcnt(" #n ")" ::: "memory")
; #define BAR __builtin_amdgcn_s_barrier()
; #define SCHED __builtin_amdgcn_sched_barrier(0)
; #define STG_A(b, h, kt) stage_half_s(lds0 + ((b) * 2 + (h)) * HT_B, ((h) ? A1 : Ap) + (kt) * BK, off0, off1)
; #define STG_B(b, h, kt) stage_half_s(lds0 + (4 + (b) * 2 + (h)) * HT_B, ((h) ? B1p : Bp) + (kt) * BK, off0, off1)
; #define STG_A(b, h, kt) stage_half_s(lds0 + ((b) * 2 + (h)) * HT_B, ((h) ? A1 : Ap) + (kt) * BK, off0, off1)
; #define STG_B(b, h, kt) stage_half_s(lds0 + (4 + (b) * 2 + (h)) * HT_B, ((h) ? B1p : Bp) + (kt) * BK, off0, off1)
; #define LDA8(b, h) _Pragma("unroll") for (int m = 0; m < 4; ++m) _Pragma("unroll") for (int k = 0; k < 2; ++k) \
;     At[m][k] = *(const bf16x8*)(SA_(shm, b, h) + abase + (m * 2 + k) * 1024)
; #define LDB8(dst, b, h) _Pragma("unroll") for (int n = 0; n < 2; ++n) _Pragma("unroll") for (int k = 0; k < 2; ++k) \
;     dst[n][k] = *(const bf16x8*)(SB_(shm, b, h) + bbase + (n * 2 + k) * 1024)
; #define MMA8(ai, bj, Bx) do { __builtin_amdgcn_s_setprio(1); \
;     _Pragma("unroll") for (int m = 0; m < 4; ++m) _Pragma("unroll") for (int n = 0; n < 2; ++n) _Pragma("unroll") for (int k = 0; k < 2; ++k) \
;       acc[ai][bj][m][n] = __builtin_amdgcn_mfma_f32_16x16x32_bf16(At[m][k], Bx[n][k], acc[ai][bj][m][n], 0, 0, 0); \
;     __builtin_amdgcn_s_setprio(0); } while (0)
; template <bool HS>
; __device__ __forceinline__ void gemm_tile8(const u16* __restrict__ Ap, const u16* __restrict__ Bp, int K,
;                                            f32x4 (&acc)[2][2][4][2], char* shm, const int tid, const float* hsr = nullptr) {
;     ...
;     LDA8(0, 1); STG_A(0, 0, t + 2);
;     BAR; WAIT_L(0); MMA8(1, 0, B0); BAR; SCHED;
;     STG_B(0, 1, t + 2);
;     WAIT_V(6); BAR; MMA8(1, 1, B1); BAR;
;     LDB8(B0, 1, 0); SCHED; LDA8(1, 0); STG_A(0, 1, t + 2);
;     WAIT_L(8); BAR; WAIT_L(0); MMA8(0, 0, B0); BAR; SCHED;
	ds_read_b128 v[158:161], v138 offset:16384
	ds_read_b128 v[162:165], v138 offset:17408
	ds_read_b128 v[166:169], v138 offset:18432
	ds_read_b128 v[170:173], v138 offset:19456
	ds_read_b128 v[174:177], v138 offset:20480
	ds_read_b128 v[180:183], v138 offset:21504
	ds_read_b128 v[184:187], v138 offset:22528
	ds_read_b128 v[188:191], v138 offset:23552
	s_add_u32 s20, s24, s4
	s_addc_u32 s21, s25, s5
	s_add_u32 s20, s20, 0x100
	s_addc_u32 s21, s21, 0
	s_add_i32 s18, s11, 0x10000
	s_mov_b32 m0, s18
	s_nop 0
	global_load_lds_dwordx4 v140, s[20:21]
	s_add_i32 s18, s11, 0x12000
	s_mov_b32 m0, s18
	s_nop 0
	global_load_lds_dwordx4 v139, s[20:21]
	s_add_u32 s20, s8, s4
	s_addc_u32 s21, s9, s5
	s_add_u32 s20, s20, 0x100
	s_addc_u32 s21, s21, 0
	s_mov_b32 m0, s11
	s_nop 0
	global_load_lds_dwordx4 v140, s[20:21]
	s_add_i32 s18, s11, 0x2000
	s_mov_b32 m0, s18
	s_nop 0
	global_load_lds_dwordx4 v139, s[20:21]
	s_add_u32 s20, s22, s4
	s_addc_u32 s21, s23, s5
	s_add_u32 s20, s20, 0x100
	s_addc_u32 s21, s21, 0
	s_add_i32 s18, s11, 0x14000
	s_mov_b32 m0, s18
	s_nop 0
	global_load_lds_dwordx4 v140, s[20:21]
	s_add_i32 s18, s11, 0x16000
	s_mov_b32 m0, s18
	s_nop 0
	global_load_lds_dwordx4 v139, s[20:21]
	s_waitcnt vmcnt(8) lgkmcnt(0)
	s_barrier
	s_setprio 1
	v_mfma_f32_16x16x32_bf16 v[62:65], v[158:161], v[142:145], 0
	v_mfma_f32_16x16x32_bf16 v[58:61], v[158:161], v[150:153], 0
	v_mfma_f32_16x16x32_bf16 v[54:57], v[166:169], v[142:145], 0
	v_mfma_f32_16x16x32_bf16 v[50:53], v[166:169], v[150:153], 0
	v_mfma_f32_16x16x32_bf16 v[46:49], v[174:177], v[142:145], 0
	v_mfma_f32_16x16x32_bf16 v[42:45], v[174:177], v[150:153], 0
	v_mfma_f32_16x16x32_bf16 v[38:41], v[184:187], v[142:145], 0
	v_mfma_f32_16x16x32_bf16 v[34:37], v[184:187], v[150:153], 0
	v_mfma_f32_16x16x32_bf16 v[62:65], v[162:165], v[146:149], v[62:65]
	v_mfma_f32_16x16x32_bf16 v[58:61], v[162:165], v[154:157], v[58:61]
	v_mfma_f32_16x16x32_bf16 v[54:57], v[170:173], v[146:149], v[54:57]
	v_mfma_f32_16x16x32_bf16 v[50:53], v[170:173], v[154:157], v[50:53]
	v_mfma_f32_16x16x32_bf16 v[46:49], v[180:183], v[146:149], v[46:49]
	v_mfma_f32_16x16x32_bf16 v[42:45], v[180:183], v[154:157], v[42:45]
	v_mfma_f32_16x16x32_bf16 v[38:41], v[188:191], v[146:149], v[38:41]
	v_mfma_f32_16x16x32_bf16 v[34:37], v[188:191], v[154:157], v[34:37]
	v_mfma_f32_16x16x32_bf16 v[30:33], v[158:161], v[192:195], 0
	v_mfma_f32_16x16x32_bf16 v[26:29], v[158:161], v[200:203], 0
	v_mfma_f32_16x16x32_bf16 v[22:25], v[166:169], v[192:195], 0
	v_mfma_f32_16x16x32_bf16 v[18:21], v[166:169], v[200:203], 0
	v_mfma_f32_16x16x32_bf16 v[14:17], v[174:177], v[192:195], 0
	v_mfma_f32_16x16x32_bf16 v[10:13], v[174:177], v[200:203], 0
	v_mfma_f32_16x16x32_bf16 v[6:9], v[184:187], v[192:195], 0
	v_mfma_f32_16x16x32_bf16 v[2:5], v[184:187], v[200:203], 0
	v_mfma_f32_16x16x32_bf16 v[30:33], v[162:165], v[196:199], v[30:33]
	v_mfma_f32_16x16x32_bf16 v[26:29], v[162:165], v[204:207], v[26:29]
	v_mfma_f32_16x16x32_bf16 v[22:25], v[170:173], v[196:199], v[22:25]
	v_mfma_f32_16x16x32_bf16 v[18:21], v[170:173], v[204:207], v[18:21]
	v_mfma_f32_16x16x32_bf16 v[14:17], v[180:183], v[196:199], v[14:17]
	v_mfma_f32_16x16x32_bf16 v[10:13], v[180:183], v[204:207], v[10:13]
	v_mfma_f32_16x16x32_bf16 v[6:9], v[188:191], v[196:199], v[6:9]
	v_mfma_f32_16x16x32_bf16 v[2:5], v[188:191], v[204:207], v[2:5]
	s_setprio 0
	s_barrier
	v_add_u32_e32 v154, 0x18000, v141
	ds_read_b128 v[142:145], v154
	ds_read_b128 v[146:149], v154 offset:1024
	ds_read_b128 v[150:153], v154 offset:2048
	ds_read_b128 v[154:157], v154 offset:3072
	ds_read_b128 v[158:161], v138 offset:32768
	ds_read_b128 v[162:165], v138 offset:33792
	ds_read_b128 v[166:169], v138 offset:34816
	ds_read_b128 v[170:173], v138 offset:35840
	ds_read_b128 v[174:177], v138 offset:36864
	ds_read_b128 v[180:183], v138 offset:37888
	ds_read_b128 v[184:187], v138 offset:38912
	ds_read_b128 v[188:191], v138 offset:39936
	v_add_u32_e32 v204, 0x1c000, v141
	ds_read_b128 v[192:195], v204
	ds_read_b128 v[196:199], v204 offset:1024
	ds_read_b128 v[200:203], v204 offset:2048
	ds_read_b128 v[204:207], v204 offset:3072
	s_add_u32 s20, s15, s4
	s_addc_u32 s21, s16, s5
	s_add_u32 s20, s20, 0x100
	s_addc_u32 s21, s21, 0
	s_add_i32 s18, s11, 0x4000
	s_mov_b32 m0, s18
	s_nop 0
	global_load_lds_dwordx4 v140, s[20:21]
	s_add_i32 s18, s11, 0x6000
	s_mov_b32 m0, s18
	s_nop 0
	global_load_lds_dwordx4 v139, s[20:21]
	s_waitcnt vmcnt(8) lgkmcnt(0)
	s_barrier
; #define WAIT_V(n) asm volatile("s_waitcnt vmcnt(" #n ")" ::: "memory")
; #define WAIT_L(n) asm volatile("s_waitcnt lgkmcnt(" #n ")" ::: "memory")
; #define BAR __builtin_amdgcn_s_barrier()
; #define SCHED __builtin_amdgcn_sched_barrier(0)
; #define STG_A(b, h, kt) stage_half_s(lds0 + ((b) * 2 + (h)) * HT_B, ((h) ? A1 : Ap) + (kt) * BK, off0, off1)
; #define STG_B(b, h, kt) stage_half_s(lds0 + (4 + (b) * 2 + (h)) * HT_B, ((h) ? B1p : Bp) + (kt) * BK, off0, off1)
; #define STG_A(b, h, kt) stage_half_s(lds0 + ((b) * 2 + (h)) * HT_B, ((h) ? A1 : Ap) + (kt) * BK, off0, off1)
; #define STG_B(b, h, kt) stage_half_s(lds0 + (4 + (b) * 2 + (h)) * HT_B, ((h) ? B1p : Bp) + (kt) * BK, off0, off1)
; #define LDA8(b, h) _Pragma("unroll") for (int m = 0; m < 4; ++m) _Pragma("unroll") for (int k = 0; k < 2; ++k) \
;     At[m][k] = *(const bf16x8*)(SA_(shm, b, h) + abase + (m * 2 + k) * 1024)
; #define LDB8(dst, b, h) _Pragma("unroll") for (int n = 0; n < 2; ++n) _Pragma("unroll") for (int k = 0; k < 2; ++k) \
;     dst[n][k] = *(const bf16x8*)(SB_(shm, b, h) + bbase + (n * 2 + k) * 1024)
; #define MMA8(ai, bj, Bx) do { __builtin_amdgcn_s_setprio(1); \
;     _Pragma("unroll") for (int m = 0; m < 4; ++m) _Pragma("unroll") for (int n = 0; n < 2; ++n) _Pragma("unroll") for (int k = 0; k < 2; ++k) \
;       acc[ai][bj][m][n] = __builtin_amdgcn_mfma_f32_16x16x32_bf16(At[m][k], Bx[n][k], acc[ai][bj][m][n], 0, 0, 0); \
;     __builtin_amdgcn_s_setprio(0); } while (0)
; template <bool HS>
; __device__ __forceinline__ void gemm_tile8(const u16* __restrict__ Ap, const u16* __restrict__ Bp, int K,
;                                            f32x4 (&acc)[2][2][4][2], char* shm, const int tid, const float* hsr = nullptr) {
;     ...
;     WAIT_L(8); BAR; WAIT_L(0); MMA8(0, 0, B0); BAR; SCHED;
;     LDB8(B1, 1, 1); STG_B(1, 0, t + 3);
;     BAR; WAIT_L(0); MMA8(0, 1, B1); BAR;
;     LDA8(1, 1); STG_A(1, 0, t + 3);
;     BAR; WAIT_L(0); MMA8(1, 0, B0); BAR; SCHED;
;     STG_B(1, 1, t + 3);
;     WAIT_V(6); BAR; MMA8(1, 1, B1); BAR;
;   }
	s_setprio 1
	v_mfma_f32_16x16x32_bf16 v[126:129], v[158:161], v[142:145], v[126:129]
	v_mfma_f32_16x16x32_bf16 v[122:125], v[158:161], v[150:153], v[122:125]
	v_mfma_f32_16x16x32_bf16 v[118:121], v[166:169], v[142:145], v[118:121]
	v_mfma_f32_16x16x32_bf16 v[114:117], v[166:169], v[150:153], v[114:117]
	v_mfma_f32_16x16x32_bf16 v[110:113], v[174:177], v[142:145], v[110:113]
	v_mfma_f32_16x16x32_bf16 v[106:109], v[174:177], v[150:153], v[106:109]
	v_mfma_f32_16x16x32_bf16 v[102:105], v[184:187], v[142:145], v[102:105]
	v_mfma_f32_16x16x32_bf16 v[98:101], v[184:187], v[150:153], v[98:101]
	v_mfma_f32_16x16x32_bf16 v[126:129], v[162:165], v[146:149], v[126:129]
	v_mfma_f32_16x16x32_bf16 v[122:125], v[162:165], v[154:157], v[122:125]
	v_mfma_f32_16x16x32_bf16 v[118:121], v[170:173], v[146:149], v[118:121]
	v_mfma_f32_16x16x32_bf16 v[114:117], v[170:173], v[154:157], v[114:117]
	v_mfma_f32_16x16x32_bf16 v[110:113], v[180:183], v[146:149], v[110:113]
	v_mfma_f32_16x16x32_bf16 v[106:109], v[180:183], v[154:157], v[106:109]
	v_mfma_f32_16x16x32_bf16 v[102:105], v[188:191], v[146:149], v[102:105]
	v_mfma_f32_16x16x32_bf16 v[98:101], v[188:191], v[154:157], v[98:101]
	v_mfma_f32_16x16x32_bf16 v[94:97], v[158:161], v[192:195], v[94:97]
	v_mfma_f32_16x16x32_bf16 v[90:93], v[158:161], v[200:203], v[90:93]
	v_mfma_f32_16x16x32_bf16 v[86:89], v[166:169], v[192:195], v[86:89]
	v_mfma_f32_16x16x32_bf16 v[82:85], v[166:169], v[200:203], v[82:85]
	v_mfma_f32_16x16x32_bf16 v[78:81], v[174:177], v[192:195], v[78:81]
	v_mfma_f32_16x16x32_bf16 v[74:77], v[174:177], v[200:203], v[74:77]
	v_mfma_f32_16x16x32_bf16 v[70:73], v[184:187], v[192:195], v[70:73]
	v_mfma_f32_16x16x32_bf16 v[66:69], v[184:187], v[200:203], v[66:69]
	v_mfma_f32_16x16x32_bf16 v[94:97], v[162:165], v[196:199], v[94:97]
	v_mfma_f32_16x16x32_bf16 v[90:93], v[162:165], v[204:207], v[90:93]
	v_mfma_f32_16x16x32_bf16 v[86:89], v[170:173], v[196:199], v[86:89]
	v_mfma_f32_16x16x32_bf16 v[82:85], v[170:173], v[204:207], v[82:85]
	v_mfma_f32_16x16x32_bf16 v[78:81], v[180:183], v[196:199], v[78:81]
	v_mfma_f32_16x16x32_bf16 v[74:77], v[180:183], v[204:207], v[74:77]
	v_mfma_f32_16x16x32_bf16 v[70:73], v[188:191], v[196:199], v[70:73]
	v_mfma_f32_16x16x32_bf16 v[66:69], v[188:191], v[204:207], v[66:69]
	s_setprio 0
	s_barrier
	ds_read_b128 v[158:161], v138 offset:49152
	ds_read_b128 v[162:165], v138 offset:50176
	ds_read_b128 v[166:169], v138 offset:51200
	ds_read_b128 v[170:173], v138 offset:52224
	ds_read_b128 v[174:177], v138 offset:53248
	ds_read_b128 v[180:183], v138 offset:54272
	ds_read_b128 v[184:187], v138 offset:55296
	ds_read_b128 v[188:191], v138 offset:56320
	s_add_u32 s20, s24, s4
	s_addc_u32 s21, s25, s5
	s_add_u32 s20, s20, 0x180
	s_addc_u32 s21, s21, 0
	s_add_i32 s18, s11, 0x18000
	s_mov_b32 m0, s18
	s_nop 0
	global_load_lds_dwordx4 v140, s[20:21]
	s_add_i32 s18, s11, 0x1a000
	s_mov_b32 m0, s18
	s_nop 0
	global_load_lds_dwordx4 v139, s[20:21]
	s_add_u32 s20, s8, s4
	s_addc_u32 s21, s9, s5
	s_add_u32 s20, s20, 0x180
	s_addc_u32 s21, s21, 0
	s_add_i32 s18, s11, 0x8000
	s_mov_b32 m0, s18
	s_nop 0
	global_load_lds_dwordx4 v140, s[20:21]
	s_add_i32 s18, s11, 0xa000
	s_mov_b32 m0, s18
	s_nop 0
	global_load_lds_dwordx4 v139, s[20:21]
	s_add_u32 s20, s22, s4
	s_addc_u32 s21, s23, s5
	s_add_u32 s20, s20, 0x180
	s_addc_u32 s21, s21, 0
	s_add_i32 s18, s11, 0x1c000
	s_mov_b32 m0, s18
	s_nop 0
	global_load_lds_dwordx4 v140, s[20:21]
	s_add_i32 s18, s11, 0x1e000
	s_mov_b32 m0, s18
	s_nop 0
	global_load_lds_dwordx4 v139, s[20:21]
	s_waitcnt vmcnt(8) lgkmcnt(0)
	s_barrier
	s_setprio 1
	v_mfma_f32_16x16x32_bf16 v[62:65], v[158:161], v[142:145], v[62:65]
	v_mfma_f32_16x16x32_bf16 v[58:61], v[158:161], v[150:153], v[58:61]
	v_mfma_f32_16x16x32_bf16 v[54:57], v[166:169], v[142:145], v[54:57]
	v_mfma_f32_16x16x32_bf16 v[50:53], v[166:169], v[150:153], v[50:53]
	v_mfma_f32_16x16x32_bf16 v[46:49], v[174:177], v[142:145], v[46:49]
	v_mfma_f32_16x16x32_bf16 v[42:45], v[174:177], v[150:153], v[42:45]
	v_mfma_f32_16x16x32_bf16 v[38:41], v[184:187], v[142:145], v[38:41]
	v_mfma_f32_16x16x32_bf16 v[34:37], v[184:187], v[150:153], v[34:37]
	v_mfma_f32_16x16x32_bf16 v[62:65], v[162:165], v[146:149], v[62:65]
	v_mfma_f32_16x16x32_bf16 v[58:61], v[162:165], v[154:157], v[58:61]
	v_mfma_f32_16x16x32_bf16 v[54:57], v[170:173], v[146:149], v[54:57]
	v_mfma_f32_16x16x32_bf16 v[50:53], v[170:173], v[154:157], v[50:53]
	v_mfma_f32_16x16x32_bf16 v[46:49], v[180:183], v[146:149], v[46:49]
	v_mfma_f32_16x16x32_bf16 v[42:45], v[180:183], v[154:157], v[42:45]
	v_mfma_f32_16x16x32_bf16 v[38:41], v[188:191], v[146:149], v[38:41]
	v_mfma_f32_16x16x32_bf16 v[34:37], v[188:191], v[154:157], v[34:37]
	v_mfma_f32_16x16x32_bf16 v[30:33], v[158:161], v[192:195], v[30:33]
	v_mfma_f32_16x16x32_bf16 v[26:29], v[158:161], v[200:203], v[26:29]
	v_mfma_f32_16x16x32_bf16 v[22:25], v[166:169], v[192:195], v[22:25]
	v_mfma_f32_16x16x32_bf16 v[18:21], v[166:169], v[200:203], v[18:21]
	v_mfma_f32_16x16x32_bf16 v[14:17], v[174:177], v[192:195], v[14:17]
	v_mfma_f32_16x16x32_bf16 v[10:13], v[174:177], v[200:203], v[10:13]
	v_mfma_f32_16x16x32_bf16 v[6:9], v[184:187], v[192:195], v[6:9]
	v_mfma_f32_16x16x32_bf16 v[2:5], v[184:187], v[200:203], v[2:5]
	v_mfma_f32_16x16x32_bf16 v[30:33], v[162:165], v[196:199], v[30:33]
	v_mfma_f32_16x16x32_bf16 v[26:29], v[162:165], v[204:207], v[26:29]
	v_mfma_f32_16x16x32_bf16 v[22:25], v[170:173], v[196:199], v[22:25]
	v_mfma_f32_16x16x32_bf16 v[18:21], v[170:173], v[204:207], v[18:21]
	v_mfma_f32_16x16x32_bf16 v[14:17], v[180:183], v[196:199], v[14:17]
	v_mfma_f32_16x16x32_bf16 v[10:13], v[180:183], v[204:207], v[10:13]
	v_mfma_f32_16x16x32_bf16 v[6:9], v[188:191], v[196:199], v[6:9]
	v_mfma_f32_16x16x32_bf16 v[2:5], v[188:191], v[204:207], v[2:5]
	s_setprio 0
	s_add_i32 s17, s17, 2
	s_add_u32 s4, s4, 0x100
	s_addc_u32 s5, s5, 0
	s_cmp_lt_u32 s17, 12
	s_barrier
	s_cbranch_scc0 .Lk_conv_in_exit

; #define WAIT_V(n) asm volatile("s_waitcnt vmcnt(" #n ")" ::: "memory")
; #define WAIT_L(n) asm volatile("s_waitcnt lgkmcnt(" #n ")" ::: "memory")
; #define BAR __builtin_amdgcn_s_barrier()
; #define STG_A(b, h, kt) stage_half_s(lds0 + ((b) * 2 + (h)) * HT_B, ((h) ? A1 : Ap) + (kt) * BK, off0, off1)
; #define STG_A(b, h, kt) stage_half_s(lds0 + ((b) * 2 + (h)) * HT_B, ((h) ? A1 : Ap) + (kt) * BK, off0, off1)
; #define LDA8(b, h) _Pragma("unroll") for (int m = 0; m < 4; ++m) _Pragma("unroll") for (int k = 0; k < 2; ++k) \
;     At[m][k] = *(const bf16x8*)(SA_(shm, b, h) + abase + (m * 2 + k) * 1024)
; #define LDB8(dst, b, h) _Pragma("unroll") for (int n = 0; n < 2; ++n) _Pragma("unroll") for (int k = 0; k < 2; ++k) \
;     dst[n][k] = *(const bf16x8*)(SB_(shm, b, h) + bbase + (n * 2 + k) * 1024)
; #define MMA8(ai, bj, Bx) do { __builtin_amdgcn_s_setprio(1); \
;     _Pragma("unroll") for (int m = 0; m < 4; ++m) _Pragma("unroll") for (int n = 0; n < 2; ++n) _Pragma("unroll") for (int k = 0; k < 2; ++k) \
;       acc[ai][bj][m][n] = __builtin_amdgcn_mfma_f32_16x16x32_bf16(At[m][k], Bx[n][k], acc[ai][bj][m][n], 0, 0, 0); \
;     __builtin_amdgcn_s_setprio(0); } while (0)
; template <bool HS>
; __device__ __forceinline__ void gemm_tile8(const u16* __restrict__ Ap, const u16* __restrict__ Bp, int K,
;                                            f32x4 (&acc)[2][2][4][2], char* shm, const int tid, const float* hsr = nullptr) {
;     ...
;   { LDB8(B0, 0, 0); LDA8(0, 0); STG_A(1, 1, nt - 1);
;     BAR; WAIT_L(0); MMA8(0, 0, B0); BAR;
;     LDB8(B1, 0, 1); BAR; WAIT_L(0); MMA8(0, 1, B1); BAR;
;     LDA8(0, 1); WAIT_V(4); BAR; WAIT_L(0); MMA8(1, 0, B0); MMA8(1, 1, B1); BAR; }
;   { LDB8(B0, 1, 0); LDA8(1, 0); WAIT_V(2); BAR; WAIT_L(0); MMA8(0, 0, B0); BAR;
;     LDB8(B1, 1, 1); WAIT_V(0); BAR; WAIT_L(0); MMA8(0, 1, B1); BAR;
.Lk_conv_in_exit:
	s_waitcnt vmcnt(6)
	s_add_i32 s18, s11, 0xc000
	s_add_i32 s19, s11, 0xe000
	v_add_u32_e32 v220, 0, v141
	v_add_u32_e32 v141, 0x10000, v220
	ds_read_b128 v[130:133], v141
	ds_read_b128 v[142:145], v141 offset:1024
	ds_read_b128 v[146:149], v141 offset:2048
	ds_read_b128 v[150:153], v141 offset:3072
	ds_read_b128 v[154:157], v138
	ds_read_b128 v[158:161], v138 offset:1024
	ds_read_b128 v[162:165], v138 offset:2048
	ds_read_b128 v[166:169], v138 offset:3072
	ds_read_b128 v[170:173], v138 offset:4096
	ds_read_b128 v[174:177], v138 offset:5120
	ds_read_b128 v[180:183], v138 offset:6144
	ds_read_b128 v[184:187], v138 offset:7168
	s_add_u32 s4, s8, 0x40780
	s_addc_u32 s5, s9, 0
	s_mov_b32 m0, s18
	s_nop 0
	global_load_lds_dwordx4 v140, s[4:5]
	s_nop 0
	s_mov_b32 m0, s19
	s_nop 0
	global_load_lds_dwordx4 v139, s[4:5]
	s_barrier
	s_waitcnt lgkmcnt(0)
	s_setprio 1
	s_waitcnt lgkmcnt(7)
	v_mfma_f32_16x16x32_bf16 v[126:129], v[154:157], v[130:133], v[126:129]
	v_mfma_f32_16x16x32_bf16 v[122:125], v[154:157], v[146:149], v[122:125]
	s_waitcnt lgkmcnt(3)
	v_mfma_f32_16x16x32_bf16 v[110:113], v[170:173], v[130:133], v[110:113]
	v_mfma_f32_16x16x32_bf16 v[106:109], v[170:173], v[146:149], v[106:109]
	v_mfma_f32_16x16x32_bf16 v[126:129], v[158:161], v[142:145], v[126:129]
	v_mfma_f32_16x16x32_bf16 v[122:125], v[158:161], v[150:153], v[122:125]
	v_mfma_f32_16x16x32_bf16 v[118:121], v[162:165], v[130:133], v[118:121]
	v_mfma_f32_16x16x32_bf16 v[114:117], v[162:165], v[146:149], v[114:117]
	s_waitcnt lgkmcnt(2)
	v_mfma_f32_16x16x32_bf16 v[110:113], v[174:177], v[142:145], v[110:113]
	v_mfma_f32_16x16x32_bf16 v[106:109], v[174:177], v[150:153], v[106:109]
	s_waitcnt lgkmcnt(1)
	v_mfma_f32_16x16x32_bf16 v[102:105], v[180:183], v[130:133], v[102:105]
	v_mfma_f32_16x16x32_bf16 v[98:101], v[180:183], v[146:149], v[98:101]
	v_mfma_f32_16x16x32_bf16 v[188:191], v[166:169], v[142:145], v[118:121]
	v_mfma_f32_16x16x32_bf16 v[192:195], v[166:169], v[150:153], v[114:117]
	s_waitcnt lgkmcnt(0)
	v_mfma_f32_16x16x32_bf16 v[196:199], v[184:187], v[142:145], v[102:105]
	v_mfma_f32_16x16x32_bf16 v[200:203], v[184:187], v[150:153], v[98:101]
	s_setprio 0
	v_add_u32_e32 v118, 0x14000, v220
	s_barrier
	ds_read_b128 v[98:101], v118
	ds_read_b128 v[102:105], v118 offset:1024
	ds_read_b128 v[114:117], v118 offset:2048
	ds_read_b128 v[118:121], v118 offset:3072
	s_barrier
	s_waitcnt lgkmcnt(0)
	s_setprio 1
	s_waitcnt lgkmcnt(3)
	v_mfma_f32_16x16x32_bf16 v[94:97], v[154:157], v[98:101], v[94:97]
	s_waitcnt lgkmcnt(1)
	v_mfma_f32_16x16x32_bf16 v[90:93], v[154:157], v[114:117], v[90:93]
	v_mfma_f32_16x16x32_bf16 v[78:81], v[170:173], v[98:101], v[78:81]
	v_mfma_f32_16x16x32_bf16 v[74:77], v[170:173], v[114:117], v[74:77]
	v_mfma_f32_16x16x32_bf16 v[94:97], v[158:161], v[102:105], v[94:97]
	s_waitcnt lgkmcnt(0)
	v_mfma_f32_16x16x32_bf16 v[90:93], v[158:161], v[118:121], v[90:93]
	v_mfma_f32_16x16x32_bf16 v[86:89], v[162:165], v[98:101], v[86:89]
	v_mfma_f32_16x16x32_bf16 v[82:85], v[162:165], v[114:117], v[82:85]
	v_mfma_f32_16x16x32_bf16 v[78:81], v[174:177], v[102:105], v[78:81]
	v_mfma_f32_16x16x32_bf16 v[74:77], v[174:177], v[118:121], v[74:77]
	v_mfma_f32_16x16x32_bf16 v[70:73], v[180:183], v[98:101], v[70:73]
	v_mfma_f32_16x16x32_bf16 v[66:69], v[180:183], v[114:117], v[66:69]
	v_mfma_f32_16x16x32_bf16 v[154:157], v[166:169], v[102:105], v[86:89]
	v_mfma_f32_16x16x32_bf16 v[158:161], v[166:169], v[118:121], v[82:85]
	v_mfma_f32_16x16x32_bf16 v[162:165], v[184:187], v[102:105], v[70:73]
	v_mfma_f32_16x16x32_bf16 v[166:169], v[184:187], v[118:121], v[66:69]
	s_setprio 0
	s_barrier
	s_nop 1
	ds_read_b128 v[66:69], v138 offset:16384
	ds_read_b128 v[70:73], v138 offset:17408
	ds_read_b128 v[82:85], v138 offset:18432
	ds_read_b128 v[86:89], v138 offset:19456
	ds_read_b128 v[170:173], v138 offset:20480
	ds_read_b128 v[174:177], v138 offset:21504
	ds_read_b128 v[180:183], v138 offset:22528
	ds_read_b128 v[184:187], v138 offset:23552
	s_waitcnt vmcnt(4)
	s_barrier
	s_waitcnt lgkmcnt(0)
	s_setprio 1
	s_waitcnt lgkmcnt(7)
	v_mfma_f32_16x16x32_bf16 v[62:65], v[66:69], v[130:133], v[62:65]
	s_waitcnt lgkmcnt(5)
	v_mfma_f32_16x16x32_bf16 v[54:57], v[82:85], v[130:133], v[54:57]
	s_waitcnt lgkmcnt(3)
	v_mfma_f32_16x16x32_bf16 v[46:49], v[170:173], v[130:133], v[46:49]
	s_waitcnt lgkmcnt(1)
	v_mfma_f32_16x16x32_bf16 v[38:41], v[180:183], v[130:133], v[38:41]
	v_mfma_f32_16x16x32_bf16 v[62:65], v[70:73], v[142:145], v[62:65]
	v_mfma_f32_16x16x32_bf16 v[58:61], v[66:69], v[146:149], v[58:61]
	v_mfma_f32_16x16x32_bf16 v[54:57], v[86:89], v[142:145], v[54:57]
	v_mfma_f32_16x16x32_bf16 v[50:53], v[82:85], v[146:149], v[50:53]
	v_mfma_f32_16x16x32_bf16 v[46:49], v[174:177], v[142:145], v[46:49]
	v_mfma_f32_16x16x32_bf16 v[42:45], v[170:173], v[146:149], v[42:45]
	s_waitcnt lgkmcnt(0)
	v_mfma_f32_16x16x32_bf16 v[38:41], v[184:187], v[142:145], v[38:41]
	v_mfma_f32_16x16x32_bf16 v[34:37], v[180:183], v[146:149], v[34:37]
	v_mfma_f32_16x16x32_bf16 v[204:207], v[70:73], v[150:153], v[58:61]
	v_mfma_f32_16x16x32_bf16 v[208:211], v[86:89], v[150:153], v[50:53]
	v_mfma_f32_16x16x32_bf16 v[212:215], v[174:177], v[150:153], v[42:45]
	v_mfma_f32_16x16x32_bf16 v[130:133], v[184:187], v[150:153], v[34:37]
	s_setprio 0
	s_setprio 1
	v_mfma_f32_16x16x32_bf16 v[30:33], v[66:69], v[98:101], v[30:33]
	v_mfma_f32_16x16x32_bf16 v[22:25], v[82:85], v[98:101], v[22:25]
	v_mfma_f32_16x16x32_bf16 v[14:17], v[170:173], v[98:101], v[14:17]
	v_mfma_f32_16x16x32_bf16 v[6:9], v[180:183], v[98:101], v[6:9]
	v_mfma_f32_16x16x32_bf16 v[30:33], v[70:73], v[102:105], v[30:33]
	v_mfma_f32_16x16x32_bf16 v[26:29], v[66:69], v[114:117], v[26:29]
	v_mfma_f32_16x16x32_bf16 v[22:25], v[86:89], v[102:105], v[22:25]
	v_mfma_f32_16x16x32_bf16 v[18:21], v[82:85], v[114:117], v[18:21]
	v_mfma_f32_16x16x32_bf16 v[14:17], v[174:177], v[102:105], v[14:17]
	v_mfma_f32_16x16x32_bf16 v[10:13], v[170:173], v[114:117], v[10:13]
	v_mfma_f32_16x16x32_bf16 v[6:9], v[184:187], v[102:105], v[6:9]
	v_mfma_f32_16x16x32_bf16 v[2:5], v[180:183], v[114:117], v[2:5]
	v_mfma_f32_16x16x32_bf16 v[140:143], v[70:73], v[118:121], v[26:29]
	v_mfma_f32_16x16x32_bf16 v[144:147], v[86:89], v[118:121], v[18:21]
	v_mfma_f32_16x16x32_bf16 v[148:151], v[174:177], v[118:121], v[10:13]
	v_mfma_f32_16x16x32_bf16 v[170:173], v[184:187], v[118:121], v[2:5]
	s_setprio 0
	v_add_u32_e32 v18, 0x18000, v220
	s_barrier
; #define WAIT_V(n) asm volatile("s_waitcnt vmcnt(" #n ")" ::: "memory")
; #define WAIT_L(n) asm volatile("s_waitcnt lgkmcnt(" #n ")" ::: "memory")
; #define BAR __builtin_amdgcn_s_barrier()
; #define LDA8(b, h) _Pragma("unroll") for (int m = 0; m < 4; ++m) _Pragma("unroll") for (int k = 0; k < 2; ++k) \
;     At[m][k] = *(const bf16x8*)(SA_(shm, b, h) + abase + (m * 2 + k) * 1024)
; #define LDB8(dst, b, h) _Pragma("unroll") for (int n = 0; n < 2; ++n) _Pragma("unroll") for (int k = 0; k < 2; ++k) \
;     dst[n][k] = *(const bf16x8*)(SB_(shm, b, h) + bbase + (n * 2 + k) * 1024)
; #define MMA8(ai, bj, Bx) do { __builtin_amdgcn_s_setprio(1); \
;     _Pragma("unroll") for (int m = 0; m < 4; ++m) _Pragma("unroll") for (int n = 0; n < 2; ++n) _Pragma("unroll") for (int k = 0; k < 2; ++k) \
;       acc[ai][bj][m][n] = __builtin_amdgcn_mfma_f32_16x16x32_bf16(At[m][k], Bx[n][k], acc[ai][bj][m][n], 0, 0, 0); \
;     __builtin_amdgcn_s_setprio(0); } while (0)
; template <bool HS>
; __device__ __forceinline__ void gemm_tile8(const u16* __restrict__ Ap, const u16* __restrict__ Bp, int K,
;                                            f32x4 (&acc)[2][2][4][2], char* shm, const int tid, const float* hsr = nullptr) {
;     ...
;     LDA8(0, 1); WAIT_V(4); BAR; WAIT_L(0); MMA8(1, 0, B0); MMA8(1, 1, B1); BAR; }
;   { LDB8(B0, 1, 0); LDA8(1, 0); WAIT_V(2); BAR; WAIT_L(0); MMA8(0, 0, B0); BAR;
;     LDB8(B1, 1, 1); WAIT_V(0); BAR; WAIT_L(0); MMA8(0, 1, B1); BAR;
;     LDA8(1, 1); BAR; WAIT_L(0); MMA8(1, 0, B0); MMA8(1, 1, B1); BAR; }
;   if (wr == 0) BAR;
	s_nop 0
	ds_read_b128 v[2:5], v18
	ds_read_b128 v[10:13], v18 offset:1024
	ds_read_b128 v[174:177], v18 offset:2048
	ds_read_b128 v[180:183], v18 offset:3072
	ds_read_b128 v[18:21], v138 offset:32768
	ds_read_b128 v[26:29], v138 offset:33792
	ds_read_b128 v[34:37], v138 offset:34816
	ds_read_b128 v[42:45], v138 offset:35840
	ds_read_b128 v[50:53], v138 offset:36864
	ds_read_b128 v[58:61], v138 offset:37888
	ds_read_b128 v[184:187], v138 offset:38912
	ds_read_b128 v[216:219], v138 offset:39936
	s_waitcnt vmcnt(2)
	s_barrier
	s_waitcnt lgkmcnt(0)
	s_setprio 1
	s_waitcnt lgkmcnt(7)
	v_mfma_f32_16x16x32_bf16 v[66:69], v[18:21], v[2:5], v[126:129]
	s_waitcnt lgkmcnt(6)
	v_mfma_f32_16x16x32_bf16 v[118:121], v[26:29], v[10:13], v[66:69]
	v_mfma_f32_16x16x32_bf16 v[66:69], v[18:21], v[174:177], v[122:125]
	v_mfma_f32_16x16x32_bf16 v[114:117], v[26:29], v[180:183], v[66:69]
	s_waitcnt lgkmcnt(5)
	v_mfma_f32_16x16x32_bf16 v[66:69], v[34:37], v[2:5], v[188:191]
	s_waitcnt lgkmcnt(4)
	v_mfma_f32_16x16x32_bf16 v[102:105], v[42:45], v[10:13], v[66:69]
	v_mfma_f32_16x16x32_bf16 v[66:69], v[34:37], v[174:177], v[192:195]
	v_mfma_f32_16x16x32_bf16 v[98:101], v[42:45], v[180:183], v[66:69]
	s_waitcnt lgkmcnt(3)
	v_mfma_f32_16x16x32_bf16 v[66:69], v[50:53], v[2:5], v[110:113]
	s_waitcnt lgkmcnt(2)
	v_mfma_f32_16x16x32_bf16 v[86:89], v[58:61], v[10:13], v[66:69]
	v_mfma_f32_16x16x32_bf16 v[66:69], v[50:53], v[174:177], v[106:109]
	v_mfma_f32_16x16x32_bf16 v[82:85], v[58:61], v[180:183], v[66:69]
	s_waitcnt lgkmcnt(1)
	v_mfma_f32_16x16x32_bf16 v[66:69], v[184:187], v[2:5], v[196:199]
	s_waitcnt lgkmcnt(0)
	v_mfma_f32_16x16x32_bf16 v[70:73], v[216:219], v[10:13], v[66:69]
	v_mfma_f32_16x16x32_bf16 v[66:69], v[184:187], v[174:177], v[200:203]
	v_mfma_f32_16x16x32_bf16 v[66:69], v[216:219], v[180:183], v[66:69]
	s_setprio 0
	v_add_u32_e32 v106, 0x1c000, v220
	s_barrier
	ds_read_b128 v[188:191], v106
	ds_read_b128 v[192:195], v106 offset:1024
	ds_read_b128 v[196:199], v106 offset:2048
	ds_read_b128 v[200:203], v106 offset:3072
	s_waitcnt vmcnt(0)
	s_barrier
	s_waitcnt lgkmcnt(0)
	s_setprio 1
	s_waitcnt lgkmcnt(3)
	v_mfma_f32_16x16x32_bf16 v[94:97], v[18:21], v[188:191], v[94:97]
	s_waitcnt lgkmcnt(1)
	v_mfma_f32_16x16x32_bf16 v[18:21], v[18:21], v[196:199], v[90:93]
	s_waitcnt lgkmcnt(0)
	v_mfma_f32_16x16x32_bf16 v[122:125], v[26:29], v[200:203], v[18:21]
	v_mfma_f32_16x16x32_bf16 v[18:21], v[34:37], v[188:191], v[154:157]
	v_mfma_f32_16x16x32_bf16 v[110:113], v[42:45], v[192:195], v[18:21]
	v_mfma_f32_16x16x32_bf16 v[18:21], v[34:37], v[196:199], v[158:161]
	v_mfma_f32_16x16x32_bf16 v[106:109], v[42:45], v[200:203], v[18:21]
	v_mfma_f32_16x16x32_bf16 v[18:21], v[50:53], v[188:191], v[78:81]
	v_mfma_f32_16x16x32_bf16 v[126:129], v[26:29], v[192:195], v[94:97]
	v_mfma_f32_16x16x32_bf16 v[94:97], v[58:61], v[192:195], v[18:21]
	v_mfma_f32_16x16x32_bf16 v[18:21], v[50:53], v[196:199], v[74:77]
	v_mfma_f32_16x16x32_bf16 v[90:93], v[58:61], v[200:203], v[18:21]
	v_mfma_f32_16x16x32_bf16 v[18:21], v[184:187], v[188:191], v[162:165]
	v_mfma_f32_16x16x32_bf16 v[78:81], v[216:219], v[192:195], v[18:21]
	v_mfma_f32_16x16x32_bf16 v[18:21], v[184:187], v[196:199], v[166:169]
	v_mfma_f32_16x16x32_bf16 v[74:77], v[216:219], v[200:203], v[18:21]
	s_setprio 0
	s_barrier
	ds_read_b128 v[152:155], v138 offset:49152
	ds_read_b128 v[156:159], v138 offset:50176
	ds_read_b128 v[160:163], v138 offset:51200
	ds_read_b128 v[164:167], v138 offset:52224
	ds_read_b128 v[184:187], v138 offset:53248
	ds_read_b128 v[216:219], v138 offset:54272
	ds_read_b128 v[220:223], v138 offset:55296
	ds_read_b128 v[224:227], v138 offset:56320
	s_barrier
	s_waitcnt lgkmcnt(0)
	s_setprio 1
	s_waitcnt lgkmcnt(7)
	v_mfma_f32_16x16x32_bf16 v[18:21], v[152:155], v[2:5], v[62:65]
	s_waitcnt lgkmcnt(6)
	v_mfma_f32_16x16x32_bf16 v[58:61], v[156:159], v[10:13], v[18:21]
	v_mfma_f32_16x16x32_bf16 v[18:21], v[152:155], v[174:177], v[204:207]
	v_mfma_f32_16x16x32_bf16 v[50:53], v[156:159], v[180:183], v[18:21]
	s_waitcnt lgkmcnt(5)
	v_mfma_f32_16x16x32_bf16 v[18:21], v[160:163], v[2:5], v[54:57]
	s_waitcnt lgkmcnt(4)
	v_mfma_f32_16x16x32_bf16 v[42:45], v[164:167], v[10:13], v[18:21]
	v_mfma_f32_16x16x32_bf16 v[18:21], v[160:163], v[174:177], v[208:211]
	v_mfma_f32_16x16x32_bf16 v[34:37], v[164:167], v[180:183], v[18:21]
	s_waitcnt lgkmcnt(3)
	v_mfma_f32_16x16x32_bf16 v[18:21], v[184:187], v[2:5], v[46:49]
	s_waitcnt lgkmcnt(1)
	v_mfma_f32_16x16x32_bf16 v[2:5], v[220:223], v[2:5], v[38:41]
	v_mfma_f32_16x16x32_bf16 v[26:29], v[216:219], v[10:13], v[18:21]
	v_mfma_f32_16x16x32_bf16 v[18:21], v[184:187], v[174:177], v[212:215]
	s_waitcnt lgkmcnt(0)
	v_mfma_f32_16x16x32_bf16 v[10:13], v[224:227], v[10:13], v[2:5]
	v_mfma_f32_16x16x32_bf16 v[2:5], v[220:223], v[174:177], v[130:133]
	v_mfma_f32_16x16x32_bf16 v[18:21], v[216:219], v[180:183], v[18:21]
	v_mfma_f32_16x16x32_bf16 v[2:5], v[224:227], v[180:183], v[2:5]
	s_setprio 0
	s_setprio 1
	v_mfma_f32_16x16x32_bf16 v[30:33], v[152:155], v[188:191], v[30:33]
	v_mfma_f32_16x16x32_bf16 v[62:65], v[156:159], v[192:195], v[30:33]
	v_mfma_f32_16x16x32_bf16 v[30:33], v[152:155], v[196:199], v[140:143]
	v_mfma_f32_16x16x32_bf16 v[22:25], v[160:163], v[188:191], v[22:25]
	v_mfma_f32_16x16x32_bf16 v[14:17], v[184:187], v[188:191], v[14:17]
	v_mfma_f32_16x16x32_bf16 v[54:57], v[156:159], v[200:203], v[30:33]
	v_mfma_f32_16x16x32_bf16 v[46:49], v[164:167], v[192:195], v[22:25]
	v_mfma_f32_16x16x32_bf16 v[22:25], v[160:163], v[196:199], v[144:147]
	v_mfma_f32_16x16x32_bf16 v[30:33], v[216:219], v[192:195], v[14:17]
	v_mfma_f32_16x16x32_bf16 v[14:17], v[184:187], v[196:199], v[148:151]
	v_mfma_f32_16x16x32_bf16 v[6:9], v[220:223], v[188:191], v[6:9]
	v_mfma_f32_16x16x32_bf16 v[38:41], v[164:167], v[200:203], v[22:25]
	v_mfma_f32_16x16x32_bf16 v[22:25], v[216:219], v[200:203], v[14:17]
	v_mfma_f32_16x16x32_bf16 v[14:17], v[224:227], v[192:195], v[6:9]
	v_mfma_f32_16x16x32_bf16 v[6:9], v[220:223], v[196:199], v[170:173]
	v_mfma_f32_16x16x32_bf16 v[6:9], v[224:227], v[200:203], v[6:9]
	s_setprio 0
	s_movk_i32 s4, 0x100
	v_cmp_gt_u32_e32 vcc, s4, v0
	s_barrier
	s_and_saveexec_b64 s[4:5], vcc
	s_cbranch_execz .LBB0_321
	s_barrier

; #define WAIT_V(n) asm volatile("s_waitcnt vmcnt(" #n ")" ::: "memory")
; #define WAIT_L(n) asm volatile("s_waitcnt lgkmcnt(" #n ")" ::: "memory")
; #define BAR __builtin_amdgcn_s_barrier()
; #define SCHED __builtin_amdgcn_sched_barrier(0)
; #define STG_A(b, h, kt) stage_half_s(lds0 + ((b) * 2 + (h)) * HT_B, ((h) ? A1 : Ap) + (kt) * BK, off0, off1)
; #define STG_B(b, h, kt) stage_half_s(lds0 + (4 + (b) * 2 + (h)) * HT_B, ((h) ? B1p : Bp) + (kt) * BK, off0, off1)
; #define STG_A(b, h, kt) stage_half_s(lds0 + ((b) * 2 + (h)) * HT_B, ((h) ? A1 : Ap) + (kt) * BK, off0, off1)
; #define STG_B(b, h, kt) stage_half_s(lds0 + (4 + (b) * 2 + (h)) * HT_B, ((h) ? B1p : Bp) + (kt) * BK, off0, off1)
; #define LDA8(b, h) _Pragma("unroll") for (int m = 0; m < 4; ++m) _Pragma("unroll") for (int k = 0; k < 2; ++k) \
;     At[m][k] = *(const bf16x8*)(SA_(shm, b, h) + abase + (m * 2 + k) * 1024)
; template <bool HS>
; __device__ __forceinline__ void gemm_tile8(const u16* __restrict__ Ap, const u16* __restrict__ Bp, int K,
;                                            f32x4 (&acc)[2][2][4][2], char* shm, const int tid, const float* hsr = nullptr) {
;   const int wid = tid >> 6, lane = tid & 63, wr = wid >> 2, wc = wid & 3, fr = lane & 15, fq = lane >> 4;
;   int r0, c0, r1, c1;
;   stage_rc(tid * 16, r0, c0);
;   stage_rc(tid * 16 + 8192, r1, c1);
;   const unsigned off0 = (unsigned)(r0 * K + c0) * 2u, off1 = (unsigned)(r1 * K + c1) * 2u;
;   const int wvoff = __builtin_amdgcn_readfirstlane(tid >> 6) * 1024;
;   const u16* A1 = Ap + (size_t)128 * K;
;   const u16* B1p = Bp + (size_t)128 * K;
; #pragma unroll
;   for (int a = 0; a < 2; ++a)
; #pragma unroll
;     for (int b = 0; b < 2; ++b)
; #pragma unroll
;       for (int m = 0; m < 4; ++m)
; #pragma unroll
;         for (int n = 0; n < 2; ++n) acc[a][b][m][n] = f32x4{0.f, 0.f, 0.f, 0.f};
;   const int abase = lds_byte(wr * 64 + fr, fq * 8), bbase = lds_byte(wc * 32 + fr, fq * 8);
;   bf16x8 At[4][2], B0[2][2], B1[2][2];
;   const unsigned lds0 = (unsigned)(size_t)(__attribute__((address_space(3))) char*)shm + (unsigned)wvoff;
;     ...
;   const int nt = K / BK;
;   WAIT_V(0);
;   if (wr == 1) BAR;
;   BAR;
;   BAR;
;     ...
;     LDB8(B0, 0, 0); SCHED; LDA8(0, 0); STG_A(1, 1, t + 1);
;     WAIT_L(8); BAR; WAIT_L(0); MMA8(0, 0, B0); BAR; SCHED;
;     LDB8(B1, 0, 1); STG_B(0, 0, t + 2);
;     BAR; WAIT_L(0); MMA8(0, 1, B1); BAR;
.LBB0_582:
	s_or_b64 exec, exec, s[8:9]
	v_bfe_i32 v6, v0, 27, 1
	v_lshlrev_b32_e32 v4, 4, v0
	v_lshrrev_b32_e32 v6, 22, v6
	v_add_u32_e32 v6, v4, v6
	v_and_b32_e32 v6, 0xfffffc00, v6
	v_ashrrev_i32_e32 v5, 31, v0
	v_sub_u32_e32 v6, v4, v6
	v_lshrrev_b32_e32 v5, 26, v5
	v_lshrrev_b32_e32 v7, 4, v6
	v_add_u32_e32 v5, v0, v5
	v_bitop3_b32 v7, v7, v6, 32 bitop3:0x6c
	v_ashrrev_i32_e32 v6, 31, v6
	v_ashrrev_i32_e32 v5, 6, v5
	v_lshrrev_b32_e32 v6, 26, v6
	v_lshlrev_b32_e32 v8, 3, v5
	v_add_u32_e32 v6, v7, v6
	v_and_b32_e32 v8, 0x1ffff0, v8
	v_ashrrev_i32_e32 v6, 6, v6
	v_add_u32_e32 v8, v6, v8
	v_mul_i32_i24_e32 v6, 64, v6
	v_add_u32_e32 v4, 0x2000, v4
	v_sub_u32_e32 v6, v7, v6
	v_ashrrev_i32_e32 v7, 31, v4
	v_lshrrev_b32_e32 v7, 22, v7
	v_add_u32_e32 v7, v4, v7
	v_ashrrev_i32_e32 v7, 10, v7
	v_mul_i32_i24_e32 v9, 0x400, v7
	v_sub_u32_e32 v4, v4, v9
	v_lshrrev_b32_e32 v9, 4, v4
	v_bitop3_b32 v4, v9, v4, 32 bitop3:0x6c
	s_ashr_i32 s7, s6, 31
	v_ashrrev_i32_e32 v10, 31, v4
	s_lshl_b64 s[6:7], s[6:7], 11
	v_readlane_b32 s20, v254, 47
	v_lshrrev_b32_e32 v10, 26, v10
	v_readlane_b32 s21, v254, 48
	s_add_u32 s8, s20, s6
	v_add_u32_e32 v10, v4, v10
	s_addc_u32 s9, s21, s7
	s_ashr_i32 s3, s2, 31
	v_lshlrev_b32_e32 v9, 3, v7
	v_lshrrev_b32_e32 v11, 6, v10
	v_and_b32_e32 v10, 0xc0, v10
	s_lshl_b64 s[6:7], s[2:3], 19
	v_readlane_b32 s3, v255, 7
	v_and_b32_e32 v9, 0x1ffff0, v9
	v_lshlrev_b32_e32 v7, 5, v7
	v_sub_u32_e32 v4, v4, v10
	s_add_u32 s3, s3, s6
	v_readlane_b32 s6, v255, 8
	v_lshlrev_b32_e32 v5, 5, v5
	v_add_u32_e32 v9, v11, v9
	v_and_b32_e32 v7, 32, v7
	v_ashrrev_i16_sdwa v4, v178, sext(v4) dst_sel:DWORD dst_unused:UNUSED_PAD src0_sel:DWORD src1_sel:BYTE_0
	s_addc_u32 s10, s6, s7
	v_and_b32_e32 v5, 32, v5
	v_ashrrev_i16_sdwa v6, v178, sext(v6) dst_sel:DWORD dst_unused:UNUSED_PAD src0_sel:DWORD src1_sel:BYTE_0
	v_bfe_i32 v4, v4, 0, 16
	v_lshl_or_b32 v7, v9, 10, v7
	s_lshl_b32 s11, s11, 10
	v_bfe_i32 v6, v6, 0, 16
	v_lshl_or_b32 v5, v8, 10, v5
	v_and_b32_e32 v8, 15, v0
	v_add_lshl_u32 v131, v7, v4, 1
	s_add_u32 s13, s3, 0x40000
	v_lshlrev_b32_e32 v7, 2, v0
	v_add_lshl_u32 v132, v5, v6, 1
	s_addc_u32 s14, s10, 0
	v_and_b32_e32 v4, 48, v0
	v_lshlrev_b32_e32 v5, 6, v8
	v_and_b32_e32 v7, 32, v7
	s_add_i32 s15, s11, 0
	v_or_b32_e32 v6, v5, v4
	v_bitop3_b32 v4, v5, v7, v4 bitop3:0x36
	v_lshlrev_b32_e32 v2, 12, v2
	s_movk_i32 s6, 0x3000
	s_add_u32 s16, s8, 0x40100
	v_and_or_b32 v133, v2, s6, v4
	s_addc_u32 s17, s9, 0
	s_add_i32 s6, s18, s19
	s_ashr_i32 s7, s6, 31
	v_lshlrev_b32_e32 v3, 13, v3
	s_lshl_b64 s[6:7], s[6:7], 11
	v_readlane_b32 s18, v254, 34
	v_bitop3_b32 v3, v6, v3, v7 bitop3:0xde
	s_add_u32 s18, s18, s6
	v_readlane_b32 s6, v254, 35
	v_mov_b32_e32 v2, 0
	s_addc_u32 s19, s6, s7
	s_mov_b32 s20, -2
	s_mov_b64 s[6:7], 0
	v_add_u32_e32 v130, 0, v3
	s_waitcnt lgkmcnt(0)
	v_readlane_b32 s22, v254, 49
	v_readlane_b32 s23, v254, 50
	s_barrier
	s_barrier
	v_add_u32_e32 v154, 0x10000, v133
	ds_read_b128 v[142:145], v154
	ds_read_b128 v[146:149], v154 offset:1024
	ds_read_b128 v[150:153], v154 offset:2048
	ds_read_b128 v[154:157], v154 offset:3072
	ds_read_b128 v[158:161], v130
	ds_read_b128 v[164:167], v130 offset:1024
	ds_read_b128 v[168:171], v130 offset:2048
	ds_read_b128 v[172:175], v130 offset:3072
	ds_read_b128 v[180:183], v130 offset:4096
	ds_read_b128 v[184:187], v130 offset:5120
	ds_read_b128 v[188:191], v130 offset:6144
	ds_read_b128 v[192:195], v130 offset:7168
	v_add_u32_e32 v208, 0x14000, v133
	ds_read_b128 v[196:199], v208
	ds_read_b128 v[200:203], v208 offset:1024
	ds_read_b128 v[204:207], v208 offset:2048
	ds_read_b128 v[208:211], v208 offset:3072
	s_add_u32 s24, s18, s6
	s_addc_u32 s25, s19, s7
	s_add_u32 s24, s24, 0x80
	s_addc_u32 s25, s25, 0
	s_add_i32 s23, s15, 0xc000
	s_mov_b32 m0, s23
	s_nop 0
	global_load_lds_dwordx4 v132, s[24:25]
	s_add_i32 s23, s15, 0xe000
	s_mov_b32 m0, s23
	s_nop 0
	global_load_lds_dwordx4 v131, s[24:25]
	s_waitcnt vmcnt(8) lgkmcnt(0)
	s_barrier
	s_setprio 1
	v_mfma_f32_16x16x32_bf16 v[126:129], v[158:161], v[142:145], 0
	v_mfma_f32_16x16x32_bf16 v[122:125], v[158:161], v[150:153], 0
	v_mfma_f32_16x16x32_bf16 v[118:121], v[168:171], v[142:145], 0
	v_mfma_f32_16x16x32_bf16 v[114:117], v[168:171], v[150:153], 0
	v_mfma_f32_16x16x32_bf16 v[110:113], v[180:183], v[142:145], 0
	v_mfma_f32_16x16x32_bf16 v[106:109], v[180:183], v[150:153], 0
	v_mfma_f32_16x16x32_bf16 v[102:105], v[188:191], v[142:145], 0
	v_mfma_f32_16x16x32_bf16 v[98:101], v[188:191], v[150:153], 0
	v_mfma_f32_16x16x32_bf16 v[126:129], v[164:167], v[146:149], v[126:129]
	v_mfma_f32_16x16x32_bf16 v[122:125], v[164:167], v[154:157], v[122:125]
	v_mfma_f32_16x16x32_bf16 v[118:121], v[172:175], v[146:149], v[118:121]
	v_mfma_f32_16x16x32_bf16 v[114:117], v[172:175], v[154:157], v[114:117]
	v_mfma_f32_16x16x32_bf16 v[110:113], v[184:187], v[146:149], v[110:113]
	v_mfma_f32_16x16x32_bf16 v[106:109], v[184:187], v[154:157], v[106:109]
	v_mfma_f32_16x16x32_bf16 v[102:105], v[192:195], v[146:149], v[102:105]
	v_mfma_f32_16x16x32_bf16 v[98:101], v[192:195], v[154:157], v[98:101]
	v_mfma_f32_16x16x32_bf16 v[94:97], v[158:161], v[196:199], 0
	v_mfma_f32_16x16x32_bf16 v[90:93], v[158:161], v[204:207], 0
	v_mfma_f32_16x16x32_bf16 v[86:89], v[168:171], v[196:199], 0
	v_mfma_f32_16x16x32_bf16 v[82:85], v[168:171], v[204:207], 0
	v_mfma_f32_16x16x32_bf16 v[78:81], v[180:183], v[196:199], 0
	v_mfma_f32_16x16x32_bf16 v[74:77], v[180:183], v[204:207], 0
	v_mfma_f32_16x16x32_bf16 v[70:73], v[188:191], v[196:199], 0
	v_mfma_f32_16x16x32_bf16 v[66:69], v[188:191], v[204:207], 0
	v_mfma_f32_16x16x32_bf16 v[94:97], v[164:167], v[200:203], v[94:97]
	v_mfma_f32_16x16x32_bf16 v[90:93], v[164:167], v[208:211], v[90:93]
	v_mfma_f32_16x16x32_bf16 v[86:89], v[172:175], v[200:203], v[86:89]
	v_mfma_f32_16x16x32_bf16 v[82:85], v[172:175], v[208:211], v[82:85]
	v_mfma_f32_16x16x32_bf16 v[78:81], v[184:187], v[200:203], v[78:81]
	v_mfma_f32_16x16x32_bf16 v[74:77], v[184:187], v[208:211], v[74:77]
	v_mfma_f32_16x16x32_bf16 v[70:73], v[192:195], v[200:203], v[70:73]
	v_mfma_f32_16x16x32_bf16 v[66:69], v[192:195], v[208:211], v[66:69]
	s_setprio 0
	s_barrier
; #define WAIT_V(n) asm volatile("s_waitcnt vmcnt(" #n ")" ::: "memory")
; #define WAIT_L(n) asm volatile("s_waitcnt lgkmcnt(" #n ")" ::: "memory")
; #define BAR __builtin_amdgcn_s_barrier()
; #define SCHED __builtin_amdgcn_sched_barrier(0)
; #define STG_A(b, h, kt) stage_half_s(lds0 + ((b) * 2 + (h)) * HT_B, ((h) ? A1 : Ap) + (kt) * BK, off0, off1)
; #define STG_B(b, h, kt) stage_half_s(lds0 + (4 + (b) * 2 + (h)) * HT_B, ((h) ? B1p : Bp) + (kt) * BK, off0, off1)
; #define STG_A(b, h, kt) stage_half_s(lds0 + ((b) * 2 + (h)) * HT_B, ((h) ? A1 : Ap) + (kt) * BK, off0, off1)
; #define STG_B(b, h, kt) stage_half_s(lds0 + (4 + (b) * 2 + (h)) * HT_B, ((h) ? B1p : Bp) + (kt) * BK, off0, off1)
; #define LDA8(b, h) _Pragma("unroll") for (int m = 0; m < 4; ++m) _Pragma("unroll") for (int k = 0; k < 2; ++k) \
;     At[m][k] = *(const bf16x8*)(SA_(shm, b, h) + abase + (m * 2 + k) * 1024)
; #define LDB8(dst, b, h) _Pragma("unroll") for (int n = 0; n < 2; ++n) _Pragma("unroll") for (int k = 0; k < 2; ++k) \
;     dst[n][k] = *(const bf16x8*)(SB_(shm, b, h) + bbase + (n * 2 + k) * 1024)
; #define MMA8(ai, bj, Bx) do { __builtin_amdgcn_s_setprio(1); \
;     _Pragma("unroll") for (int m = 0; m < 4; ++m) _Pragma("unroll") for (int n = 0; n < 2; ++n) _Pragma("unroll") for (int k = 0; k < 2; ++k) \
;       acc[ai][bj][m][n] = __builtin_amdgcn_mfma_f32_16x16x32_bf16(At[m][k], Bx[n][k], acc[ai][bj][m][n], 0, 0, 0); \
;     __builtin_amdgcn_s_setprio(0); } while (0)
; template <bool HS>
; __device__ __forceinline__ void gemm_tile8(const u16* __restrict__ Ap, const u16* __restrict__ Bp, int K,
;                                            f32x4 (&acc)[2][2][4][2], char* shm, const int tid, const float* hsr = nullptr) {
;     ...
;     LDA8(0, 1); STG_A(0, 0, t + 2);
;     BAR; WAIT_L(0); MMA8(1, 0, B0); BAR; SCHED;
;     STG_B(0, 1, t + 2);
;     WAIT_V(6); BAR; MMA8(1, 1, B1); BAR;
;     LDB8(B0, 1, 0); SCHED; LDA8(1, 0); STG_A(0, 1, t + 2);
;     WAIT_L(8); BAR; WAIT_L(0); MMA8(0, 0, B0); BAR; SCHED;
	ds_read_b128 v[158:161], v130 offset:16384
	ds_read_b128 v[164:167], v130 offset:17408
	ds_read_b128 v[168:171], v130 offset:18432
	ds_read_b128 v[172:175], v130 offset:19456
	ds_read_b128 v[180:183], v130 offset:20480
	ds_read_b128 v[184:187], v130 offset:21504
	ds_read_b128 v[188:191], v130 offset:22528
	ds_read_b128 v[192:195], v130 offset:23552
	s_add_u32 s24, s3, s6
	s_addc_u32 s25, s10, s7
	s_add_u32 s24, s24, 0x100
	s_addc_u32 s25, s25, 0
	s_add_i32 s23, s15, 0x10000
	s_mov_b32 m0, s23
	s_nop 0
	global_load_lds_dwordx4 v132, s[24:25]
	s_add_i32 s23, s15, 0x12000
	s_mov_b32 m0, s23
	s_nop 0
	global_load_lds_dwordx4 v131, s[24:25]
	s_add_u32 s24, s8, s6
	s_addc_u32 s25, s9, s7
	s_add_u32 s24, s24, 0x100
	s_addc_u32 s25, s25, 0
	s_mov_b32 m0, s15
	s_nop 0
	global_load_lds_dwordx4 v132, s[24:25]
	s_add_i32 s23, s15, 0x2000
	s_mov_b32 m0, s23
	s_nop 0
	global_load_lds_dwordx4 v131, s[24:25]
	s_add_u32 s24, s13, s6
	s_addc_u32 s25, s14, s7
	s_add_u32 s24, s24, 0x100
	s_addc_u32 s25, s25, 0
	s_add_i32 s23, s15, 0x14000
	s_mov_b32 m0, s23
	s_nop 0
	global_load_lds_dwordx4 v132, s[24:25]
	s_add_i32 s23, s15, 0x16000
	s_mov_b32 m0, s23
	s_nop 0
	global_load_lds_dwordx4 v131, s[24:25]
	s_waitcnt vmcnt(8) lgkmcnt(0)
	s_barrier
	s_setprio 1
	v_mfma_f32_16x16x32_bf16 v[62:65], v[158:161], v[142:145], 0
	v_mfma_f32_16x16x32_bf16 v[58:61], v[158:161], v[150:153], 0
	v_mfma_f32_16x16x32_bf16 v[54:57], v[168:171], v[142:145], 0
	v_mfma_f32_16x16x32_bf16 v[50:53], v[168:171], v[150:153], 0
	v_mfma_f32_16x16x32_bf16 v[46:49], v[180:183], v[142:145], 0
	v_mfma_f32_16x16x32_bf16 v[42:45], v[180:183], v[150:153], 0
	v_mfma_f32_16x16x32_bf16 v[38:41], v[188:191], v[142:145], 0
	v_mfma_f32_16x16x32_bf16 v[34:37], v[188:191], v[150:153], 0
	v_mfma_f32_16x16x32_bf16 v[62:65], v[164:167], v[146:149], v[62:65]
	v_mfma_f32_16x16x32_bf16 v[58:61], v[164:167], v[154:157], v[58:61]
	v_mfma_f32_16x16x32_bf16 v[54:57], v[172:175], v[146:149], v[54:57]
	v_mfma_f32_16x16x32_bf16 v[50:53], v[172:175], v[154:157], v[50:53]
	v_mfma_f32_16x16x32_bf16 v[46:49], v[184:187], v[146:149], v[46:49]
	v_mfma_f32_16x16x32_bf16 v[42:45], v[184:187], v[154:157], v[42:45]
	v_mfma_f32_16x16x32_bf16 v[38:41], v[192:195], v[146:149], v[38:41]
	v_mfma_f32_16x16x32_bf16 v[34:37], v[192:195], v[154:157], v[34:37]
	v_mfma_f32_16x16x32_bf16 v[30:33], v[158:161], v[196:199], 0
	v_mfma_f32_16x16x32_bf16 v[26:29], v[158:161], v[204:207], 0
	v_mfma_f32_16x16x32_bf16 v[22:25], v[168:171], v[196:199], 0
	v_mfma_f32_16x16x32_bf16 v[18:21], v[168:171], v[204:207], 0
	v_mfma_f32_16x16x32_bf16 v[14:17], v[180:183], v[196:199], 0
	v_mfma_f32_16x16x32_bf16 v[10:13], v[180:183], v[204:207], 0
	v_mfma_f32_16x16x32_bf16 v[6:9], v[188:191], v[196:199], 0
	v_mfma_f32_16x16x32_bf16 v[2:5], v[188:191], v[204:207], 0
	v_mfma_f32_16x16x32_bf16 v[30:33], v[164:167], v[200:203], v[30:33]
	v_mfma_f32_16x16x32_bf16 v[26:29], v[164:167], v[208:211], v[26:29]
	v_mfma_f32_16x16x32_bf16 v[22:25], v[172:175], v[200:203], v[22:25]
	v_mfma_f32_16x16x32_bf16 v[18:21], v[172:175], v[208:211], v[18:21]
	v_mfma_f32_16x16x32_bf16 v[14:17], v[184:187], v[200:203], v[14:17]
	v_mfma_f32_16x16x32_bf16 v[10:13], v[184:187], v[208:211], v[10:13]
	v_mfma_f32_16x16x32_bf16 v[6:9], v[192:195], v[200:203], v[6:9]
	v_mfma_f32_16x16x32_bf16 v[2:5], v[192:195], v[208:211], v[2:5]
	s_setprio 0
	s_barrier
	v_add_u32_e32 v154, 0x18000, v133
	ds_read_b128 v[142:145], v154
	ds_read_b128 v[146:149], v154 offset:1024
	ds_read_b128 v[150:153], v154 offset:2048
	ds_read_b128 v[154:157], v154 offset:3072
	ds_read_b128 v[158:161], v130 offset:32768
	ds_read_b128 v[164:167], v130 offset:33792
	ds_read_b128 v[168:171], v130 offset:34816
	ds_read_b128 v[172:175], v130 offset:35840
	ds_read_b128 v[180:183], v130 offset:36864
	ds_read_b128 v[184:187], v130 offset:37888
	ds_read_b128 v[188:191], v130 offset:38912
	ds_read_b128 v[192:195], v130 offset:39936
	v_add_u32_e32 v208, 0x1c000, v133
	ds_read_b128 v[196:199], v208
	ds_read_b128 v[200:203], v208 offset:1024
	ds_read_b128 v[204:207], v208 offset:2048
	ds_read_b128 v[208:211], v208 offset:3072
	s_add_u32 s24, s18, s6
	s_addc_u32 s25, s19, s7
	s_add_u32 s24, s24, 0x100
	s_addc_u32 s25, s25, 0
	s_add_i32 s23, s15, 0x4000
	s_mov_b32 m0, s23
	s_nop 0
	global_load_lds_dwordx4 v132, s[24:25]
	s_add_i32 s23, s15, 0x6000
	s_mov_b32 m0, s23
	s_nop 0
	global_load_lds_dwordx4 v131, s[24:25]
	s_waitcnt vmcnt(8) lgkmcnt(0)
	s_barrier
; #define WAIT_V(n) asm volatile("s_waitcnt vmcnt(" #n ")" ::: "memory")
; #define WAIT_L(n) asm volatile("s_waitcnt lgkmcnt(" #n ")" ::: "memory")
; #define BAR __builtin_amdgcn_s_barrier()
; #define SCHED __builtin_amdgcn_sched_barrier(0)
; #define STG_A(b, h, kt) stage_half_s(lds0 + ((b) * 2 + (h)) * HT_B, ((h) ? A1 : Ap) + (kt) * BK, off0, off1)
; #define STG_B(b, h, kt) stage_half_s(lds0 + (4 + (b) * 2 + (h)) * HT_B, ((h) ? B1p : Bp) + (kt) * BK, off0, off1)
; #define STG_A(b, h, kt) stage_half_s(lds0 + ((b) * 2 + (h)) * HT_B, ((h) ? A1 : Ap) + (kt) * BK, off0, off1)
; #define STG_B(b, h, kt) stage_half_s(lds0 + (4 + (b) * 2 + (h)) * HT_B, ((h) ? B1p : Bp) + (kt) * BK, off0, off1)
; #define LDA8(b, h) _Pragma("unroll") for (int m = 0; m < 4; ++m) _Pragma("unroll") for (int k = 0; k < 2; ++k) \
;     At[m][k] = *(const bf16x8*)(SA_(shm, b, h) + abase + (m * 2 + k) * 1024)
; #define LDB8(dst, b, h) _Pragma("unroll") for (int n = 0; n < 2; ++n) _Pragma("unroll") for (int k = 0; k < 2; ++k) \
;     dst[n][k] = *(const bf16x8*)(SB_(shm, b, h) + bbase + (n * 2 + k) * 1024)
; #define MMA8(ai, bj, Bx) do { __builtin_amdgcn_s_setprio(1); \
;     _Pragma("unroll") for (int m = 0; m < 4; ++m) _Pragma("unroll") for (int n = 0; n < 2; ++n) _Pragma("unroll") for (int k = 0; k < 2; ++k) \
;       acc[ai][bj][m][n] = __builtin_amdgcn_mfma_f32_16x16x32_bf16(At[m][k], Bx[n][k], acc[ai][bj][m][n], 0, 0, 0); \
;     __builtin_amdgcn_s_setprio(0); } while (0)
; template <bool HS>
; __device__ __forceinline__ void gemm_tile8(const u16* __restrict__ Ap, const u16* __restrict__ Bp, int K,
;                                            f32x4 (&acc)[2][2][4][2], char* shm, const int tid, const float* hsr = nullptr) {
;     ...
;     WAIT_L(8); BAR; WAIT_L(0); MMA8(0, 0, B0); BAR; SCHED;
;     LDB8(B1, 1, 1); STG_B(1, 0, t + 3);
;     BAR; WAIT_L(0); MMA8(0, 1, B1); BAR;
;     LDA8(1, 1); STG_A(1, 0, t + 3);
;     BAR; WAIT_L(0); MMA8(1, 0, B0); BAR; SCHED;
;     STG_B(1, 1, t + 3);
;     WAIT_V(6); BAR; MMA8(1, 1, B1); BAR;
;   }
	s_setprio 1
	v_mfma_f32_16x16x32_bf16 v[126:129], v[158:161], v[142:145], v[126:129]
	v_mfma_f32_16x16x32_bf16 v[122:125], v[158:161], v[150:153], v[122:125]
	v_mfma_f32_16x16x32_bf16 v[118:121], v[168:171], v[142:145], v[118:121]
	v_mfma_f32_16x16x32_bf16 v[114:117], v[168:171], v[150:153], v[114:117]
	v_mfma_f32_16x16x32_bf16 v[110:113], v[180:183], v[142:145], v[110:113]
	v_mfma_f32_16x16x32_bf16 v[106:109], v[180:183], v[150:153], v[106:109]
	v_mfma_f32_16x16x32_bf16 v[102:105], v[188:191], v[142:145], v[102:105]
	v_mfma_f32_16x16x32_bf16 v[98:101], v[188:191], v[150:153], v[98:101]
	v_mfma_f32_16x16x32_bf16 v[126:129], v[164:167], v[146:149], v[126:129]
	v_mfma_f32_16x16x32_bf16 v[122:125], v[164:167], v[154:157], v[122:125]
	v_mfma_f32_16x16x32_bf16 v[118:121], v[172:175], v[146:149], v[118:121]
	v_mfma_f32_16x16x32_bf16 v[114:117], v[172:175], v[154:157], v[114:117]
	v_mfma_f32_16x16x32_bf16 v[110:113], v[184:187], v[146:149], v[110:113]
	v_mfma_f32_16x16x32_bf16 v[106:109], v[184:187], v[154:157], v[106:109]
	v_mfma_f32_16x16x32_bf16 v[102:105], v[192:195], v[146:149], v[102:105]
	v_mfma_f32_16x16x32_bf16 v[98:101], v[192:195], v[154:157], v[98:101]
	v_mfma_f32_16x16x32_bf16 v[94:97], v[158:161], v[196:199], v[94:97]
	v_mfma_f32_16x16x32_bf16 v[90:93], v[158:161], v[204:207], v[90:93]
	v_mfma_f32_16x16x32_bf16 v[86:89], v[168:171], v[196:199], v[86:89]
	v_mfma_f32_16x16x32_bf16 v[82:85], v[168:171], v[204:207], v[82:85]
	v_mfma_f32_16x16x32_bf16 v[78:81], v[180:183], v[196:199], v[78:81]
	v_mfma_f32_16x16x32_bf16 v[74:77], v[180:183], v[204:207], v[74:77]
	v_mfma_f32_16x16x32_bf16 v[70:73], v[188:191], v[196:199], v[70:73]
	v_mfma_f32_16x16x32_bf16 v[66:69], v[188:191], v[204:207], v[66:69]
	v_mfma_f32_16x16x32_bf16 v[94:97], v[164:167], v[200:203], v[94:97]
	v_mfma_f32_16x16x32_bf16 v[90:93], v[164:167], v[208:211], v[90:93]
	v_mfma_f32_16x16x32_bf16 v[86:89], v[172:175], v[200:203], v[86:89]
	v_mfma_f32_16x16x32_bf16 v[82:85], v[172:175], v[208:211], v[82:85]
	v_mfma_f32_16x16x32_bf16 v[78:81], v[184:187], v[200:203], v[78:81]
	v_mfma_f32_16x16x32_bf16 v[74:77], v[184:187], v[208:211], v[74:77]
	v_mfma_f32_16x16x32_bf16 v[70:73], v[192:195], v[200:203], v[70:73]
	v_mfma_f32_16x16x32_bf16 v[66:69], v[192:195], v[208:211], v[66:69]
	s_setprio 0
	s_barrier
	ds_read_b128 v[158:161], v130 offset:49152
	ds_read_b128 v[164:167], v130 offset:50176
	ds_read_b128 v[168:171], v130 offset:51200
	ds_read_b128 v[172:175], v130 offset:52224
	ds_read_b128 v[180:183], v130 offset:53248
	ds_read_b128 v[184:187], v130 offset:54272
	ds_read_b128 v[188:191], v130 offset:55296
	ds_read_b128 v[192:195], v130 offset:56320
	s_add_u32 s24, s3, s6
	s_addc_u32 s25, s10, s7
	s_add_u32 s24, s24, 0x180
	s_addc_u32 s25, s25, 0
	s_add_i32 s23, s15, 0x18000
	s_mov_b32 m0, s23
	s_nop 0
	global_load_lds_dwordx4 v132, s[24:25]
	s_add_i32 s23, s15, 0x1a000
	s_mov_b32 m0, s23
	s_nop 0
	global_load_lds_dwordx4 v131, s[24:25]
	s_add_u32 s24, s8, s6
	s_addc_u32 s25, s9, s7
	s_add_u32 s24, s24, 0x180
	s_addc_u32 s25, s25, 0
	s_add_i32 s23, s15, 0x8000
	s_mov_b32 m0, s23
	s_nop 0
	global_load_lds_dwordx4 v132, s[24:25]
	s_add_i32 s23, s15, 0xa000
	s_mov_b32 m0, s23
	s_nop 0
	global_load_lds_dwordx4 v131, s[24:25]
	s_add_u32 s24, s13, s6
	s_addc_u32 s25, s14, s7
	s_add_u32 s24, s24, 0x180
	s_addc_u32 s25, s25, 0
	s_add_i32 s23, s15, 0x1c000
	s_mov_b32 m0, s23
	s_nop 0
	global_load_lds_dwordx4 v132, s[24:25]
	s_add_i32 s23, s15, 0x1e000
	s_mov_b32 m0, s23
	s_nop 0
	global_load_lds_dwordx4 v131, s[24:25]
	s_waitcnt vmcnt(8) lgkmcnt(0)
	s_barrier
	s_setprio 1
	v_mfma_f32_16x16x32_bf16 v[62:65], v[158:161], v[142:145], v[62:65]
	v_mfma_f32_16x16x32_bf16 v[58:61], v[158:161], v[150:153], v[58:61]
	v_mfma_f32_16x16x32_bf16 v[54:57], v[168:171], v[142:145], v[54:57]
	v_mfma_f32_16x16x32_bf16 v[50:53], v[168:171], v[150:153], v[50:53]
	v_mfma_f32_16x16x32_bf16 v[46:49], v[180:183], v[142:145], v[46:49]
	v_mfma_f32_16x16x32_bf16 v[42:45], v[180:183], v[150:153], v[42:45]
	v_mfma_f32_16x16x32_bf16 v[38:41], v[188:191], v[142:145], v[38:41]
	v_mfma_f32_16x16x32_bf16 v[34:37], v[188:191], v[150:153], v[34:37]
	v_mfma_f32_16x16x32_bf16 v[62:65], v[164:167], v[146:149], v[62:65]
	v_mfma_f32_16x16x32_bf16 v[58:61], v[164:167], v[154:157], v[58:61]
	v_mfma_f32_16x16x32_bf16 v[54:57], v[172:175], v[146:149], v[54:57]
	v_mfma_f32_16x16x32_bf16 v[50:53], v[172:175], v[154:157], v[50:53]
	v_mfma_f32_16x16x32_bf16 v[46:49], v[184:187], v[146:149], v[46:49]
	v_mfma_f32_16x16x32_bf16 v[42:45], v[184:187], v[154:157], v[42:45]
	v_mfma_f32_16x16x32_bf16 v[38:41], v[192:195], v[146:149], v[38:41]
	v_mfma_f32_16x16x32_bf16 v[34:37], v[192:195], v[154:157], v[34:37]
	v_mfma_f32_16x16x32_bf16 v[30:33], v[158:161], v[196:199], v[30:33]
	v_mfma_f32_16x16x32_bf16 v[26:29], v[158:161], v[204:207], v[26:29]
	v_mfma_f32_16x16x32_bf16 v[22:25], v[168:171], v[196:199], v[22:25]
	v_mfma_f32_16x16x32_bf16 v[18:21], v[168:171], v[204:207], v[18:21]
	v_mfma_f32_16x16x32_bf16 v[14:17], v[180:183], v[196:199], v[14:17]
	v_mfma_f32_16x16x32_bf16 v[10:13], v[180:183], v[204:207], v[10:13]
	v_mfma_f32_16x16x32_bf16 v[6:9], v[188:191], v[196:199], v[6:9]
	v_mfma_f32_16x16x32_bf16 v[2:5], v[188:191], v[204:207], v[2:5]
	v_mfma_f32_16x16x32_bf16 v[30:33], v[164:167], v[200:203], v[30:33]
	v_mfma_f32_16x16x32_bf16 v[26:29], v[164:167], v[208:211], v[26:29]
	v_mfma_f32_16x16x32_bf16 v[22:25], v[172:175], v[200:203], v[22:25]
	v_mfma_f32_16x16x32_bf16 v[18:21], v[172:175], v[208:211], v[18:21]
	v_mfma_f32_16x16x32_bf16 v[14:17], v[184:187], v[200:203], v[14:17]
	v_mfma_f32_16x16x32_bf16 v[10:13], v[184:187], v[208:211], v[10:13]
	v_mfma_f32_16x16x32_bf16 v[6:9], v[192:195], v[200:203], v[6:9]
	v_mfma_f32_16x16x32_bf16 v[2:5], v[192:195], v[208:211], v[2:5]
	s_setprio 0
	s_add_i32 s20, s20, 2
	s_add_u32 s6, s6, 0x100
	s_addc_u32 s7, s7, 0
	s_cmp_lt_u32 s20, 12
	s_barrier
	s_cbranch_scc0 .Lk_ret_in_exit

; #define WAIT_V(n) asm volatile("s_waitcnt vmcnt(" #n ")" ::: "memory")
; #define WAIT_L(n) asm volatile("s_waitcnt lgkmcnt(" #n ")" ::: "memory")
; #define BAR __builtin_amdgcn_s_barrier()
; #define STG_A(b, h, kt) stage_half_s(lds0 + ((b) * 2 + (h)) * HT_B, ((h) ? A1 : Ap) + (kt) * BK, off0, off1)
; #define STG_A(b, h, kt) stage_half_s(lds0 + ((b) * 2 + (h)) * HT_B, ((h) ? A1 : Ap) + (kt) * BK, off0, off1)
; #define LDA8(b, h) _Pragma("unroll") for (int m = 0; m < 4; ++m) _Pragma("unroll") for (int k = 0; k < 2; ++k) \
;     At[m][k] = *(const bf16x8*)(SA_(shm, b, h) + abase + (m * 2 + k) * 1024)
; #define LDB8(dst, b, h) _Pragma("unroll") for (int n = 0; n < 2; ++n) _Pragma("unroll") for (int k = 0; k < 2; ++k) \
;     dst[n][k] = *(const bf16x8*)(SB_(shm, b, h) + bbase + (n * 2 + k) * 1024)
; #define MMA8(ai, bj, Bx) do { __builtin_amdgcn_s_setprio(1); \
;     _Pragma("unroll") for (int m = 0; m < 4; ++m) _Pragma("unroll") for (int n = 0; n < 2; ++n) _Pragma("unroll") for (int k = 0; k < 2; ++k) \
;       acc[ai][bj][m][n] = __builtin_amdgcn_mfma_f32_16x16x32_bf16(At[m][k], Bx[n][k], acc[ai][bj][m][n], 0, 0, 0); \
;     __builtin_amdgcn_s_setprio(0); } while (0)
; template <bool HS>
; __device__ __forceinline__ void gemm_tile8(const u16* __restrict__ Ap, const u16* __restrict__ Bp, int K,
;                                            f32x4 (&acc)[2][2][4][2], char* shm, const int tid, const float* hsr = nullptr) {
;     ...
;   { LDB8(B0, 0, 0); LDA8(0, 0); STG_A(1, 1, nt - 1);
;     BAR; WAIT_L(0); MMA8(0, 0, B0); BAR;
;     LDB8(B1, 0, 1); BAR; WAIT_L(0); MMA8(0, 1, B1); BAR;
;     LDA8(0, 1); WAIT_V(4); BAR; WAIT_L(0); MMA8(1, 0, B0); MMA8(1, 1, B1); BAR; }
.Lk_ret_in_exit:
	s_waitcnt vmcnt(6)
	s_add_i32 s21, s15, 0xc000
	s_add_i32 s22, s15, 0xe000
	s_mov_b32 s89, 0x10000
	v_add_u32_e32 v133, 0, v133
	v_add_u32_e32 v135, 0x10000, v133
	ds_read_b128 v[142:145], v135
	ds_read_b128 v[146:149], v135 offset:1024
	ds_read_b128 v[150:153], v135 offset:2048
	ds_read_b128 v[154:157], v135 offset:3072
	ds_read_b128 v[158:161], v130
	ds_read_b128 v[164:167], v130 offset:1024
	ds_read_b128 v[168:171], v130 offset:2048
	ds_read_b128 v[172:175], v130 offset:3072
	ds_read_b128 v[180:183], v130 offset:4096
	ds_read_b128 v[184:187], v130 offset:5120
	ds_read_b128 v[188:191], v130 offset:6144
	ds_read_b128 v[192:195], v130 offset:7168
	s_add_u32 s6, s8, 0x40780
	s_addc_u32 s7, s9, 0
	s_mov_b32 m0, s21
	s_nop 0
	global_load_lds_dwordx4 v132, s[6:7]
	s_nop 0
	s_mov_b32 m0, s22
	s_nop 0
	global_load_lds_dwordx4 v131, s[6:7]
	s_barrier
	s_waitcnt lgkmcnt(0)
	s_setprio 1
	s_waitcnt lgkmcnt(7)
	v_mfma_f32_16x16x32_bf16 v[126:129], v[158:161], v[142:145], v[126:129]
	s_waitcnt lgkmcnt(5)
	v_mfma_f32_16x16x32_bf16 v[118:121], v[168:171], v[142:145], v[118:121]
	v_mfma_f32_16x16x32_bf16 v[114:117], v[168:171], v[150:153], v[114:117]
	s_waitcnt lgkmcnt(1)
	v_mfma_f32_16x16x32_bf16 v[102:105], v[188:191], v[142:145], v[102:105]
	v_mfma_f32_16x16x32_bf16 v[98:101], v[188:191], v[150:153], v[98:101]
	v_mfma_f32_16x16x32_bf16 v[126:129], v[164:167], v[146:149], v[126:129]
	v_mfma_f32_16x16x32_bf16 v[122:125], v[158:161], v[150:153], v[122:125]
	v_mfma_f32_16x16x32_bf16 v[118:121], v[172:175], v[146:149], v[118:121]
	v_mfma_f32_16x16x32_bf16 v[114:117], v[172:175], v[154:157], v[114:117]
	v_mfma_f32_16x16x32_bf16 v[110:113], v[180:183], v[142:145], v[110:113]
	v_mfma_f32_16x16x32_bf16 v[106:109], v[180:183], v[150:153], v[106:109]
	s_waitcnt lgkmcnt(0)
	v_mfma_f32_16x16x32_bf16 v[102:105], v[192:195], v[146:149], v[102:105]
	v_mfma_f32_16x16x32_bf16 v[98:101], v[192:195], v[154:157], v[98:101]
	v_mfma_f32_16x16x32_bf16 v[196:199], v[164:167], v[154:157], v[122:125]
	v_mfma_f32_16x16x32_bf16 v[200:203], v[184:187], v[146:149], v[110:113]
	v_mfma_f32_16x16x32_bf16 v[204:207], v[184:187], v[154:157], v[106:109]
	s_setprio 0
	v_add_u32_e32 v131, 0x14000, v133
	s_barrier
	ds_read_b128 v[106:109], v131
	ds_read_b128 v[110:113], v131 offset:1024
	ds_read_b128 v[122:125], v131 offset:2048
	ds_read_b128 v[208:211], v131 offset:3072
	s_barrier
	s_waitcnt lgkmcnt(0)
	s_setprio 1
	s_waitcnt lgkmcnt(3)
	v_mfma_f32_16x16x32_bf16 v[86:89], v[168:171], v[106:109], v[86:89]
	s_waitcnt lgkmcnt(1)
	v_mfma_f32_16x16x32_bf16 v[82:85], v[168:171], v[122:125], v[82:85]
	v_mfma_f32_16x16x32_bf16 v[70:73], v[188:191], v[106:109], v[70:73]
	v_mfma_f32_16x16x32_bf16 v[94:97], v[158:161], v[106:109], v[94:97]
	v_mfma_f32_16x16x32_bf16 v[90:93], v[158:161], v[122:125], v[90:93]
	v_mfma_f32_16x16x32_bf16 v[86:89], v[172:175], v[110:113], v[86:89]
	s_waitcnt lgkmcnt(0)
	v_mfma_f32_16x16x32_bf16 v[82:85], v[172:175], v[208:211], v[82:85]
	v_mfma_f32_16x16x32_bf16 v[78:81], v[180:183], v[106:109], v[78:81]
	v_mfma_f32_16x16x32_bf16 v[74:77], v[180:183], v[122:125], v[74:77]
	v_mfma_f32_16x16x32_bf16 v[70:73], v[192:195], v[110:113], v[70:73]
	v_mfma_f32_16x16x32_bf16 v[66:69], v[188:191], v[122:125], v[66:69]
	v_mfma_f32_16x16x32_bf16 v[212:215], v[164:167], v[110:113], v[94:97]
	v_mfma_f32_16x16x32_bf16 v[158:161], v[164:167], v[208:211], v[90:93]
	v_mfma_f32_16x16x32_bf16 v[164:167], v[184:187], v[110:113], v[78:81]
	v_mfma_f32_16x16x32_bf16 v[168:171], v[184:187], v[208:211], v[74:77]
	v_mfma_f32_16x16x32_bf16 v[172:175], v[192:195], v[208:211], v[66:69]
	s_setprio 0
	s_barrier
	s_nop 0
	ds_read_b128 v[66:69], v130 offset:16384
	ds_read_b128 v[74:77], v130 offset:17408
	ds_read_b128 v[78:81], v130 offset:18432
	ds_read_b128 v[90:93], v130 offset:19456
	ds_read_b128 v[94:97], v130 offset:20480
	ds_read_b128 v[180:183], v130 offset:21504
	ds_read_b128 v[184:187], v130 offset:22528
	ds_read_b128 v[188:191], v130 offset:23552
	s_waitcnt vmcnt(4)
	s_barrier
	s_waitcnt lgkmcnt(0)
	s_setprio 1
	s_waitcnt lgkmcnt(7)
	v_mfma_f32_16x16x32_bf16 v[62:65], v[66:69], v[142:145], v[62:65]
	s_waitcnt lgkmcnt(5)
	v_mfma_f32_16x16x32_bf16 v[54:57], v[78:81], v[142:145], v[54:57]
	v_mfma_f32_16x16x32_bf16 v[50:53], v[78:81], v[150:153], v[50:53]
	s_waitcnt lgkmcnt(1)
	v_mfma_f32_16x16x32_bf16 v[38:41], v[184:187], v[142:145], v[38:41]
	v_mfma_f32_16x16x32_bf16 v[34:37], v[184:187], v[150:153], v[34:37]
	v_mfma_f32_16x16x32_bf16 v[62:65], v[74:77], v[146:149], v[62:65]
	v_mfma_f32_16x16x32_bf16 v[58:61], v[66:69], v[150:153], v[58:61]
	v_mfma_f32_16x16x32_bf16 v[54:57], v[90:93], v[146:149], v[54:57]
	v_mfma_f32_16x16x32_bf16 v[50:53], v[90:93], v[154:157], v[50:53]
	v_mfma_f32_16x16x32_bf16 v[46:49], v[94:97], v[142:145], v[46:49]
	v_mfma_f32_16x16x32_bf16 v[42:45], v[94:97], v[150:153], v[42:45]
	s_waitcnt lgkmcnt(0)
	v_mfma_f32_16x16x32_bf16 v[38:41], v[188:191], v[146:149], v[38:41]
	v_mfma_f32_16x16x32_bf16 v[34:37], v[188:191], v[154:157], v[34:37]
	v_mfma_f32_16x16x32_bf16 v[192:195], v[74:77], v[154:157], v[58:61]
	v_mfma_f32_16x16x32_bf16 v[220:223], v[180:183], v[146:149], v[46:49]
	v_mfma_f32_16x16x32_bf16 v[224:227], v[180:183], v[154:157], v[42:45]
	s_setprio 0
	s_setprio 1
	v_mfma_f32_16x16x32_bf16 v[22:25], v[78:81], v[106:109], v[22:25]
	v_mfma_f32_16x16x32_bf16 v[18:21], v[78:81], v[122:125], v[18:21]
	v_mfma_f32_16x16x32_bf16 v[6:9], v[184:187], v[106:109], v[6:9]
	v_mfma_f32_16x16x32_bf16 v[30:33], v[66:69], v[106:109], v[30:33]
	v_mfma_f32_16x16x32_bf16 v[26:29], v[66:69], v[122:125], v[26:29]
	v_mfma_f32_16x16x32_bf16 v[22:25], v[90:93], v[110:113], v[22:25]
	v_mfma_f32_16x16x32_bf16 v[18:21], v[90:93], v[208:211], v[18:21]
	v_mfma_f32_16x16x32_bf16 v[14:17], v[94:97], v[106:109], v[14:17]
	v_mfma_f32_16x16x32_bf16 v[10:13], v[94:97], v[122:125], v[10:13]
	v_mfma_f32_16x16x32_bf16 v[6:9], v[188:191], v[110:113], v[6:9]
	v_mfma_f32_16x16x32_bf16 v[2:5], v[184:187], v[122:125], v[2:5]
	v_mfma_f32_16x16x32_bf16 v[142:145], v[74:77], v[110:113], v[30:33]
	v_mfma_f32_16x16x32_bf16 v[146:149], v[74:77], v[208:211], v[26:29]
	v_mfma_f32_16x16x32_bf16 v[150:153], v[180:183], v[110:113], v[14:17]
	v_mfma_f32_16x16x32_bf16 v[154:157], v[180:183], v[208:211], v[10:13]
	v_mfma_f32_16x16x32_bf16 v[180:183], v[188:191], v[208:211], v[2:5]
	s_setprio 0
	v_add_u32_e32 v26, 0x18000, v133
	s_barrier
; #define WAIT_V(n) asm volatile("s_waitcnt vmcnt(" #n ")" ::: "memory")
; #define WAIT_L(n) asm volatile("s_waitcnt lgkmcnt(" #n ")" ::: "memory")
; #define BAR __builtin_amdgcn_s_barrier()
; #define LDA8(b, h) _Pragma("unroll") for (int m = 0; m < 4; ++m) _Pragma("unroll") for (int k = 0; k < 2; ++k) \
;     At[m][k] = *(const bf16x8*)(SA_(shm, b, h) + abase + (m * 2 + k) * 1024)
; #define LDB8(dst, b, h) _Pragma("unroll") for (int n = 0; n < 2; ++n) _Pragma("unroll") for (int k = 0; k < 2; ++k) \
;     dst[n][k] = *(const bf16x8*)(SB_(shm, b, h) + bbase + (n * 2 + k) * 1024)
; #define MMA8(ai, bj, Bx) do { __builtin_amdgcn_s_setprio(1); \
;     _Pragma("unroll") for (int m = 0; m < 4; ++m) _Pragma("unroll") for (int n = 0; n < 2; ++n) _Pragma("unroll") for (int k = 0; k < 2; ++k) \
;       acc[ai][bj][m][n] = __builtin_amdgcn_mfma_f32_16x16x32_bf16(At[m][k], Bx[n][k], acc[ai][bj][m][n], 0, 0, 0); \
;     __builtin_amdgcn_s_setprio(0); } while (0)
; template <bool HS>
; __device__ __forceinline__ void gemm_tile8(const u16* __restrict__ Ap, const u16* __restrict__ Bp, int K,
;                                            f32x4 (&acc)[2][2][4][2], char* shm, const int tid, const float* hsr = nullptr) {
;     ...
;   { LDB8(B0, 1, 0); LDA8(1, 0); WAIT_V(2); BAR; WAIT_L(0); MMA8(0, 0, B0); BAR;
;     LDB8(B1, 1, 1); WAIT_V(0); BAR; WAIT_L(0); MMA8(0, 1, B1); BAR;
;     LDA8(1, 1); BAR; WAIT_L(0); MMA8(1, 0, B0); MMA8(1, 1, B1); BAR; }
;   if (wr == 0) BAR;
	ds_read_b128 v[2:5], v26
	ds_read_b128 v[10:13], v26 offset:1024
	ds_read_b128 v[14:17], v26 offset:2048
	ds_read_b128 v[184:187], v26 offset:3072
	ds_read_b128 v[26:29], v130 offset:32768
	ds_read_b128 v[30:33], v130 offset:33792
	ds_read_b128 v[42:45], v130 offset:34816
	ds_read_b128 v[46:49], v130 offset:35840
	ds_read_b128 v[58:61], v130 offset:36864
	ds_read_b128 v[66:69], v130 offset:37888
	ds_read_b128 v[188:191], v130 offset:38912
	ds_read_b128 v[208:211], v130 offset:39936
	s_waitcnt vmcnt(2)
	s_barrier
	s_waitcnt lgkmcnt(0)
	s_setprio 1
	s_waitcnt lgkmcnt(7)
	v_mfma_f32_16x16x32_bf16 v[74:77], v[26:29], v[2:5], v[126:129]
	s_waitcnt lgkmcnt(6)
	v_mfma_f32_16x16x32_bf16 v[122:125], v[30:33], v[10:13], v[74:77]
	v_mfma_f32_16x16x32_bf16 v[74:77], v[26:29], v[14:17], v[196:199]
	v_mfma_f32_16x16x32_bf16 v[126:129], v[30:33], v[184:187], v[74:77]
	s_waitcnt lgkmcnt(5)
	v_mfma_f32_16x16x32_bf16 v[74:77], v[42:45], v[2:5], v[118:121]
	s_waitcnt lgkmcnt(4)
	v_mfma_f32_16x16x32_bf16 v[106:109], v[46:49], v[10:13], v[74:77]
	v_mfma_f32_16x16x32_bf16 v[74:77], v[42:45], v[14:17], v[114:117]
	v_mfma_f32_16x16x32_bf16 v[110:113], v[46:49], v[184:187], v[74:77]
	s_waitcnt lgkmcnt(3)
	v_mfma_f32_16x16x32_bf16 v[74:77], v[58:61], v[2:5], v[200:203]
	s_waitcnt lgkmcnt(2)
	v_mfma_f32_16x16x32_bf16 v[90:93], v[66:69], v[10:13], v[74:77]
	v_mfma_f32_16x16x32_bf16 v[74:77], v[58:61], v[14:17], v[204:207]
	v_mfma_f32_16x16x32_bf16 v[94:97], v[66:69], v[184:187], v[74:77]
	s_waitcnt lgkmcnt(1)
	v_mfma_f32_16x16x32_bf16 v[74:77], v[188:191], v[2:5], v[102:105]
	v_mfma_f32_16x16x32_bf16 v[78:81], v[188:191], v[14:17], v[98:101]
	s_waitcnt lgkmcnt(0)
	v_mfma_f32_16x16x32_bf16 v[74:77], v[208:211], v[10:13], v[74:77]
	v_mfma_f32_16x16x32_bf16 v[78:81], v[208:211], v[184:187], v[78:81]
	s_setprio 0
	v_add_u32_e32 v98, 0x1c000, v133
	s_barrier
	ds_read_b128 v[196:199], v98
	ds_read_b128 v[200:203], v98 offset:1024
	ds_read_b128 v[204:207], v98 offset:2048
	ds_read_b128 v[228:231], v98 offset:3072
	s_waitcnt vmcnt(0)
	s_barrier
	s_waitcnt lgkmcnt(0)
	s_setprio 1
	s_waitcnt lgkmcnt(3)
	v_mfma_f32_16x16x32_bf16 v[98:101], v[26:29], v[196:199], v[212:215]
	s_waitcnt lgkmcnt(1)
	v_mfma_f32_16x16x32_bf16 v[26:29], v[26:29], v[204:207], v[158:161]
	s_waitcnt lgkmcnt(0)
	v_mfma_f32_16x16x32_bf16 v[118:121], v[30:33], v[228:231], v[26:29]
	v_mfma_f32_16x16x32_bf16 v[26:29], v[42:45], v[196:199], v[86:89]
	v_mfma_f32_16x16x32_bf16 v[114:117], v[30:33], v[200:203], v[98:101]
	v_mfma_f32_16x16x32_bf16 v[98:101], v[46:49], v[200:203], v[26:29]
	v_mfma_f32_16x16x32_bf16 v[26:29], v[42:45], v[204:207], v[82:85]
	v_mfma_f32_16x16x32_bf16 v[102:105], v[46:49], v[228:231], v[26:29]
	v_mfma_f32_16x16x32_bf16 v[26:29], v[58:61], v[196:199], v[164:167]
	v_mfma_f32_16x16x32_bf16 v[82:85], v[66:69], v[200:203], v[26:29]
	v_mfma_f32_16x16x32_bf16 v[26:29], v[58:61], v[204:207], v[168:171]
	v_mfma_f32_16x16x32_bf16 v[86:89], v[66:69], v[228:231], v[26:29]
	v_mfma_f32_16x16x32_bf16 v[26:29], v[188:191], v[196:199], v[70:73]
	v_mfma_f32_16x16x32_bf16 v[66:69], v[208:211], v[200:203], v[26:29]
	v_mfma_f32_16x16x32_bf16 v[26:29], v[188:191], v[204:207], v[172:175]
	v_mfma_f32_16x16x32_bf16 v[70:73], v[208:211], v[228:231], v[26:29]
	s_setprio 0
	s_barrier
	ds_read_b128 v[158:161], v130 offset:49152
	ds_read_b128 v[164:167], v130 offset:50176
	ds_read_b128 v[168:171], v130 offset:51200
	ds_read_b128 v[172:175], v130 offset:52224
	ds_read_b128 v[188:191], v130 offset:53248
	ds_read_b128 v[208:211], v130 offset:54272
	ds_read_b128 v[212:215], v130 offset:55296
	ds_read_b128 v[130:133], v130 offset:56320
	s_barrier
	s_waitcnt lgkmcnt(0)
	s_setprio 1
	s_waitcnt lgkmcnt(7)
	v_mfma_f32_16x16x32_bf16 v[26:29], v[158:161], v[2:5], v[62:65]
	s_waitcnt lgkmcnt(6)
	v_mfma_f32_16x16x32_bf16 v[58:61], v[164:167], v[10:13], v[26:29]
	v_mfma_f32_16x16x32_bf16 v[26:29], v[158:161], v[14:17], v[192:195]
	v_mfma_f32_16x16x32_bf16 v[62:65], v[164:167], v[184:187], v[26:29]
	s_waitcnt lgkmcnt(5)
	v_mfma_f32_16x16x32_bf16 v[26:29], v[168:171], v[2:5], v[54:57]
	s_waitcnt lgkmcnt(4)
	v_mfma_f32_16x16x32_bf16 v[42:45], v[172:175], v[10:13], v[26:29]
	v_mfma_f32_16x16x32_bf16 v[26:29], v[168:171], v[14:17], v[50:53]
	v_mfma_f32_16x16x32_bf16 v[46:49], v[172:175], v[184:187], v[26:29]
	s_waitcnt lgkmcnt(3)
	v_mfma_f32_16x16x32_bf16 v[26:29], v[188:191], v[2:5], v[220:223]
	s_waitcnt lgkmcnt(1)
	v_mfma_f32_16x16x32_bf16 v[2:5], v[212:215], v[2:5], v[38:41]
	v_mfma_f32_16x16x32_bf16 v[26:29], v[208:211], v[10:13], v[26:29]
	v_mfma_f32_16x16x32_bf16 v[30:33], v[188:191], v[14:17], v[224:227]
	s_waitcnt lgkmcnt(0)
	v_mfma_f32_16x16x32_bf16 v[10:13], v[130:133], v[10:13], v[2:5]
	v_mfma_f32_16x16x32_bf16 v[2:5], v[212:215], v[14:17], v[34:37]
	v_mfma_f32_16x16x32_bf16 v[30:33], v[208:211], v[184:187], v[30:33]
	v_mfma_f32_16x16x32_bf16 v[14:17], v[130:133], v[184:187], v[2:5]
	s_setprio 0
	s_setprio 1
	v_mfma_f32_16x16x32_bf16 v[2:5], v[158:161], v[196:199], v[142:145]
	v_mfma_f32_16x16x32_bf16 v[50:53], v[164:167], v[200:203], v[2:5]
	v_mfma_f32_16x16x32_bf16 v[2:5], v[158:161], v[204:207], v[146:149]
	v_mfma_f32_16x16x32_bf16 v[54:57], v[164:167], v[228:231], v[2:5]
	v_mfma_f32_16x16x32_bf16 v[2:5], v[168:171], v[196:199], v[22:25]
	v_mfma_f32_16x16x32_bf16 v[34:37], v[172:175], v[200:203], v[2:5]
	v_mfma_f32_16x16x32_bf16 v[2:5], v[168:171], v[204:207], v[18:21]
	v_mfma_f32_16x16x32_bf16 v[38:41], v[172:175], v[228:231], v[2:5]
	v_mfma_f32_16x16x32_bf16 v[2:5], v[188:191], v[196:199], v[150:153]
	v_mfma_f32_16x16x32_bf16 v[18:21], v[208:211], v[200:203], v[2:5]
	v_mfma_f32_16x16x32_bf16 v[2:5], v[188:191], v[204:207], v[154:157]
	v_mfma_f32_16x16x32_bf16 v[22:25], v[208:211], v[228:231], v[2:5]
	v_mfma_f32_16x16x32_bf16 v[2:5], v[212:215], v[196:199], v[6:9]
	v_mfma_f32_16x16x32_bf16 v[6:9], v[212:215], v[204:207], v[180:183]
	v_mfma_f32_16x16x32_bf16 v[2:5], v[130:133], v[200:203], v[2:5]
	v_mfma_f32_16x16x32_bf16 v[6:9], v[130:133], v[228:231], v[6:9]
	s_setprio 0
	s_movk_i32 s3, 0x100
	v_cmp_gt_u32_e32 vcc, s3, v0
	s_barrier
	s_and_saveexec_b64 s[6:7], vcc
	s_cbranch_execz .LBB0_586
	s_barrier

; #define WAIT_L(n) asm volatile("s_waitcnt lgkmcnt(" #n ")" ::: "memory")
; #define BAR __builtin_amdgcn_s_barrier()
; #define SCHED __builtin_amdgcn_sched_barrier(0)
; #define STG_A(b, h, kt) stage_half_s(lds0 + ((b) * 2 + (h)) * HT_B, ((h) ? A1 : Ap) + (kt) * BK, off0, off1)
; #define STG_B(b, h, kt) stage_half_s(lds0 + (4 + (b) * 2 + (h)) * HT_B, ((h) ? B1p : Bp) + (kt) * BK, off0, off1)
; #define STG_A(b, h, kt) stage_half_s(lds0 + ((b) * 2 + (h)) * HT_B, ((h) ? A1 : Ap) + (kt) * BK, off0, off1)
; #define STG_B(b, h, kt) stage_half_s(lds0 + (4 + (b) * 2 + (h)) * HT_B, ((h) ? B1p : Bp) + (kt) * BK, off0, off1)
; #define LDA8(b, h) _Pragma("unroll") for (int m = 0; m < 4; ++m) _Pragma("unroll") for (int k = 0; k < 2; ++k) \
;     At[m][k] = *(const bf16x8*)(SA_(shm, b, h) + abase + (m * 2 + k) * 1024)
; template <bool HS>
; __device__ __forceinline__ void gemm_tile8(const u16* __restrict__ Ap, const u16* __restrict__ Bp, int K,
;                                            f32x4 (&acc)[2][2][4][2], char* shm, const int tid, const float* hsr = nullptr) {
;   const int wid = tid >> 6, lane = tid & 63, wr = wid >> 2, wc = wid & 3, fr = lane & 15, fq = lane >> 4;
;   int r0, c0, r1, c1;
;   stage_rc(tid * 16, r0, c0);
;   stage_rc(tid * 16 + 8192, r1, c1);
;   const unsigned off0 = (unsigned)(r0 * K + c0) * 2u, off1 = (unsigned)(r1 * K + c1) * 2u;
;   const int wvoff = __builtin_amdgcn_readfirstlane(tid >> 6) * 1024;
;   const u16* A1 = Ap + (size_t)128 * K;
;   const u16* B1p = Bp + (size_t)128 * K;
; #pragma unroll
;   for (int a = 0; a < 2; ++a)
; #pragma unroll
;     for (int b = 0; b < 2; ++b)
; #pragma unroll
;       for (int m = 0; m < 4; ++m)
; #pragma unroll
;         for (int n = 0; n < 2; ++n) acc[a][b][m][n] = f32x4{0.f, 0.f, 0.f, 0.f};
;   const int abase = lds_byte(wr * 64 + fr, fq * 8), bbase = lds_byte(wc * 32 + fr, fq * 8);
;   bf16x8 At[4][2], B0[2][2], B1[2][2];
;   const unsigned lds0 = (unsigned)(size_t)(__attribute__((address_space(3))) char*)shm + (unsigned)wvoff;
;     ...
;     LDB8(B0, 0, 0); SCHED; LDA8(0, 0); STG_A(1, 1, t + 1);
;     WAIT_L(8); BAR; WAIT_L(0); MMA8(0, 0, B0); BAR; SCHED;
;     LDB8(B1, 0, 1); STG_B(0, 0, t + 2);
;     BAR; WAIT_L(0); MMA8(0, 1, B1); BAR;
.LBB0_650:
	s_or_b64 exec, exec, s[0:1]
	v_bfe_i32 v6, v0, 27, 1
	v_lshlrev_b32_e32 v4, 4, v0
	v_lshrrev_b32_e32 v6, 22, v6
	v_add_u32_e32 v6, v4, v6
	v_and_b32_e32 v6, 0xfffffc00, v6
	v_ashrrev_i32_e32 v5, 31, v0
	v_sub_u32_e32 v6, v4, v6
	v_lshrrev_b32_e32 v5, 26, v5
	v_lshrrev_b32_e32 v7, 4, v6
	v_add_u32_e32 v5, v0, v5
	v_bitop3_b32 v7, v7, v6, 32 bitop3:0x6c
	v_ashrrev_i32_e32 v6, 31, v6
	v_ashrrev_i32_e32 v5, 6, v5
	v_lshrrev_b32_e32 v6, 26, v6
	v_lshlrev_b32_e32 v8, 3, v5
	v_add_u32_e32 v6, v7, v6
	v_and_b32_e32 v8, 0xfffff0, v8
	v_ashrrev_i32_e32 v6, 6, v6
	v_add_u32_e32 v8, v6, v8
	v_mul_i32_i24_e32 v6, 64, v6
	v_add_u32_e32 v4, 0x2000, v4
	v_sub_u32_e32 v6, v7, v6
	v_ashrrev_i32_e32 v7, 31, v4
	v_lshrrev_b32_e32 v7, 22, v7
	v_add_u32_e32 v7, v4, v7
	v_ashrrev_i32_e32 v7, 10, v7
	v_mul_i32_i24_e32 v9, 0x400, v7
	v_sub_u32_e32 v4, v4, v9
	v_lshrrev_b32_e32 v9, 4, v4
	s_ashr_i32 s5, s4, 31
	s_mul_i32 s1, s4, 0x1600
	v_bitop3_b32 v4, v9, v4, 32 bitop3:0x6c
	s_mul_hi_i32 s0, s4, 0x1600
	s_add_u32 s3, s90, s1
	v_ashrrev_i32_e32 v10, 31, v4
	s_addc_u32 s8, s91, s0
	s_mul_i32 s0, s10, 0x160000
	v_lshrrev_b32_e32 v10, 26, v10
	s_ashr_i32 s1, s0, 31
	v_lshlrev_b32_e32 v9, 3, v7
	v_add_u32_e32 v10, v4, v10
	v_lshl_add_u64 v[130:131], v[146:147], 0, s[0:1]
	v_and_b32_e32 v9, 0xfffff0, v9
	v_lshrrev_b32_e32 v11, 6, v10
	v_and_b32_e32 v10, 0xc0, v10
	s_movk_i32 s0, 0xb00
	v_lshlrev_b32_e32 v5, 5, v5
	v_add_u32_e32 v9, v11, v9
	v_sub_u32_e32 v4, v4, v10
	v_mul_lo_u32 v8, v8, s0
	v_lshlrev_b32_e32 v7, 5, v7
	v_ashrrev_i16_sdwa v4, v178, sext(v4) dst_sel:DWORD dst_unused:UNUSED_PAD src0_sel:DWORD src1_sel:BYTE_0
	v_and_or_b32 v5, v5, 32, v8
	v_mul_lo_u32 v8, v9, s0
	v_ashrrev_i16_sdwa v6, v178, sext(v6) dst_sel:DWORD dst_unused:UNUSED_PAD src0_sel:DWORD src1_sel:BYTE_0
	v_bfe_i32 v4, v4, 0, 16
	v_and_or_b32 v7, v7, 32, v8
	v_bfe_i32 v6, v6, 0, 16
	s_add_u32 s9, s3, 0xb0000
	v_and_b32_e32 v8, 15, v0
	v_add_lshl_u32 v135, v7, v4, 1
	v_lshlrev_b32_e32 v7, 2, v0
	s_addc_u32 s11, s8, 0
	v_add_lshl_u32 v136, v5, v6, 1
	s_lshl_b32 s12, s12, 10
	s_mov_b64 s[0:1], 0xb0000
	v_and_b32_e32 v4, 48, v0
	v_lshlrev_b32_e32 v5, 6, v8
	v_and_b32_e32 v7, 32, v7
	v_lshl_add_u64 v[132:133], v[130:131], 0, s[0:1]
	v_or_b32_e32 v6, v5, v4
	v_lshlrev_b32_e32 v3, 13, v3
	v_bitop3_b32 v4, v5, v7, v4 bitop3:0x36
	v_lshlrev_b32_e32 v2, 12, v2
	s_movk_i32 s0, 0x3000
	s_add_i32 s13, s12, 0
	v_bitop3_b32 v3, v6, v3, v7 bitop3:0xde
	v_and_or_b32 v137, v2, s0, v4
	s_add_u32 s14, s3, 0xb0100
	v_mov_b32_e32 v2, 0
	s_addc_u32 s15, s8, 0
	s_mov_b32 s16, -2
	s_mov_b64 s[0:1], 0
	v_add_u32_e32 v134, 0, v3
	s_waitcnt lgkmcnt(0)
	v_readfirstlane_b32 s22, v130
	v_readfirstlane_b32 s23, v131
	v_readfirstlane_b32 s18, v132
	v_readfirstlane_b32 s19, v133
	s_barrier
	s_barrier
	v_add_u32_e32 v164, 0x10000, v137
	ds_read_b128 v[138:141], v164
	ds_read_b128 v[142:145], v164 offset:1024
	ds_read_b128 v[156:159], v164 offset:2048
	ds_read_b128 v[164:167], v164 offset:3072
	ds_read_b128 v[168:171], v134
	ds_read_b128 v[172:175], v134 offset:1024
	ds_read_b128 v[180:183], v134 offset:2048
	ds_read_b128 v[184:187], v134 offset:3072
	ds_read_b128 v[188:191], v134 offset:4096
	ds_read_b128 v[192:195], v134 offset:5120
	ds_read_b128 v[196:199], v134 offset:6144
	ds_read_b128 v[200:203], v134 offset:7168
	v_add_u32_e32 v220, 0x14000, v137
	ds_read_b128 v[204:207], v220
	ds_read_b128 v[208:211], v220 offset:1024
	ds_read_b128 v[212:215], v220 offset:2048
	ds_read_b128 v[220:223], v220 offset:3072
	s_add_u32 s20, s9, s0
	s_addc_u32 s21, s11, s1
	s_add_u32 s20, s20, 0x80
	s_addc_u32 s21, s21, 0
	s_add_i32 s17, s13, 0xc000
	s_mov_b32 m0, s17
	s_nop 0
	global_load_lds_dwordx4 v136, s[20:21]
	s_add_i32 s17, s13, 0xe000
	s_mov_b32 m0, s17
	s_nop 0
	global_load_lds_dwordx4 v135, s[20:21]
	s_waitcnt vmcnt(8) lgkmcnt(0)
	s_barrier
	s_setprio 1
	v_mfma_f32_16x16x32_bf16 v[126:129], v[168:171], v[138:141], 0
	v_mfma_f32_16x16x32_bf16 v[122:125], v[168:171], v[156:159], 0
	v_mfma_f32_16x16x32_bf16 v[118:121], v[180:183], v[138:141], 0
	v_mfma_f32_16x16x32_bf16 v[114:117], v[180:183], v[156:159], 0
	v_mfma_f32_16x16x32_bf16 v[110:113], v[188:191], v[138:141], 0
	v_mfma_f32_16x16x32_bf16 v[106:109], v[188:191], v[156:159], 0
	v_mfma_f32_16x16x32_bf16 v[102:105], v[196:199], v[138:141], 0
	v_mfma_f32_16x16x32_bf16 v[98:101], v[196:199], v[156:159], 0
	v_mfma_f32_16x16x32_bf16 v[126:129], v[172:175], v[142:145], v[126:129]
	v_mfma_f32_16x16x32_bf16 v[122:125], v[172:175], v[164:167], v[122:125]
	v_mfma_f32_16x16x32_bf16 v[118:121], v[184:187], v[142:145], v[118:121]
	v_mfma_f32_16x16x32_bf16 v[114:117], v[184:187], v[164:167], v[114:117]
	v_mfma_f32_16x16x32_bf16 v[110:113], v[192:195], v[142:145], v[110:113]
	v_mfma_f32_16x16x32_bf16 v[106:109], v[192:195], v[164:167], v[106:109]
	v_mfma_f32_16x16x32_bf16 v[102:105], v[200:203], v[142:145], v[102:105]
	v_mfma_f32_16x16x32_bf16 v[98:101], v[200:203], v[164:167], v[98:101]
	v_mfma_f32_16x16x32_bf16 v[94:97], v[168:171], v[204:207], 0
	v_mfma_f32_16x16x32_bf16 v[90:93], v[168:171], v[212:215], 0
	v_mfma_f32_16x16x32_bf16 v[86:89], v[180:183], v[204:207], 0
	v_mfma_f32_16x16x32_bf16 v[82:85], v[180:183], v[212:215], 0
	v_mfma_f32_16x16x32_bf16 v[78:81], v[188:191], v[204:207], 0
	v_mfma_f32_16x16x32_bf16 v[74:77], v[188:191], v[212:215], 0
	v_mfma_f32_16x16x32_bf16 v[70:73], v[196:199], v[204:207], 0
	v_mfma_f32_16x16x32_bf16 v[66:69], v[196:199], v[212:215], 0
	v_mfma_f32_16x16x32_bf16 v[94:97], v[172:175], v[208:211], v[94:97]
	v_mfma_f32_16x16x32_bf16 v[90:93], v[172:175], v[220:223], v[90:93]
	v_mfma_f32_16x16x32_bf16 v[86:89], v[184:187], v[208:211], v[86:89]
	v_mfma_f32_16x16x32_bf16 v[82:85], v[184:187], v[220:223], v[82:85]
	v_mfma_f32_16x16x32_bf16 v[78:81], v[192:195], v[208:211], v[78:81]
	v_mfma_f32_16x16x32_bf16 v[74:77], v[192:195], v[220:223], v[74:77]
	v_mfma_f32_16x16x32_bf16 v[70:73], v[200:203], v[208:211], v[70:73]
	v_mfma_f32_16x16x32_bf16 v[66:69], v[200:203], v[220:223], v[66:69]
	s_setprio 0
	s_barrier
; #define WAIT_V(n) asm volatile("s_waitcnt vmcnt(" #n ")" ::: "memory")
; #define WAIT_L(n) asm volatile("s_waitcnt lgkmcnt(" #n ")" ::: "memory")
; #define BAR __builtin_amdgcn_s_barrier()
; #define SCHED __builtin_amdgcn_sched_barrier(0)
; #define STG_A(b, h, kt) stage_half_s(lds0 + ((b) * 2 + (h)) * HT_B, ((h) ? A1 : Ap) + (kt) * BK, off0, off1)
; #define STG_B(b, h, kt) stage_half_s(lds0 + (4 + (b) * 2 + (h)) * HT_B, ((h) ? B1p : Bp) + (kt) * BK, off0, off1)
; #define STG_A(b, h, kt) stage_half_s(lds0 + ((b) * 2 + (h)) * HT_B, ((h) ? A1 : Ap) + (kt) * BK, off0, off1)
; #define STG_B(b, h, kt) stage_half_s(lds0 + (4 + (b) * 2 + (h)) * HT_B, ((h) ? B1p : Bp) + (kt) * BK, off0, off1)
; #define LDA8(b, h) _Pragma("unroll") for (int m = 0; m < 4; ++m) _Pragma("unroll") for (int k = 0; k < 2; ++k) \
;     At[m][k] = *(const bf16x8*)(SA_(shm, b, h) + abase + (m * 2 + k) * 1024)
; #define LDB8(dst, b, h) _Pragma("unroll") for (int n = 0; n < 2; ++n) _Pragma("unroll") for (int k = 0; k < 2; ++k) \
;     dst[n][k] = *(const bf16x8*)(SB_(shm, b, h) + bbase + (n * 2 + k) * 1024)
; #define MMA8(ai, bj, Bx) do { __builtin_amdgcn_s_setprio(1); \
;     _Pragma("unroll") for (int m = 0; m < 4; ++m) _Pragma("unroll") for (int n = 0; n < 2; ++n) _Pragma("unroll") for (int k = 0; k < 2; ++k) \
;       acc[ai][bj][m][n] = __builtin_amdgcn_mfma_f32_16x16x32_bf16(At[m][k], Bx[n][k], acc[ai][bj][m][n], 0, 0, 0); \
;     __builtin_amdgcn_s_setprio(0); } while (0)
; template <bool HS>
; __device__ __forceinline__ void gemm_tile8(const u16* __restrict__ Ap, const u16* __restrict__ Bp, int K,
;                                            f32x4 (&acc)[2][2][4][2], char* shm, const int tid, const float* hsr = nullptr) {
;     ...
;     BAR; WAIT_L(0); MMA8(0, 1, B1); BAR;
;     LDA8(0, 1); STG_A(0, 0, t + 2);
;     BAR; WAIT_L(0); MMA8(1, 0, B0); BAR; SCHED;
;     STG_B(0, 1, t + 2);
;     WAIT_V(6); BAR; MMA8(1, 1, B1); BAR;
;     LDB8(B0, 1, 0); SCHED; LDA8(1, 0); STG_A(0, 1, t + 2);
;     WAIT_L(8); BAR; WAIT_L(0); MMA8(0, 0, B0); BAR; SCHED;
	ds_read_b128 v[168:171], v134 offset:16384
	ds_read_b128 v[172:175], v134 offset:17408
	ds_read_b128 v[180:183], v134 offset:18432
	ds_read_b128 v[184:187], v134 offset:19456
	ds_read_b128 v[188:191], v134 offset:20480
	ds_read_b128 v[192:195], v134 offset:21504
	ds_read_b128 v[196:199], v134 offset:22528
	ds_read_b128 v[200:203], v134 offset:23552
	s_add_u32 s20, s22, s0
	s_addc_u32 s21, s23, s1
	s_add_u32 s20, s20, 0x100
	s_addc_u32 s21, s21, 0
	s_add_i32 s17, s13, 0x10000
	s_mov_b32 m0, s17
	s_nop 0
	global_load_lds_dwordx4 v136, s[20:21]
	s_add_i32 s17, s13, 0x12000
	s_mov_b32 m0, s17
	s_nop 0
	global_load_lds_dwordx4 v135, s[20:21]
	s_add_u32 s20, s3, s0
	s_addc_u32 s21, s8, s1
	s_add_u32 s20, s20, 0x100
	s_addc_u32 s21, s21, 0
	s_mov_b32 m0, s13
	s_nop 0
	global_load_lds_dwordx4 v136, s[20:21]
	s_add_i32 s17, s13, 0x2000
	s_mov_b32 m0, s17
	s_nop 0
	global_load_lds_dwordx4 v135, s[20:21]
	s_add_u32 s20, s18, s0
	s_addc_u32 s21, s19, s1
	s_add_u32 s20, s20, 0x100
	s_addc_u32 s21, s21, 0
	s_add_i32 s17, s13, 0x14000
	s_mov_b32 m0, s17
	s_nop 0
	global_load_lds_dwordx4 v136, s[20:21]
	s_add_i32 s17, s13, 0x16000
	s_mov_b32 m0, s17
	s_nop 0
	global_load_lds_dwordx4 v135, s[20:21]
	s_waitcnt vmcnt(8) lgkmcnt(0)
	s_barrier
	s_setprio 1
	v_mfma_f32_16x16x32_bf16 v[62:65], v[168:171], v[138:141], 0
	v_mfma_f32_16x16x32_bf16 v[58:61], v[168:171], v[156:159], 0
	v_mfma_f32_16x16x32_bf16 v[54:57], v[180:183], v[138:141], 0
	v_mfma_f32_16x16x32_bf16 v[50:53], v[180:183], v[156:159], 0
	v_mfma_f32_16x16x32_bf16 v[46:49], v[188:191], v[138:141], 0
	v_mfma_f32_16x16x32_bf16 v[42:45], v[188:191], v[156:159], 0
	v_mfma_f32_16x16x32_bf16 v[38:41], v[196:199], v[138:141], 0
	v_mfma_f32_16x16x32_bf16 v[34:37], v[196:199], v[156:159], 0
	v_mfma_f32_16x16x32_bf16 v[62:65], v[172:175], v[142:145], v[62:65]
	v_mfma_f32_16x16x32_bf16 v[58:61], v[172:175], v[164:167], v[58:61]
	v_mfma_f32_16x16x32_bf16 v[54:57], v[184:187], v[142:145], v[54:57]
	v_mfma_f32_16x16x32_bf16 v[50:53], v[184:187], v[164:167], v[50:53]
	v_mfma_f32_16x16x32_bf16 v[46:49], v[192:195], v[142:145], v[46:49]
	v_mfma_f32_16x16x32_bf16 v[42:45], v[192:195], v[164:167], v[42:45]
	v_mfma_f32_16x16x32_bf16 v[38:41], v[200:203], v[142:145], v[38:41]
	v_mfma_f32_16x16x32_bf16 v[34:37], v[200:203], v[164:167], v[34:37]
	v_mfma_f32_16x16x32_bf16 v[30:33], v[168:171], v[204:207], 0
	v_mfma_f32_16x16x32_bf16 v[26:29], v[168:171], v[212:215], 0
	v_mfma_f32_16x16x32_bf16 v[22:25], v[180:183], v[204:207], 0
	v_mfma_f32_16x16x32_bf16 v[18:21], v[180:183], v[212:215], 0
	v_mfma_f32_16x16x32_bf16 v[14:17], v[188:191], v[204:207], 0
	v_mfma_f32_16x16x32_bf16 v[10:13], v[188:191], v[212:215], 0
	v_mfma_f32_16x16x32_bf16 v[6:9], v[196:199], v[204:207], 0
	v_mfma_f32_16x16x32_bf16 v[2:5], v[196:199], v[212:215], 0
	v_mfma_f32_16x16x32_bf16 v[30:33], v[172:175], v[208:211], v[30:33]
	v_mfma_f32_16x16x32_bf16 v[26:29], v[172:175], v[220:223], v[26:29]
	v_mfma_f32_16x16x32_bf16 v[22:25], v[184:187], v[208:211], v[22:25]
	v_mfma_f32_16x16x32_bf16 v[18:21], v[184:187], v[220:223], v[18:21]
	v_mfma_f32_16x16x32_bf16 v[14:17], v[192:195], v[208:211], v[14:17]
	v_mfma_f32_16x16x32_bf16 v[10:13], v[192:195], v[220:223], v[10:13]
	v_mfma_f32_16x16x32_bf16 v[6:9], v[200:203], v[208:211], v[6:9]
	v_mfma_f32_16x16x32_bf16 v[2:5], v[200:203], v[220:223], v[2:5]
	s_setprio 0
	s_barrier
	v_add_u32_e32 v164, 0x18000, v137
	ds_read_b128 v[138:141], v164
	ds_read_b128 v[142:145], v164 offset:1024
	ds_read_b128 v[156:159], v164 offset:2048
	ds_read_b128 v[164:167], v164 offset:3072
	ds_read_b128 v[168:171], v134 offset:32768
	ds_read_b128 v[172:175], v134 offset:33792
	ds_read_b128 v[180:183], v134 offset:34816
	ds_read_b128 v[184:187], v134 offset:35840
	ds_read_b128 v[188:191], v134 offset:36864
	ds_read_b128 v[192:195], v134 offset:37888
	ds_read_b128 v[196:199], v134 offset:38912
	ds_read_b128 v[200:203], v134 offset:39936
	v_add_u32_e32 v220, 0x1c000, v137
	ds_read_b128 v[204:207], v220
	ds_read_b128 v[208:211], v220 offset:1024
	ds_read_b128 v[212:215], v220 offset:2048
	ds_read_b128 v[220:223], v220 offset:3072
	s_add_u32 s20, s9, s0
	s_addc_u32 s21, s11, s1
	s_add_u32 s20, s20, 0x100
	s_addc_u32 s21, s21, 0
	s_add_i32 s17, s13, 0x4000
	s_mov_b32 m0, s17
	s_nop 0
	global_load_lds_dwordx4 v136, s[20:21]
	s_add_i32 s17, s13, 0x6000
	s_mov_b32 m0, s17
	s_nop 0
	global_load_lds_dwordx4 v135, s[20:21]
	s_waitcnt vmcnt(8) lgkmcnt(0)
	s_barrier
; #define WAIT_V(n) asm volatile("s_waitcnt vmcnt(" #n ")" ::: "memory")
; #define WAIT_L(n) asm volatile("s_waitcnt lgkmcnt(" #n ")" ::: "memory")
; #define BAR __builtin_amdgcn_s_barrier()
; #define SCHED __builtin_amdgcn_sched_barrier(0)
; #define STG_A(b, h, kt) stage_half_s(lds0 + ((b) * 2 + (h)) * HT_B, ((h) ? A1 : Ap) + (kt) * BK, off0, off1)
; #define STG_B(b, h, kt) stage_half_s(lds0 + (4 + (b) * 2 + (h)) * HT_B, ((h) ? B1p : Bp) + (kt) * BK, off0, off1)
; #define STG_A(b, h, kt) stage_half_s(lds0 + ((b) * 2 + (h)) * HT_B, ((h) ? A1 : Ap) + (kt) * BK, off0, off1)
; #define STG_B(b, h, kt) stage_half_s(lds0 + (4 + (b) * 2 + (h)) * HT_B, ((h) ? B1p : Bp) + (kt) * BK, off0, off1)
; #define LDA8(b, h) _Pragma("unroll") for (int m = 0; m < 4; ++m) _Pragma("unroll") for (int k = 0; k < 2; ++k) \
;     At[m][k] = *(const bf16x8*)(SA_(shm, b, h) + abase + (m * 2 + k) * 1024)
; #define LDB8(dst, b, h) _Pragma("unroll") for (int n = 0; n < 2; ++n) _Pragma("unroll") for (int k = 0; k < 2; ++k) \
;     dst[n][k] = *(const bf16x8*)(SB_(shm, b, h) + bbase + (n * 2 + k) * 1024)
; #define MMA8(ai, bj, Bx) do { __builtin_amdgcn_s_setprio(1); \
;     _Pragma("unroll") for (int m = 0; m < 4; ++m) _Pragma("unroll") for (int n = 0; n < 2; ++n) _Pragma("unroll") for (int k = 0; k < 2; ++k) \
;       acc[ai][bj][m][n] = __builtin_amdgcn_mfma_f32_16x16x32_bf16(At[m][k], Bx[n][k], acc[ai][bj][m][n], 0, 0, 0); \
;     __builtin_amdgcn_s_setprio(0); } while (0)
; template <bool HS>
; __device__ __forceinline__ void gemm_tile8(const u16* __restrict__ Ap, const u16* __restrict__ Bp, int K,
;                                            f32x4 (&acc)[2][2][4][2], char* shm, const int tid, const float* hsr = nullptr) {
;     ...
;     WAIT_L(8); BAR; WAIT_L(0); MMA8(0, 0, B0); BAR; SCHED;
;     LDB8(B1, 1, 1); STG_B(1, 0, t + 3);
;     BAR; WAIT_L(0); MMA8(0, 1, B1); BAR;
;     LDA8(1, 1); STG_A(1, 0, t + 3);
;     BAR; WAIT_L(0); MMA8(1, 0, B0); BAR; SCHED;
;     STG_B(1, 1, t + 3);
;     WAIT_V(6); BAR; MMA8(1, 1, B1); BAR;
;   }
	s_setprio 1
	v_mfma_f32_16x16x32_bf16 v[126:129], v[168:171], v[138:141], v[126:129]
	v_mfma_f32_16x16x32_bf16 v[122:125], v[168:171], v[156:159], v[122:125]
	v_mfma_f32_16x16x32_bf16 v[118:121], v[180:183], v[138:141], v[118:121]
	v_mfma_f32_16x16x32_bf16 v[114:117], v[180:183], v[156:159], v[114:117]
	v_mfma_f32_16x16x32_bf16 v[110:113], v[188:191], v[138:141], v[110:113]
	v_mfma_f32_16x16x32_bf16 v[106:109], v[188:191], v[156:159], v[106:109]
	v_mfma_f32_16x16x32_bf16 v[102:105], v[196:199], v[138:141], v[102:105]
	v_mfma_f32_16x16x32_bf16 v[98:101], v[196:199], v[156:159], v[98:101]
	v_mfma_f32_16x16x32_bf16 v[126:129], v[172:175], v[142:145], v[126:129]
	v_mfma_f32_16x16x32_bf16 v[122:125], v[172:175], v[164:167], v[122:125]
	v_mfma_f32_16x16x32_bf16 v[118:121], v[184:187], v[142:145], v[118:121]
	v_mfma_f32_16x16x32_bf16 v[114:117], v[184:187], v[164:167], v[114:117]
	v_mfma_f32_16x16x32_bf16 v[110:113], v[192:195], v[142:145], v[110:113]
	v_mfma_f32_16x16x32_bf16 v[106:109], v[192:195], v[164:167], v[106:109]
	v_mfma_f32_16x16x32_bf16 v[102:105], v[200:203], v[142:145], v[102:105]
	v_mfma_f32_16x16x32_bf16 v[98:101], v[200:203], v[164:167], v[98:101]
	v_mfma_f32_16x16x32_bf16 v[94:97], v[168:171], v[204:207], v[94:97]
	v_mfma_f32_16x16x32_bf16 v[90:93], v[168:171], v[212:215], v[90:93]
	v_mfma_f32_16x16x32_bf16 v[86:89], v[180:183], v[204:207], v[86:89]
	v_mfma_f32_16x16x32_bf16 v[82:85], v[180:183], v[212:215], v[82:85]
	v_mfma_f32_16x16x32_bf16 v[78:81], v[188:191], v[204:207], v[78:81]
	v_mfma_f32_16x16x32_bf16 v[74:77], v[188:191], v[212:215], v[74:77]
	v_mfma_f32_16x16x32_bf16 v[70:73], v[196:199], v[204:207], v[70:73]
	v_mfma_f32_16x16x32_bf16 v[66:69], v[196:199], v[212:215], v[66:69]
	v_mfma_f32_16x16x32_bf16 v[94:97], v[172:175], v[208:211], v[94:97]
	v_mfma_f32_16x16x32_bf16 v[90:93], v[172:175], v[220:223], v[90:93]
	v_mfma_f32_16x16x32_bf16 v[86:89], v[184:187], v[208:211], v[86:89]
	v_mfma_f32_16x16x32_bf16 v[82:85], v[184:187], v[220:223], v[82:85]
	v_mfma_f32_16x16x32_bf16 v[78:81], v[192:195], v[208:211], v[78:81]
	v_mfma_f32_16x16x32_bf16 v[74:77], v[192:195], v[220:223], v[74:77]
	v_mfma_f32_16x16x32_bf16 v[70:73], v[200:203], v[208:211], v[70:73]
	v_mfma_f32_16x16x32_bf16 v[66:69], v[200:203], v[220:223], v[66:69]
	s_setprio 0
	s_barrier
	ds_read_b128 v[168:171], v134 offset:49152
	ds_read_b128 v[172:175], v134 offset:50176
	ds_read_b128 v[180:183], v134 offset:51200
	ds_read_b128 v[184:187], v134 offset:52224
	ds_read_b128 v[188:191], v134 offset:53248
	ds_read_b128 v[192:195], v134 offset:54272
	ds_read_b128 v[196:199], v134 offset:55296
	ds_read_b128 v[200:203], v134 offset:56320
	s_add_u32 s20, s22, s0
	s_addc_u32 s21, s23, s1
	s_add_u32 s20, s20, 0x180
	s_addc_u32 s21, s21, 0
	s_add_i32 s17, s13, 0x18000
	s_mov_b32 m0, s17
	s_nop 0
	global_load_lds_dwordx4 v136, s[20:21]
	s_add_i32 s17, s13, 0x1a000
	s_mov_b32 m0, s17
	s_nop 0
	global_load_lds_dwordx4 v135, s[20:21]
	s_add_u32 s20, s3, s0
	s_addc_u32 s21, s8, s1
	s_add_u32 s20, s20, 0x180
	s_addc_u32 s21, s21, 0
	s_add_i32 s17, s13, 0x8000
	s_mov_b32 m0, s17
	s_nop 0
	global_load_lds_dwordx4 v136, s[20:21]
	s_add_i32 s17, s13, 0xa000
	s_mov_b32 m0, s17
	s_nop 0
	global_load_lds_dwordx4 v135, s[20:21]
	s_add_u32 s20, s18, s0
	s_addc_u32 s21, s19, s1
	s_add_u32 s20, s20, 0x180
	s_addc_u32 s21, s21, 0
	s_add_i32 s17, s13, 0x1c000
	s_mov_b32 m0, s17
	s_nop 0
	global_load_lds_dwordx4 v136, s[20:21]
	s_add_i32 s17, s13, 0x1e000
	s_mov_b32 m0, s17
	s_nop 0
	global_load_lds_dwordx4 v135, s[20:21]
	s_waitcnt vmcnt(8) lgkmcnt(0)
	s_barrier
	s_setprio 1
	v_mfma_f32_16x16x32_bf16 v[62:65], v[168:171], v[138:141], v[62:65]
	v_mfma_f32_16x16x32_bf16 v[58:61], v[168:171], v[156:159], v[58:61]
	v_mfma_f32_16x16x32_bf16 v[54:57], v[180:183], v[138:141], v[54:57]
	v_mfma_f32_16x16x32_bf16 v[50:53], v[180:183], v[156:159], v[50:53]
	v_mfma_f32_16x16x32_bf16 v[46:49], v[188:191], v[138:141], v[46:49]
	v_mfma_f32_16x16x32_bf16 v[42:45], v[188:191], v[156:159], v[42:45]
	v_mfma_f32_16x16x32_bf16 v[38:41], v[196:199], v[138:141], v[38:41]
	v_mfma_f32_16x16x32_bf16 v[34:37], v[196:199], v[156:159], v[34:37]
	v_mfma_f32_16x16x32_bf16 v[62:65], v[172:175], v[142:145], v[62:65]
	v_mfma_f32_16x16x32_bf16 v[58:61], v[172:175], v[164:167], v[58:61]
	v_mfma_f32_16x16x32_bf16 v[54:57], v[184:187], v[142:145], v[54:57]
	v_mfma_f32_16x16x32_bf16 v[50:53], v[184:187], v[164:167], v[50:53]
	v_mfma_f32_16x16x32_bf16 v[46:49], v[192:195], v[142:145], v[46:49]
	v_mfma_f32_16x16x32_bf16 v[42:45], v[192:195], v[164:167], v[42:45]
	v_mfma_f32_16x16x32_bf16 v[38:41], v[200:203], v[142:145], v[38:41]
	v_mfma_f32_16x16x32_bf16 v[34:37], v[200:203], v[164:167], v[34:37]
	v_mfma_f32_16x16x32_bf16 v[30:33], v[168:171], v[204:207], v[30:33]
	v_mfma_f32_16x16x32_bf16 v[26:29], v[168:171], v[212:215], v[26:29]
	v_mfma_f32_16x16x32_bf16 v[22:25], v[180:183], v[204:207], v[22:25]
	v_mfma_f32_16x16x32_bf16 v[18:21], v[180:183], v[212:215], v[18:21]
	v_mfma_f32_16x16x32_bf16 v[14:17], v[188:191], v[204:207], v[14:17]
	v_mfma_f32_16x16x32_bf16 v[10:13], v[188:191], v[212:215], v[10:13]
	v_mfma_f32_16x16x32_bf16 v[6:9], v[196:199], v[204:207], v[6:9]
	v_mfma_f32_16x16x32_bf16 v[2:5], v[196:199], v[212:215], v[2:5]
	v_mfma_f32_16x16x32_bf16 v[30:33], v[172:175], v[208:211], v[30:33]
	v_mfma_f32_16x16x32_bf16 v[26:29], v[172:175], v[220:223], v[26:29]
	v_mfma_f32_16x16x32_bf16 v[22:25], v[184:187], v[208:211], v[22:25]
	v_mfma_f32_16x16x32_bf16 v[18:21], v[184:187], v[220:223], v[18:21]
	v_mfma_f32_16x16x32_bf16 v[14:17], v[192:195], v[208:211], v[14:17]
	v_mfma_f32_16x16x32_bf16 v[10:13], v[192:195], v[220:223], v[10:13]
	v_mfma_f32_16x16x32_bf16 v[6:9], v[200:203], v[208:211], v[6:9]
	v_mfma_f32_16x16x32_bf16 v[2:5], v[200:203], v[220:223], v[2:5]
	s_setprio 0
	s_add_i32 s16, s16, 2
	s_add_u32 s0, s0, 0x100
	s_addc_u32 s1, s1, 0
	s_cmp_lt_u32 s16, 40
	s_barrier
	s_cbranch_scc0 .Lk_ffn_out_exit

; #define WAIT_V(n) asm volatile("s_waitcnt vmcnt(" #n ")" ::: "memory")
; #define WAIT_L(n) asm volatile("s_waitcnt lgkmcnt(" #n ")" ::: "memory")
; #define BAR __builtin_amdgcn_s_barrier()
; #define STG_A(b, h, kt) stage_half_s(lds0 + ((b) * 2 + (h)) * HT_B, ((h) ? A1 : Ap) + (kt) * BK, off0, off1)
; #define STG_A(b, h, kt) stage_half_s(lds0 + ((b) * 2 + (h)) * HT_B, ((h) ? A1 : Ap) + (kt) * BK, off0, off1)
; #define LDA8(b, h) _Pragma("unroll") for (int m = 0; m < 4; ++m) _Pragma("unroll") for (int k = 0; k < 2; ++k) \
;     At[m][k] = *(const bf16x8*)(SA_(shm, b, h) + abase + (m * 2 + k) * 1024)
; #define LDB8(dst, b, h) _Pragma("unroll") for (int n = 0; n < 2; ++n) _Pragma("unroll") for (int k = 0; k < 2; ++k) \
;     dst[n][k] = *(const bf16x8*)(SB_(shm, b, h) + bbase + (n * 2 + k) * 1024)
; #define MMA8(ai, bj, Bx) do { __builtin_amdgcn_s_setprio(1); \
;     _Pragma("unroll") for (int m = 0; m < 4; ++m) _Pragma("unroll") for (int n = 0; n < 2; ++n) _Pragma("unroll") for (int k = 0; k < 2; ++k) \
;       acc[ai][bj][m][n] = __builtin_amdgcn_mfma_f32_16x16x32_bf16(At[m][k], Bx[n][k], acc[ai][bj][m][n], 0, 0, 0); \
;     __builtin_amdgcn_s_setprio(0); } while (0)
; template <bool HS>
; __device__ __forceinline__ void gemm_tile8(const u16* __restrict__ Ap, const u16* __restrict__ Bp, int K,
;                                            f32x4 (&acc)[2][2][4][2], char* shm, const int tid, const float* hsr = nullptr) {
;     ...
;   { LDB8(B0, 0, 0); LDA8(0, 0); STG_A(1, 1, nt - 1);
;     BAR; WAIT_L(0); MMA8(0, 0, B0); BAR;
;     LDB8(B1, 0, 1); BAR; WAIT_L(0); MMA8(0, 1, B1); BAR;
;     LDA8(0, 1); WAIT_V(4); BAR; WAIT_L(0); MMA8(1, 0, B0); MMA8(1, 1, B1); BAR; }
.Lk_ffn_out_exit:
	s_waitcnt vmcnt(6)
	s_add_i32 s17, s13, 0xc000
	s_add_i32 s18, s13, 0xe000
	v_add_u32_e32 v160, 0, v137
	v_add_u32_e32 v137, 0x10000, v160
	ds_read_b128 v[130:133], v137
	ds_read_b128 v[138:141], v137 offset:1024
	ds_read_b128 v[142:145], v137 offset:2048
	ds_read_b128 v[156:159], v137 offset:3072
	ds_read_b128 v[164:167], v134
	ds_read_b128 v[168:171], v134 offset:1024
	ds_read_b128 v[172:175], v134 offset:2048
	ds_read_b128 v[180:183], v134 offset:3072
	ds_read_b128 v[184:187], v134 offset:4096
	ds_read_b128 v[188:191], v134 offset:5120
	ds_read_b128 v[192:195], v134 offset:6144
	ds_read_b128 v[196:199], v134 offset:7168
	s_add_u32 s0, s3, 0xb1580
	s_addc_u32 s1, s8, 0
	s_mov_b32 m0, s17
	s_nop 0
	global_load_lds_dwordx4 v136, s[0:1]
	s_nop 0
	s_mov_b32 m0, s18
	s_nop 0
	global_load_lds_dwordx4 v135, s[0:1]
	s_barrier
	s_waitcnt lgkmcnt(0)
	s_setprio 1
	s_waitcnt lgkmcnt(7)
	v_mfma_f32_16x16x32_bf16 v[126:129], v[164:167], v[130:133], v[126:129]
	s_waitcnt lgkmcnt(5)
	v_mfma_f32_16x16x32_bf16 v[118:121], v[172:175], v[130:133], v[118:121]
	v_mfma_f32_16x16x32_bf16 v[114:117], v[172:175], v[142:145], v[114:117]
	s_waitcnt lgkmcnt(1)
	v_mfma_f32_16x16x32_bf16 v[102:105], v[192:195], v[130:133], v[102:105]
	v_mfma_f32_16x16x32_bf16 v[98:101], v[192:195], v[142:145], v[98:101]
	v_mfma_f32_16x16x32_bf16 v[126:129], v[168:171], v[138:141], v[126:129]
	v_mfma_f32_16x16x32_bf16 v[122:125], v[164:167], v[142:145], v[122:125]
	v_mfma_f32_16x16x32_bf16 v[118:121], v[180:183], v[138:141], v[118:121]
	v_mfma_f32_16x16x32_bf16 v[114:117], v[180:183], v[156:159], v[114:117]
	v_mfma_f32_16x16x32_bf16 v[110:113], v[184:187], v[130:133], v[110:113]
	v_mfma_f32_16x16x32_bf16 v[106:109], v[184:187], v[142:145], v[106:109]
	s_waitcnt lgkmcnt(0)
	v_mfma_f32_16x16x32_bf16 v[102:105], v[196:199], v[138:141], v[102:105]
	v_mfma_f32_16x16x32_bf16 v[98:101], v[196:199], v[156:159], v[98:101]
	v_mfma_f32_16x16x32_bf16 v[200:203], v[168:171], v[156:159], v[122:125]
	v_mfma_f32_16x16x32_bf16 v[204:207], v[188:191], v[138:141], v[110:113]
	v_mfma_f32_16x16x32_bf16 v[208:211], v[188:191], v[156:159], v[106:109]
	s_setprio 0
	v_add_u32_e32 v135, 0x14000, v160
	s_barrier
	ds_read_b128 v[106:109], v135
	ds_read_b128 v[110:113], v135 offset:1024
	ds_read_b128 v[122:125], v135 offset:2048
	ds_read_b128 v[212:215], v135 offset:3072
	s_barrier
	s_waitcnt lgkmcnt(0)
	s_setprio 1
	s_waitcnt lgkmcnt(3)
	v_mfma_f32_16x16x32_bf16 v[86:89], v[172:175], v[106:109], v[86:89]
	s_waitcnt lgkmcnt(1)
	v_mfma_f32_16x16x32_bf16 v[82:85], v[172:175], v[122:125], v[82:85]
	v_mfma_f32_16x16x32_bf16 v[70:73], v[192:195], v[106:109], v[70:73]
	v_mfma_f32_16x16x32_bf16 v[94:97], v[164:167], v[106:109], v[94:97]
	v_mfma_f32_16x16x32_bf16 v[90:93], v[164:167], v[122:125], v[90:93]
	v_mfma_f32_16x16x32_bf16 v[86:89], v[180:183], v[110:113], v[86:89]
	s_waitcnt lgkmcnt(0)
	v_mfma_f32_16x16x32_bf16 v[82:85], v[180:183], v[212:215], v[82:85]
	v_mfma_f32_16x16x32_bf16 v[78:81], v[184:187], v[106:109], v[78:81]
	v_mfma_f32_16x16x32_bf16 v[74:77], v[184:187], v[122:125], v[74:77]
	v_mfma_f32_16x16x32_bf16 v[70:73], v[196:199], v[110:113], v[70:73]
	v_mfma_f32_16x16x32_bf16 v[66:69], v[192:195], v[122:125], v[66:69]
	v_mfma_f32_16x16x32_bf16 v[220:223], v[168:171], v[110:113], v[94:97]
	v_mfma_f32_16x16x32_bf16 v[164:167], v[168:171], v[212:215], v[90:93]
	v_mfma_f32_16x16x32_bf16 v[168:171], v[188:191], v[110:113], v[78:81]
	v_mfma_f32_16x16x32_bf16 v[172:175], v[188:191], v[212:215], v[74:77]
	v_mfma_f32_16x16x32_bf16 v[180:183], v[196:199], v[212:215], v[66:69]
	s_setprio 0
	s_barrier
	s_nop 0
	ds_read_b128 v[66:69], v134 offset:16384
	ds_read_b128 v[74:77], v134 offset:17408
	ds_read_b128 v[78:81], v134 offset:18432
	ds_read_b128 v[90:93], v134 offset:19456
	ds_read_b128 v[94:97], v134 offset:20480
	ds_read_b128 v[184:187], v134 offset:21504
	ds_read_b128 v[188:191], v134 offset:22528
	ds_read_b128 v[192:195], v134 offset:23552
	s_waitcnt vmcnt(4)
	s_barrier
	s_waitcnt lgkmcnt(0)
	s_setprio 1
	s_waitcnt lgkmcnt(7)
	v_mfma_f32_16x16x32_bf16 v[62:65], v[66:69], v[130:133], v[62:65]
	s_waitcnt lgkmcnt(5)
	v_mfma_f32_16x16x32_bf16 v[54:57], v[78:81], v[130:133], v[54:57]
	v_mfma_f32_16x16x32_bf16 v[50:53], v[78:81], v[142:145], v[50:53]
	s_waitcnt lgkmcnt(1)
	v_mfma_f32_16x16x32_bf16 v[38:41], v[188:191], v[130:133], v[38:41]
	v_mfma_f32_16x16x32_bf16 v[34:37], v[188:191], v[142:145], v[34:37]
	v_mfma_f32_16x16x32_bf16 v[62:65], v[74:77], v[138:141], v[62:65]
	v_mfma_f32_16x16x32_bf16 v[58:61], v[66:69], v[142:145], v[58:61]
	v_mfma_f32_16x16x32_bf16 v[54:57], v[90:93], v[138:141], v[54:57]
	v_mfma_f32_16x16x32_bf16 v[50:53], v[90:93], v[156:159], v[50:53]
	v_mfma_f32_16x16x32_bf16 v[46:49], v[94:97], v[130:133], v[46:49]
	v_mfma_f32_16x16x32_bf16 v[42:45], v[94:97], v[142:145], v[42:45]
	s_waitcnt lgkmcnt(0)
	v_mfma_f32_16x16x32_bf16 v[38:41], v[192:195], v[138:141], v[38:41]
	v_mfma_f32_16x16x32_bf16 v[34:37], v[192:195], v[156:159], v[34:37]
	v_mfma_f32_16x16x32_bf16 v[196:199], v[74:77], v[156:159], v[58:61]
	v_mfma_f32_16x16x32_bf16 v[242:245], v[184:187], v[138:141], v[46:49]
	v_mfma_f32_16x16x32_bf16 v[246:249], v[184:187], v[156:159], v[42:45]
	s_setprio 0
	s_setprio 1
	v_mfma_f32_16x16x32_bf16 v[22:25], v[78:81], v[106:109], v[22:25]
	v_mfma_f32_16x16x32_bf16 v[18:21], v[78:81], v[122:125], v[18:21]
	v_mfma_f32_16x16x32_bf16 v[6:9], v[188:191], v[106:109], v[6:9]
	v_mfma_f32_16x16x32_bf16 v[30:33], v[66:69], v[106:109], v[30:33]
	v_mfma_f32_16x16x32_bf16 v[26:29], v[66:69], v[122:125], v[26:29]
	v_mfma_f32_16x16x32_bf16 v[22:25], v[90:93], v[110:113], v[22:25]
	v_mfma_f32_16x16x32_bf16 v[18:21], v[90:93], v[212:215], v[18:21]
	v_mfma_f32_16x16x32_bf16 v[14:17], v[94:97], v[106:109], v[14:17]
	v_mfma_f32_16x16x32_bf16 v[10:13], v[94:97], v[122:125], v[10:13]
	v_mfma_f32_16x16x32_bf16 v[6:9], v[192:195], v[110:113], v[6:9]
	v_mfma_f32_16x16x32_bf16 v[2:5], v[188:191], v[122:125], v[2:5]
	v_mfma_f32_16x16x32_bf16 v[130:133], v[74:77], v[110:113], v[30:33]
	v_mfma_f32_16x16x32_bf16 v[136:139], v[74:77], v[212:215], v[26:29]
	v_mfma_f32_16x16x32_bf16 v[140:143], v[184:187], v[110:113], v[14:17]
	v_mfma_f32_16x16x32_bf16 v[156:159], v[184:187], v[212:215], v[10:13]
	v_mfma_f32_16x16x32_bf16 v[184:187], v[192:195], v[212:215], v[2:5]
	s_setprio 0
	v_add_u32_e32 v26, 0x18000, v160
	s_barrier
; #define WAIT_V(n) asm volatile("s_waitcnt vmcnt(" #n ")" ::: "memory")
; #define WAIT_L(n) asm volatile("s_waitcnt lgkmcnt(" #n ")" ::: "memory")
; #define BAR __builtin_amdgcn_s_barrier()
; #define LDA8(b, h) _Pragma("unroll") for (int m = 0; m < 4; ++m) _Pragma("unroll") for (int k = 0; k < 2; ++k) \
;     At[m][k] = *(const bf16x8*)(SA_(shm, b, h) + abase + (m * 2 + k) * 1024)
; #define LDB8(dst, b, h) _Pragma("unroll") for (int n = 0; n < 2; ++n) _Pragma("unroll") for (int k = 0; k < 2; ++k) \
;     dst[n][k] = *(const bf16x8*)(SB_(shm, b, h) + bbase + (n * 2 + k) * 1024)
; #define MMA8(ai, bj, Bx) do { __builtin_amdgcn_s_setprio(1); \
;     _Pragma("unroll") for (int m = 0; m < 4; ++m) _Pragma("unroll") for (int n = 0; n < 2; ++n) _Pragma("unroll") for (int k = 0; k < 2; ++k) \
;       acc[ai][bj][m][n] = __builtin_amdgcn_mfma_f32_16x16x32_bf16(At[m][k], Bx[n][k], acc[ai][bj][m][n], 0, 0, 0); \
;     __builtin_amdgcn_s_setprio(0); } while (0)
; template <bool HS>
; __device__ __forceinline__ void gemm_tile8(const u16* __restrict__ Ap, const u16* __restrict__ Bp, int K,
;                                            f32x4 (&acc)[2][2][4][2], char* shm, const int tid, const float* hsr = nullptr) {
;     ...
;   { LDB8(B0, 1, 0); LDA8(1, 0); WAIT_V(2); BAR; WAIT_L(0); MMA8(0, 0, B0); BAR;
;     LDB8(B1, 1, 1); WAIT_V(0); BAR; WAIT_L(0); MMA8(0, 1, B1); BAR;
;     LDA8(1, 1); BAR; WAIT_L(0); MMA8(1, 0, B0); MMA8(1, 1, B1); BAR; }
;   if (wr == 0) BAR;
	ds_read_b128 v[2:5], v26
	ds_read_b128 v[10:13], v26 offset:1024
	ds_read_b128 v[14:17], v26 offset:2048
	ds_read_b128 v[188:191], v26 offset:3072
	ds_read_b128 v[26:29], v134 offset:32768
	ds_read_b128 v[30:33], v134 offset:33792
	ds_read_b128 v[42:45], v134 offset:34816
	ds_read_b128 v[46:49], v134 offset:35840
	ds_read_b128 v[58:61], v134 offset:36864
	ds_read_b128 v[66:69], v134 offset:37888
	ds_read_b128 v[192:195], v134 offset:38912
	ds_read_b128 v[212:215], v134 offset:39936
	s_waitcnt vmcnt(2)
	s_barrier
	s_waitcnt lgkmcnt(0)
	s_setprio 1
	s_waitcnt lgkmcnt(7)
	v_mfma_f32_16x16x32_bf16 v[74:77], v[26:29], v[2:5], v[126:129]
	s_waitcnt lgkmcnt(6)
	v_mfma_f32_16x16x32_bf16 v[122:125], v[30:33], v[10:13], v[74:77]
	v_mfma_f32_16x16x32_bf16 v[74:77], v[26:29], v[14:17], v[200:203]
	v_mfma_f32_16x16x32_bf16 v[126:129], v[30:33], v[188:191], v[74:77]
	s_waitcnt lgkmcnt(5)
	v_mfma_f32_16x16x32_bf16 v[74:77], v[42:45], v[2:5], v[118:121]
	s_waitcnt lgkmcnt(4)
	v_mfma_f32_16x16x32_bf16 v[106:109], v[46:49], v[10:13], v[74:77]
	v_mfma_f32_16x16x32_bf16 v[74:77], v[42:45], v[14:17], v[114:117]
	v_mfma_f32_16x16x32_bf16 v[110:113], v[46:49], v[188:191], v[74:77]
	s_waitcnt lgkmcnt(3)
	v_mfma_f32_16x16x32_bf16 v[74:77], v[58:61], v[2:5], v[204:207]
	s_waitcnt lgkmcnt(2)
	v_mfma_f32_16x16x32_bf16 v[90:93], v[66:69], v[10:13], v[74:77]
	v_mfma_f32_16x16x32_bf16 v[74:77], v[58:61], v[14:17], v[208:211]
	v_mfma_f32_16x16x32_bf16 v[94:97], v[66:69], v[188:191], v[74:77]
	s_waitcnt lgkmcnt(1)
	v_mfma_f32_16x16x32_bf16 v[74:77], v[192:195], v[2:5], v[102:105]
	v_mfma_f32_16x16x32_bf16 v[78:81], v[192:195], v[14:17], v[98:101]
	s_waitcnt lgkmcnt(0)
	v_mfma_f32_16x16x32_bf16 v[74:77], v[212:215], v[10:13], v[74:77]
	v_mfma_f32_16x16x32_bf16 v[78:81], v[212:215], v[188:191], v[78:81]
	s_setprio 0
	v_add_u32_e32 v98, 0x1c000, v160
	s_barrier
	ds_read_b128 v[200:203], v98
	ds_read_b128 v[204:207], v98 offset:1024
	ds_read_b128 v[208:211], v98 offset:2048
	ds_read_b128 v[224:227], v98 offset:3072
	s_waitcnt vmcnt(0)
	s_barrier
	s_waitcnt lgkmcnt(0)
	s_setprio 1
	s_waitcnt lgkmcnt(3)
	v_mfma_f32_16x16x32_bf16 v[98:101], v[26:29], v[200:203], v[220:223]
	s_waitcnt lgkmcnt(1)
	v_mfma_f32_16x16x32_bf16 v[26:29], v[26:29], v[208:211], v[164:167]
	s_waitcnt lgkmcnt(0)
	v_mfma_f32_16x16x32_bf16 v[118:121], v[30:33], v[224:227], v[26:29]
	v_mfma_f32_16x16x32_bf16 v[26:29], v[42:45], v[200:203], v[86:89]
	v_mfma_f32_16x16x32_bf16 v[114:117], v[30:33], v[204:207], v[98:101]
	v_mfma_f32_16x16x32_bf16 v[98:101], v[46:49], v[204:207], v[26:29]
	v_mfma_f32_16x16x32_bf16 v[26:29], v[42:45], v[208:211], v[82:85]
	v_mfma_f32_16x16x32_bf16 v[102:105], v[46:49], v[224:227], v[26:29]
	v_mfma_f32_16x16x32_bf16 v[26:29], v[58:61], v[200:203], v[168:171]
	v_mfma_f32_16x16x32_bf16 v[82:85], v[66:69], v[204:207], v[26:29]
	v_mfma_f32_16x16x32_bf16 v[26:29], v[58:61], v[208:211], v[172:175]
	v_mfma_f32_16x16x32_bf16 v[86:89], v[66:69], v[224:227], v[26:29]
	v_mfma_f32_16x16x32_bf16 v[26:29], v[192:195], v[200:203], v[70:73]
	v_mfma_f32_16x16x32_bf16 v[66:69], v[212:215], v[204:207], v[26:29]
	v_mfma_f32_16x16x32_bf16 v[26:29], v[192:195], v[208:211], v[180:183]
	v_mfma_f32_16x16x32_bf16 v[70:73], v[212:215], v[224:227], v[26:29]
	s_setprio 0
	s_barrier
	ds_read_b128 v[164:167], v134 offset:49152
	ds_read_b128 v[168:171], v134 offset:50176
	ds_read_b128 v[172:175], v134 offset:51200
	ds_read_b128 v[180:183], v134 offset:52224
	ds_read_b128 v[192:195], v134 offset:53248
	ds_read_b128 v[212:215], v134 offset:54272
	ds_read_b128 v[220:223], v134 offset:55296
	ds_read_b128 v[228:231], v134 offset:56320
	s_barrier
	s_waitcnt lgkmcnt(0)
	s_setprio 1
	s_waitcnt lgkmcnt(7)
	v_mfma_f32_16x16x32_bf16 v[26:29], v[164:167], v[2:5], v[62:65]
	s_waitcnt lgkmcnt(6)
	v_mfma_f32_16x16x32_bf16 v[58:61], v[168:171], v[10:13], v[26:29]
	v_mfma_f32_16x16x32_bf16 v[26:29], v[164:167], v[14:17], v[196:199]
	v_mfma_f32_16x16x32_bf16 v[62:65], v[168:171], v[188:191], v[26:29]
	s_waitcnt lgkmcnt(5)
	v_mfma_f32_16x16x32_bf16 v[26:29], v[172:175], v[2:5], v[54:57]
	s_waitcnt lgkmcnt(4)
	v_mfma_f32_16x16x32_bf16 v[42:45], v[180:183], v[10:13], v[26:29]
	v_mfma_f32_16x16x32_bf16 v[26:29], v[172:175], v[14:17], v[50:53]
	v_mfma_f32_16x16x32_bf16 v[46:49], v[180:183], v[188:191], v[26:29]
	s_waitcnt lgkmcnt(3)
	v_mfma_f32_16x16x32_bf16 v[26:29], v[192:195], v[2:5], v[242:245]
	s_waitcnt lgkmcnt(1)
	v_mfma_f32_16x16x32_bf16 v[2:5], v[220:223], v[2:5], v[38:41]
	v_mfma_f32_16x16x32_bf16 v[26:29], v[212:215], v[10:13], v[26:29]
	v_mfma_f32_16x16x32_bf16 v[30:33], v[192:195], v[14:17], v[246:249]
	s_waitcnt lgkmcnt(0)
	v_mfma_f32_16x16x32_bf16 v[10:13], v[228:231], v[10:13], v[2:5]
	v_mfma_f32_16x16x32_bf16 v[2:5], v[220:223], v[14:17], v[34:37]
	v_mfma_f32_16x16x32_bf16 v[30:33], v[212:215], v[188:191], v[30:33]
	v_mfma_f32_16x16x32_bf16 v[14:17], v[228:231], v[188:191], v[2:5]
	s_setprio 0
	s_setprio 1
	v_mfma_f32_16x16x32_bf16 v[2:5], v[164:167], v[200:203], v[130:133]
	v_mfma_f32_16x16x32_bf16 v[50:53], v[168:171], v[204:207], v[2:5]
	v_mfma_f32_16x16x32_bf16 v[2:5], v[164:167], v[208:211], v[136:139]
	v_mfma_f32_16x16x32_bf16 v[54:57], v[168:171], v[224:227], v[2:5]
	v_mfma_f32_16x16x32_bf16 v[2:5], v[172:175], v[200:203], v[22:25]
	v_mfma_f32_16x16x32_bf16 v[34:37], v[180:183], v[204:207], v[2:5]
	v_mfma_f32_16x16x32_bf16 v[2:5], v[172:175], v[208:211], v[18:21]
	v_mfma_f32_16x16x32_bf16 v[38:41], v[180:183], v[224:227], v[2:5]
	v_mfma_f32_16x16x32_bf16 v[2:5], v[192:195], v[200:203], v[140:143]
	v_mfma_f32_16x16x32_bf16 v[18:21], v[212:215], v[204:207], v[2:5]
	v_mfma_f32_16x16x32_bf16 v[2:5], v[192:195], v[208:211], v[156:159]
	v_mfma_f32_16x16x32_bf16 v[22:25], v[212:215], v[224:227], v[2:5]
	v_mfma_f32_16x16x32_bf16 v[2:5], v[220:223], v[200:203], v[6:9]
	v_mfma_f32_16x16x32_bf16 v[6:9], v[220:223], v[208:211], v[184:187]
	v_mfma_f32_16x16x32_bf16 v[2:5], v[228:231], v[204:207], v[2:5]
	v_mfma_f32_16x16x32_bf16 v[6:9], v[228:231], v[224:227], v[6:9]
	s_setprio 0
	s_movk_i32 s0, 0x100
	v_cmp_gt_u32_e32 vcc, s0, v0
	s_barrier
	s_and_saveexec_b64 s[0:1], vcc
	s_cbranch_execz .LBB0_654
	s_barrier
